# c11 + same column remap (wave owns 64 contiguous columns) for both merge GEMMs and the output GEMM: epilogue loads/stores of a row are contiguous per wave
# baseline (speedup 1.0000x reference)
; #define PG8_STAGE(bufoff, gbase, voff) do { _Pragma("unroll") for (int _i = 0; _i < 2; ++_i) \
;         __builtin_amdgcn_global_load_lds((const unsigned*)((const char*)(gbase) + (voff)[_i]), (PG8_LAS unsigned*)(lds + (bufoff) + ldsw + _i * 8192), 16, 0, 0); } while (0)
; #define PG8_WAIT_V(n) asm volatile("s_waitcnt vmcnt(" #n ")" ::: "memory")
; #define PG8_BAR __builtin_amdgcn_s_barrier()
; template <class Epi, class Sched, bool ALIGN_EPI = false, bool SP2 = false>
; __device__ __forceinline__ void gemm_phase(PG8_LAS unsigned char* lds, const Gemm g, const Sched& S, const Epi& E) {
;     ...
;     for (int i = 0; i < 2; ++i) { int R, C; stage_rc(tid * 16 + i * 8192, R, C); const int Rb = Epi::PERM ? ((R & ~31) + perm32(R & 31)) : R;
;         voffA[i] = (unsigned)(R * K + C) * 2u; voffB[i] = (unsigned)(Rb * K + C) * 2u; }
;     const size_t kstep = (size_t)(BK * 2);
;     const size_t hstep = (size_t)HALF * K * 2;
;     const size_t tstep = 2 * hstep;
;     const unsigned ldsw = (unsigned)wid * 1024u;
;     const int aoff = lds_byte(wr * 64 + fr, fq * 8), boff = lds_byte(wc * 32 + fr, fq * 8);
;     ...
;         PG8_STAGE(PG8_SB(1, 0), cB + kstep, voffB); PG8_STAGE(PG8_SA(1, 0), cA + kstep, voffA); PG8_STAGE(PG8_SB(1, 1), cB + hstep + kstep, voffB);
;         PG8_WAIT_V(6); PG8_BAR;
.LBB0_830:
	s_mov_b64 s[14:15], 0x80
	s_lshl_b32 s1, s1, 5
	s_add_i32 m0, s37, 0x18000
	v_lshl_add_u64 v[6:7], v[6:7], 0, s[14:15]
	s_lshl_b32 s18, s5, 13
	s_and_b32 s19, s1, 0x60
	s_waitcnt vmcnt(2)
	s_barrier
	global_load_lds_dwordx4 v[6:7], off
	v_lshl_add_u64 v[4:5], v[4:5], 0, s[14:15]
	s_add_i32 m0, s37, 0x1a000
	s_add_i32 s54, s37, 0x8000
	s_add_i32 s55, s37, 0xa000
	global_load_lds_dwordx4 v[4:5], off
	v_lshl_add_u64 v[0:1], v[0:1], 0, s[14:15]
	s_mov_b32 m0, s54
	s_add_u32 s16, s40, 0x40080
	global_load_lds_dwordx4 v[0:1], off
	v_lshl_add_u64 v[0:1], v[2:3], 0, s[14:15]
	s_mov_b32 m0, s55
	s_addc_u32 s17, s41, 0
	global_load_lds_dwordx4 v[0:1], off
	s_add_i32 m0, s37, 0x1c000
	v_lshl_add_u64 v[0:1], s[16:17], 0, v[154:155]
	global_load_lds_dwordx4 v[0:1], off
	v_lshl_add_u64 v[0:1], s[16:17], 0, v[158:159]
	s_add_i32 m0, s37, 0x1e000
	v_lshlrev_b32_e32 v2, 11, v182
	global_load_lds_dwordx4 v[0:1], off
	v_lshlrev_b32_e32 v1, 2, v185
	v_lshl_or_b32 v0, v185, 6, v186
	v_and_b32_e32 v1, 32, v1
	v_bitop3_b32 v0, v0, s18, v1 bitop3:0xde
	v_lshlrev_b32_e32 v1, 8, v161
	v_and_b32_e32 v1, 0x38000, v1
	v_or3_b32 v1, v180, v1, v2
	v_add_u32_e32 v162, v1, v181
	v_lshlrev_b32_e32 v1, 4, v183
	s_waitcnt vmcnt(6)
	s_cmpk_lt_u32 s3, 0x100
	v_and_b32_e32 v1, 0x78000, v1
	v_lshl_or_b32 v194, s19, 8, v187
	s_cselect_b64 s[16:17], -1, 0
	v_or3_b32 v1, v180, v1, v2
	s_add_i32 s61, 0, 0x10000
	s_add_i32 s62, 0, 0x14000
	s_sext_i32_i8 s1, s4
	v_lshl_or_b32 v193, s5, 6, v185
	s_waitcnt lgkmcnt(0)
	s_ashr_i32 s60, s33, 31
	v_lshl_add_u32 v195, s19, 1, v184
	v_mov_b32_e32 v163, v155
	v_add_u32_e32 v164, v1, v181
	v_mov_b32_e32 v165, v155
	v_mov_b64_e32 v[166:167], 0x400
	v_mov_b64_e32 v[168:169], 0x3ff
	v_add_u32_e32 v196, s61, v194
	v_add_u32_e32 v197, 0x11000, v194
	v_add_u32_e32 v198, 0, v0
	s_mov_b64 s[18:19], 0x80000
	s_mov_b64 s[20:21], 0x90000
	s_mov_b64 s[22:23], 0xa0000
	s_mov_b64 s[24:25], 0xb0000
	s_barrier
	s_branch .LBB0_833

; #define PG8_STAGE(bufoff, gbase, voff) do { _Pragma("unroll") for (int _i = 0; _i < 2; ++_i) \
;         __builtin_amdgcn_global_load_lds((const unsigned*)((const char*)(gbase) + (voff)[_i]), (PG8_LAS unsigned*)(lds + (bufoff) + ldsw + _i * 8192), 16, 0, 0); } while (0)
; #define PG8_LDA(dst, b, h) do { _Pragma("unroll") for (int m = 0; m < 4; ++m) _Pragma("unroll") for (int k = 0; k < 2; ++k) dst[m][k] = *(const PG8_LAS bf16x8*)(lds + PG8_SA(b, h) + aoff + m * 2048 + k * 1024); } while (0)
; #define PG8_LDB(dst, b, h) do { _Pragma("unroll") for (int n = 0; n < 2; ++n) _Pragma("unroll") for (int k = 0; k < 2; ++k) dst[n][k] = *(const PG8_LAS bf16x8*)(lds + PG8_SB(b, h) + boff + n * 2048 + k * 1024); } while (0)
; #define PG8_MMA(ai, bj, At, Bt) do { __builtin_amdgcn_s_setprio(1); _Pragma("unroll") for (int m = 0; m < 4; ++m) _Pragma("unroll") for (int n = 0; n < 2; ++n) _Pragma("unroll") for (int k = 0; k < 2; ++k) \
;         acc[ai][bj][m][n] = __builtin_amdgcn_mfma_f32_16x16x32_bf16(Bt[n][k], At[m][k], acc[ai][bj][m][n], 0, 0, 0); __builtin_amdgcn_s_setprio(0); } while (0)
; #define PG8_WAIT_V(n) asm volatile("s_waitcnt vmcnt(" #n ")" ::: "memory")
; #define PG8_BAR __builtin_amdgcn_s_barrier()
; template <class Epi, class Sched, bool ALIGN_EPI = false, bool SP2 = false>
; __device__ __forceinline__ void gemm_phase(PG8_LAS unsigned char* lds, const Gemm g, const Sched& S, const Epi& E) {
;     ...
;         for (int t = 0; t < nt; t += 2) {
;             const bool last = (t == nt - 2);
;             const char* a1 = cA + (size_t)(t + 1) * kstep;
;             const char* a2 = last ? nA : cA + (size_t)(t + 2) * kstep; const char* b2 = last ? nB : cB + (size_t)(t + 2) * kstep;
;             const char* a3 = a2 + kstep; const char* b3 = b2 + kstep;
;             if (last && has_next) S.a_ready(nxt);
;             if constexpr (SP2) {
;             PG8_LDB(B0, 0, 0); PG8_LDB(B1, 0, 1); PG8_SCHED; PG8_LDA(At, 0, 0); PG8_STAGE(PG8_SA(1, 1), a1 + hstep, voffA);
;             PG8_WAIT_V(8); PG8_WAIT_L(0); PG8_BAR; PG8_MMA(0, 0, At, B0); PG8_MMA(0, 1, At, B1); PG8_BAR; PG8_SCHED;
;             PG8_LDA(At, 0, 1); PG8_STAGE(PG8_SB(0, 0), b2, voffB); PG8_STAGE(PG8_SB(0, 1), b2 + hstep, voffB); PG8_STAGE(PG8_SA(0, 0), a2, voffA);
;             PG8_WAIT_V(8); PG8_WAIT_L(0); PG8_BAR; PG8_MMA(1, 0, At, B0); PG8_MMA(1, 1, At, B1); PG8_BAR; PG8_SCHED;
.LBB0_840:
	ds_read_b128 v[128:131], v196
	ds_read_b128 v[132:135], v196 offset:1024
	ds_read_b128 v[136:139], v196 offset:2048
	ds_read_b128 v[140:143], v196 offset:3072
	ds_read_b128 v[144:147], v197
	ds_read_b128 v[148:151], v197 offset:1024
	ds_read_b128 v[170:173], v197 offset:2048
	ds_read_b128 v[174:177], v197 offset:3072
	s_add_u32 s40, s38, 0xfffc0080
	s_addc_u32 s41, s39, -1
	s_cmp_eq_u32 s59, 12
	s_cselect_b32 s43, s3, s41
	s_cselect_b32 s42, s29, s40
	s_cselect_b32 s41, s27, s58
	s_cselect_b32 s40, s56, s57
	v_lshl_add_u64 v[178:179], s[38:39], 0, v[162:163]
	s_add_i32 m0, s37, 0xc000
	ds_read_b128 v[200:203], v198
	ds_read_b128 v[204:207], v198 offset:1024
	ds_read_b128 v[208:211], v198 offset:2048
	ds_read_b128 v[212:215], v198 offset:3072
	ds_read_b128 v[216:219], v198 offset:4096
	ds_read_b128 v[220:223], v198 offset:5120
	ds_read_b128 v[224:227], v198 offset:6144
	ds_read_b128 v[228:231], v198 offset:7168
	global_load_lds_dwordx4 v[178:179], off
	v_lshl_add_u64 v[178:179], s[38:39], 0, v[164:165]
	s_add_i32 m0, s37, 0xe000
	s_nop 0
	global_load_lds_dwordx4 v[178:179], off
	s_waitcnt vmcnt(8)
	s_waitcnt lgkmcnt(0)
	s_barrier
	s_setprio 1
	s_waitcnt lgkmcnt(0)
	v_mfma_f32_16x16x32_bf16 v[124:127], v[128:131], v[200:203], v[124:127]
	v_mfma_f32_16x16x32_bf16 v[120:123], v[136:139], v[200:203], v[120:123]
	v_mfma_f32_16x16x32_bf16 v[108:111], v[128:131], v[208:211], v[108:111]
	v_mfma_f32_16x16x32_bf16 v[104:107], v[136:139], v[208:211], v[104:107]
	v_mfma_f32_16x16x32_bf16 v[92:95], v[128:131], v[216:219], v[92:95]
	v_mfma_f32_16x16x32_bf16 v[88:91], v[136:139], v[216:219], v[88:91]
	v_mfma_f32_16x16x32_bf16 v[76:79], v[128:131], v[224:227], v[76:79]
	v_mfma_f32_16x16x32_bf16 v[72:75], v[136:139], v[224:227], v[72:75]
	v_mfma_f32_16x16x32_bf16 v[124:127], v[132:135], v[204:207], v[124:127]
	v_mfma_f32_16x16x32_bf16 v[120:123], v[140:143], v[204:207], v[120:123]
	v_mfma_f32_16x16x32_bf16 v[108:111], v[132:135], v[212:215], v[108:111]
	v_mfma_f32_16x16x32_bf16 v[104:107], v[140:143], v[212:215], v[104:107]
	v_mfma_f32_16x16x32_bf16 v[92:95], v[132:135], v[220:223], v[92:95]
	v_mfma_f32_16x16x32_bf16 v[88:91], v[140:143], v[220:223], v[88:91]
	v_mfma_f32_16x16x32_bf16 v[76:79], v[132:135], v[228:231], v[76:79]
	v_mfma_f32_16x16x32_bf16 v[72:75], v[140:143], v[228:231], v[72:75]
	s_setprio 0
	s_setprio 1
	v_mfma_f32_16x16x32_bf16 v[116:119], v[144:147], v[200:203], v[116:119]
	v_mfma_f32_16x16x32_bf16 v[112:115], v[170:173], v[200:203], v[112:115]
	v_mfma_f32_16x16x32_bf16 v[100:103], v[144:147], v[208:211], v[100:103]
	v_mfma_f32_16x16x32_bf16 v[96:99], v[170:173], v[208:211], v[96:99]
	v_mfma_f32_16x16x32_bf16 v[84:87], v[144:147], v[216:219], v[84:87]
	v_mfma_f32_16x16x32_bf16 v[80:83], v[170:173], v[216:219], v[80:83]
	v_mfma_f32_16x16x32_bf16 v[68:71], v[144:147], v[224:227], v[68:71]
	v_mfma_f32_16x16x32_bf16 v[64:67], v[170:173], v[224:227], v[64:67]
	v_mfma_f32_16x16x32_bf16 v[116:119], v[148:151], v[204:207], v[116:119]
	v_mfma_f32_16x16x32_bf16 v[112:115], v[174:177], v[204:207], v[112:115]
	v_mfma_f32_16x16x32_bf16 v[100:103], v[148:151], v[212:215], v[100:103]
	v_mfma_f32_16x16x32_bf16 v[96:99], v[174:177], v[212:215], v[96:99]
	v_mfma_f32_16x16x32_bf16 v[84:87], v[148:151], v[220:223], v[84:87]
	v_mfma_f32_16x16x32_bf16 v[80:83], v[174:177], v[220:223], v[80:83]
	v_mfma_f32_16x16x32_bf16 v[68:71], v[148:151], v[228:231], v[68:71]
	v_mfma_f32_16x16x32_bf16 v[64:67], v[174:177], v[228:231], v[64:67]
	s_setprio 0
	s_barrier
	s_add_i32 s63, s61, s49
	v_lshl_add_u64 v[178:179], s[40:41], 0, v[154:155]
	s_mov_b32 m0, s63
	ds_read_b128 v[200:203], v198 offset:16384
	ds_read_b128 v[204:207], v198 offset:17408
	ds_read_b128 v[208:211], v198 offset:18432
	ds_read_b128 v[212:215], v198 offset:19456
	ds_read_b128 v[216:219], v198 offset:20480
	ds_read_b128 v[220:223], v198 offset:21504
	ds_read_b128 v[224:227], v198 offset:22528
	ds_read_b128 v[228:231], v198 offset:23552
	global_load_lds_dwordx4 v[178:179], off
	s_add_i32 m0, s63, 0x2000
	s_add_u32 s64, s40, 0x40000
	v_lshl_add_u64 v[232:233], s[40:41], 0, v[158:159]
	s_addc_u32 s65, s41, 0
	s_add_i32 s63, s62, s49
	global_load_lds_dwordx4 v[232:233], off
	v_lshl_add_u64 v[234:235], s[64:65], 0, v[154:155]
	s_mov_b32 m0, s63
	v_lshl_add_u64 v[236:237], s[42:43], 0, v[156:157]
	global_load_lds_dwordx4 v[234:235], off
	v_lshl_add_u64 v[234:235], s[64:65], 0, v[158:159]
	s_add_i32 m0, s63, 0x2000
	s_nop 0
	global_load_lds_dwordx4 v[234:235], off
	v_lshl_add_u64 v[234:235], s[42:43], 0, v[152:153]
	s_mov_b32 m0, s37
	s_nop 0
	global_load_lds_dwordx4 v[234:235], off
	s_mov_b32 m0, s50
	s_nop 0
	global_load_lds_dwordx4 v[236:237], off
	s_waitcnt vmcnt(8)
	s_waitcnt lgkmcnt(0)
	s_barrier
; #define PG8_STAGE(bufoff, gbase, voff) do { _Pragma("unroll") for (int _i = 0; _i < 2; ++_i) \
;         __builtin_amdgcn_global_load_lds((const unsigned*)((const char*)(gbase) + (voff)[_i]), (PG8_LAS unsigned*)(lds + (bufoff) + ldsw + _i * 8192), 16, 0, 0); } while (0)
; #define PG8_LDA(dst, b, h) do { _Pragma("unroll") for (int m = 0; m < 4; ++m) _Pragma("unroll") for (int k = 0; k < 2; ++k) dst[m][k] = *(const PG8_LAS bf16x8*)(lds + PG8_SA(b, h) + aoff + m * 2048 + k * 1024); } while (0)
; #define PG8_LDB(dst, b, h) do { _Pragma("unroll") for (int n = 0; n < 2; ++n) _Pragma("unroll") for (int k = 0; k < 2; ++k) dst[n][k] = *(const PG8_LAS bf16x8*)(lds + PG8_SB(b, h) + boff + n * 2048 + k * 1024); } while (0)
; #define PG8_MMA(ai, bj, At, Bt) do { __builtin_amdgcn_s_setprio(1); _Pragma("unroll") for (int m = 0; m < 4; ++m) _Pragma("unroll") for (int n = 0; n < 2; ++n) _Pragma("unroll") for (int k = 0; k < 2; ++k) \
;         acc[ai][bj][m][n] = __builtin_amdgcn_mfma_f32_16x16x32_bf16(Bt[n][k], At[m][k], acc[ai][bj][m][n], 0, 0, 0); __builtin_amdgcn_s_setprio(0); } while (0)
; #define PG8_WAIT_V(n) asm volatile("s_waitcnt vmcnt(" #n ")" ::: "memory")
; #define PG8_WAIT_L(n) asm volatile("s_waitcnt lgkmcnt(" #n ")" ::: "memory")
; #define PG8_BAR __builtin_amdgcn_s_barrier()
; #define PG8_SCHED __builtin_amdgcn_sched_barrier(0)
; template <class Epi, class Sched, bool ALIGN_EPI = false, bool SP2 = false>
; __device__ __forceinline__ void gemm_phase(PG8_LAS unsigned char* lds, const Gemm g, const Sched& S, const Epi& E) {
;     ...
;             PG8_WAIT_V(8); PG8_WAIT_L(0); PG8_BAR; PG8_MMA(1, 0, At, B0); PG8_MMA(1, 1, At, B1); PG8_BAR; PG8_SCHED;
;             PG8_LDB(B0, 1, 0); PG8_LDB(B1, 1, 1); PG8_SCHED; PG8_LDA(At, 1, 0); PG8_STAGE(PG8_SA(0, 1), a2 + hstep, voffA);
;             PG8_WAIT_V(8); PG8_WAIT_L(0); PG8_BAR; PG8_MMA(0, 0, At, B0); PG8_MMA(0, 1, At, B1); PG8_BAR; PG8_SCHED;
;             PG8_LDA(At, 1, 1); PG8_STAGE(PG8_SB(1, 0), b3, voffB); PG8_STAGE(PG8_SB(1, 1), b3 + hstep, voffB); PG8_STAGE(PG8_SA(1, 0), a3, voffA);
;             PG8_WAIT_V(8); PG8_WAIT_L(0); PG8_BAR; PG8_MMA(1, 0, At, B0); PG8_MMA(1, 1, At, B1); PG8_BAR; PG8_SCHED;
	s_setprio 1
	s_waitcnt lgkmcnt(0)
	v_mfma_f32_16x16x32_bf16 v[60:63], v[128:131], v[200:203], v[60:63]
	v_mfma_f32_16x16x32_bf16 v[56:59], v[136:139], v[200:203], v[56:59]
	v_mfma_f32_16x16x32_bf16 v[44:47], v[128:131], v[208:211], v[44:47]
	v_mfma_f32_16x16x32_bf16 v[40:43], v[136:139], v[208:211], v[40:43]
	v_mfma_f32_16x16x32_bf16 v[28:31], v[128:131], v[216:219], v[28:31]
	v_mfma_f32_16x16x32_bf16 v[24:27], v[136:139], v[216:219], v[24:27]
	v_mfma_f32_16x16x32_bf16 v[12:15], v[128:131], v[224:227], v[12:15]
	v_mfma_f32_16x16x32_bf16 v[8:11], v[136:139], v[224:227], v[8:11]
	v_mfma_f32_16x16x32_bf16 v[60:63], v[132:135], v[204:207], v[60:63]
	v_mfma_f32_16x16x32_bf16 v[56:59], v[140:143], v[204:207], v[56:59]
	v_mfma_f32_16x16x32_bf16 v[44:47], v[132:135], v[212:215], v[44:47]
	v_mfma_f32_16x16x32_bf16 v[40:43], v[140:143], v[212:215], v[40:43]
	v_mfma_f32_16x16x32_bf16 v[28:31], v[132:135], v[220:223], v[28:31]
	v_mfma_f32_16x16x32_bf16 v[24:27], v[140:143], v[220:223], v[24:27]
	v_mfma_f32_16x16x32_bf16 v[12:15], v[132:135], v[228:231], v[12:15]
	v_mfma_f32_16x16x32_bf16 v[8:11], v[140:143], v[228:231], v[8:11]
	s_setprio 0
	s_setprio 1
	v_mfma_f32_16x16x32_bf16 v[52:55], v[144:147], v[200:203], v[52:55]
	v_mfma_f32_16x16x32_bf16 v[48:51], v[170:173], v[200:203], v[48:51]
	v_mfma_f32_16x16x32_bf16 v[36:39], v[144:147], v[208:211], v[36:39]
	v_mfma_f32_16x16x32_bf16 v[32:35], v[170:173], v[208:211], v[32:35]
	v_mfma_f32_16x16x32_bf16 v[20:23], v[144:147], v[216:219], v[20:23]
	v_mfma_f32_16x16x32_bf16 v[16:19], v[170:173], v[216:219], v[16:19]
	v_mfma_f32_16x16x32_bf16 v[4:7], v[144:147], v[224:227], v[4:7]
	v_mfma_f32_16x16x32_bf16 v[0:3], v[170:173], v[224:227], v[0:3]
	v_mfma_f32_16x16x32_bf16 v[52:55], v[148:151], v[204:207], v[52:55]
	v_mfma_f32_16x16x32_bf16 v[48:51], v[174:177], v[204:207], v[48:51]
	v_mfma_f32_16x16x32_bf16 v[36:39], v[148:151], v[212:215], v[36:39]
	v_mfma_f32_16x16x32_bf16 v[32:35], v[174:177], v[212:215], v[32:35]
	v_mfma_f32_16x16x32_bf16 v[20:23], v[148:151], v[220:223], v[20:23]
	v_mfma_f32_16x16x32_bf16 v[16:19], v[174:177], v[220:223], v[16:19]
	v_mfma_f32_16x16x32_bf16 v[4:7], v[148:151], v[228:231], v[4:7]
	v_mfma_f32_16x16x32_bf16 v[0:3], v[174:177], v[228:231], v[0:3]
	s_setprio 0
	s_barrier
	s_add_i32 s63, 0, 0x18000
	s_add_i32 s64, 0, 0x1c000
	v_add_u32_e32 v140, s63, v194
	v_add_u32_e32 v174, 0x19000, v194
	ds_read_b128 v[128:131], v140
	ds_read_b128 v[132:135], v140 offset:1024
	ds_read_b128 v[136:139], v140 offset:2048
	ds_read_b128 v[140:143], v140 offset:3072
	ds_read_b128 v[144:147], v174
	ds_read_b128 v[148:151], v174 offset:1024
	ds_read_b128 v[170:173], v174 offset:2048
	ds_read_b128 v[174:177], v174 offset:3072
	s_add_u32 s42, s42, 0x40000
	s_addc_u32 s43, s43, 0
	s_mov_b32 m0, s51
	v_lshl_add_u64 v[238:239], s[42:43], 0, v[152:153]
	ds_read_b128 v[200:203], v198 offset:32768
	ds_read_b128 v[204:207], v198 offset:33792
	ds_read_b128 v[208:211], v198 offset:34816
	ds_read_b128 v[212:215], v198 offset:35840
	ds_read_b128 v[216:219], v198 offset:36864
	ds_read_b128 v[220:223], v198 offset:37888
	ds_read_b128 v[224:227], v198 offset:38912
	ds_read_b128 v[228:231], v198 offset:39936
	global_load_lds_dwordx4 v[238:239], off
	v_lshl_add_u64 v[238:239], s[42:43], 0, v[156:157]
	s_mov_b32 m0, s52
	s_nop 0
	global_load_lds_dwordx4 v[238:239], off
	s_waitcnt vmcnt(8)
	s_waitcnt lgkmcnt(0)
	s_barrier
	s_setprio 1
	s_waitcnt lgkmcnt(0)
	v_mfma_f32_16x16x32_bf16 v[124:127], v[128:131], v[200:203], v[124:127]
	v_mfma_f32_16x16x32_bf16 v[120:123], v[136:139], v[200:203], v[120:123]
	v_mfma_f32_16x16x32_bf16 v[108:111], v[128:131], v[208:211], v[108:111]
	v_mfma_f32_16x16x32_bf16 v[104:107], v[136:139], v[208:211], v[104:107]
	v_mfma_f32_16x16x32_bf16 v[92:95], v[128:131], v[216:219], v[92:95]
	v_mfma_f32_16x16x32_bf16 v[88:91], v[136:139], v[216:219], v[88:91]
	v_mfma_f32_16x16x32_bf16 v[76:79], v[128:131], v[224:227], v[76:79]
	v_mfma_f32_16x16x32_bf16 v[72:75], v[136:139], v[224:227], v[72:75]
	v_mfma_f32_16x16x32_bf16 v[124:127], v[132:135], v[204:207], v[124:127]
	v_mfma_f32_16x16x32_bf16 v[120:123], v[140:143], v[204:207], v[120:123]
	v_mfma_f32_16x16x32_bf16 v[108:111], v[132:135], v[212:215], v[108:111]
	v_mfma_f32_16x16x32_bf16 v[104:107], v[140:143], v[212:215], v[104:107]
	v_mfma_f32_16x16x32_bf16 v[92:95], v[132:135], v[220:223], v[92:95]
	v_mfma_f32_16x16x32_bf16 v[88:91], v[140:143], v[220:223], v[88:91]
	v_mfma_f32_16x16x32_bf16 v[76:79], v[132:135], v[228:231], v[76:79]
	v_mfma_f32_16x16x32_bf16 v[72:75], v[140:143], v[228:231], v[72:75]
	s_setprio 0
	s_setprio 1
	v_mfma_f32_16x16x32_bf16 v[116:119], v[144:147], v[200:203], v[116:119]
	v_mfma_f32_16x16x32_bf16 v[112:115], v[170:173], v[200:203], v[112:115]
	v_mfma_f32_16x16x32_bf16 v[100:103], v[144:147], v[208:211], v[100:103]
	v_mfma_f32_16x16x32_bf16 v[96:99], v[170:173], v[208:211], v[96:99]
	v_mfma_f32_16x16x32_bf16 v[84:87], v[144:147], v[216:219], v[84:87]
	v_mfma_f32_16x16x32_bf16 v[80:83], v[170:173], v[216:219], v[80:83]
	v_mfma_f32_16x16x32_bf16 v[68:71], v[144:147], v[224:227], v[68:71]
	v_mfma_f32_16x16x32_bf16 v[64:67], v[170:173], v[224:227], v[64:67]
	v_mfma_f32_16x16x32_bf16 v[116:119], v[148:151], v[204:207], v[116:119]
	v_mfma_f32_16x16x32_bf16 v[112:115], v[174:177], v[204:207], v[112:115]
	v_mfma_f32_16x16x32_bf16 v[100:103], v[148:151], v[212:215], v[100:103]
	v_mfma_f32_16x16x32_bf16 v[96:99], v[174:177], v[212:215], v[96:99]
	v_mfma_f32_16x16x32_bf16 v[84:87], v[148:151], v[220:223], v[84:87]
	v_mfma_f32_16x16x32_bf16 v[80:83], v[174:177], v[220:223], v[80:83]
	v_mfma_f32_16x16x32_bf16 v[68:71], v[148:151], v[228:231], v[68:71]
	v_mfma_f32_16x16x32_bf16 v[64:67], v[174:177], v[228:231], v[64:67]
	s_setprio 0
	s_barrier
; #define PG8_STAGE(bufoff, gbase, voff) do { _Pragma("unroll") for (int _i = 0; _i < 2; ++_i) \
;         __builtin_amdgcn_global_load_lds((const unsigned*)((const char*)(gbase) + (voff)[_i]), (PG8_LAS unsigned*)(lds + (bufoff) + ldsw + _i * 8192), 16, 0, 0); } while (0)
; #define PG8_LDA(dst, b, h) do { _Pragma("unroll") for (int m = 0; m < 4; ++m) _Pragma("unroll") for (int k = 0; k < 2; ++k) dst[m][k] = *(const PG8_LAS bf16x8*)(lds + PG8_SA(b, h) + aoff + m * 2048 + k * 1024); } while (0)
; #define PG8_MMA(ai, bj, At, Bt) do { __builtin_amdgcn_s_setprio(1); _Pragma("unroll") for (int m = 0; m < 4; ++m) _Pragma("unroll") for (int n = 0; n < 2; ++n) _Pragma("unroll") for (int k = 0; k < 2; ++k) \
;         acc[ai][bj][m][n] = __builtin_amdgcn_mfma_f32_16x16x32_bf16(Bt[n][k], At[m][k], acc[ai][bj][m][n], 0, 0, 0); __builtin_amdgcn_s_setprio(0); } while (0)
; #define PG8_WAIT_V(n) asm volatile("s_waitcnt vmcnt(" #n ")" ::: "memory")
; #define PG8_WAIT_L(n) asm volatile("s_waitcnt lgkmcnt(" #n ")" ::: "memory")
; #define PG8_BAR __builtin_amdgcn_s_barrier()
; #define PG8_SCHED __builtin_amdgcn_sched_barrier(0)
; template <class Epi, class Sched, bool ALIGN_EPI = false, bool SP2 = false>
; __device__ __forceinline__ void gemm_phase(PG8_LAS unsigned char* lds, const Gemm g, const Sched& S, const Epi& E) {
;     ...
;             PG8_WAIT_V(8); PG8_WAIT_L(0); PG8_BAR; PG8_MMA(0, 0, At, B0); PG8_MMA(0, 1, At, B1); PG8_BAR; PG8_SCHED;
;             PG8_LDA(At, 1, 1); PG8_STAGE(PG8_SB(1, 0), b3, voffB); PG8_STAGE(PG8_SB(1, 1), b3 + hstep, voffB); PG8_STAGE(PG8_SA(1, 0), a3, voffA);
;             PG8_WAIT_V(8); PG8_WAIT_L(0); PG8_BAR; PG8_MMA(1, 0, At, B0); PG8_MMA(1, 1, At, B1); PG8_BAR; PG8_SCHED;
;     __device__ __forceinline__ void operator()(const f32x4 (&acc)[2][2][4][2], const pg8::Unit& u, int wr, int wc, int fr, int fq) const {
;         const int row0 = u.pm * 256 + wr * 64 + fr, col0 = u.pn * 256 + wc * 32 + 8 * fq;
; #pragma unroll
;         for (int ai = 0; ai < 2; ++ai) {
;             u32x4 gb[4][2];
; #pragma unroll
;             for (int m = 0; m < 4; ++m)
; #pragma unroll
;                 for (int bj = 0; bj < 2; ++bj) gb[m][bj] = *(const u32x4*)(G + (size_t)(row0 + ai * 128 + m * 16) * 2048 + col0 + bj * 128);
	s_add_i32 s42, s63, s49
	v_lshl_add_u64 v[178:179], v[178:179], 0, s[14:15]
	s_mov_b32 m0, s42
	ds_read_b128 v[200:203], v198 offset:49152
	ds_read_b128 v[204:207], v198 offset:50176
	ds_read_b128 v[208:211], v198 offset:51200
	ds_read_b128 v[212:215], v198 offset:52224
	ds_read_b128 v[216:219], v198 offset:53248
	ds_read_b128 v[220:223], v198 offset:54272
	ds_read_b128 v[224:227], v198 offset:55296
	ds_read_b128 v[228:231], v198 offset:56320
	global_load_lds_dwordx4 v[178:179], off
	s_add_i32 m0, s42, 0x2000
	s_add_u32 s40, s40, 0x40080
	v_lshl_add_u64 v[178:179], v[232:233], 0, s[14:15]
	s_addc_u32 s41, s41, 0
	s_add_i32 s42, s64, s49
	global_load_lds_dwordx4 v[178:179], off
	v_lshl_add_u64 v[178:179], s[40:41], 0, v[154:155]
	s_mov_b32 m0, s42
	s_nop 0
	global_load_lds_dwordx4 v[178:179], off
	v_lshl_add_u64 v[178:179], s[40:41], 0, v[158:159]
	s_add_i32 m0, s42, 0x2000
	s_nop 0
	global_load_lds_dwordx4 v[178:179], off
	v_lshl_add_u64 v[178:179], v[234:235], 0, s[14:15]
	s_mov_b32 m0, s54
	s_nop 0
	global_load_lds_dwordx4 v[178:179], off
	v_lshl_add_u64 v[178:179], v[236:237], 0, s[14:15]
	s_mov_b32 m0, s55
	s_nop 0
	global_load_lds_dwordx4 v[178:179], off
	s_waitcnt vmcnt(8)
	s_waitcnt lgkmcnt(0)
	s_barrier
	s_setprio 1
	s_waitcnt lgkmcnt(0)
	v_mfma_f32_16x16x32_bf16 v[60:63], v[128:131], v[200:203], v[60:63]
	v_mfma_f32_16x16x32_bf16 v[56:59], v[136:139], v[200:203], v[56:59]
	v_mfma_f32_16x16x32_bf16 v[44:47], v[128:131], v[208:211], v[44:47]
	v_mfma_f32_16x16x32_bf16 v[40:43], v[136:139], v[208:211], v[40:43]
	v_mfma_f32_16x16x32_bf16 v[28:31], v[128:131], v[216:219], v[28:31]
	v_mfma_f32_16x16x32_bf16 v[24:27], v[136:139], v[216:219], v[24:27]
	v_mfma_f32_16x16x32_bf16 v[12:15], v[128:131], v[224:227], v[12:15]
	v_mfma_f32_16x16x32_bf16 v[8:11], v[136:139], v[224:227], v[8:11]
	v_mfma_f32_16x16x32_bf16 v[60:63], v[132:135], v[204:207], v[60:63]
	v_mfma_f32_16x16x32_bf16 v[56:59], v[140:143], v[204:207], v[56:59]
	v_mfma_f32_16x16x32_bf16 v[44:47], v[132:135], v[212:215], v[44:47]
	v_mfma_f32_16x16x32_bf16 v[40:43], v[140:143], v[212:215], v[40:43]
	v_mfma_f32_16x16x32_bf16 v[28:31], v[132:135], v[220:223], v[28:31]
	v_mfma_f32_16x16x32_bf16 v[24:27], v[140:143], v[220:223], v[24:27]
	v_mfma_f32_16x16x32_bf16 v[12:15], v[132:135], v[228:231], v[12:15]
	v_mfma_f32_16x16x32_bf16 v[8:11], v[140:143], v[228:231], v[8:11]
	s_setprio 0
	s_setprio 1
	v_mfma_f32_16x16x32_bf16 v[52:55], v[144:147], v[200:203], v[52:55]
	v_mfma_f32_16x16x32_bf16 v[48:51], v[170:173], v[200:203], v[48:51]
	v_mfma_f32_16x16x32_bf16 v[36:39], v[144:147], v[208:211], v[36:39]
	v_mfma_f32_16x16x32_bf16 v[32:35], v[170:173], v[208:211], v[32:35]
	v_mfma_f32_16x16x32_bf16 v[20:23], v[144:147], v[216:219], v[20:23]
	v_mfma_f32_16x16x32_bf16 v[16:19], v[170:173], v[216:219], v[16:19]
	v_mfma_f32_16x16x32_bf16 v[4:7], v[144:147], v[224:227], v[4:7]
	v_mfma_f32_16x16x32_bf16 v[0:3], v[170:173], v[224:227], v[0:3]
	v_mfma_f32_16x16x32_bf16 v[52:55], v[148:151], v[204:207], v[52:55]
	v_mfma_f32_16x16x32_bf16 v[48:51], v[174:177], v[204:207], v[48:51]
	v_mfma_f32_16x16x32_bf16 v[36:39], v[148:151], v[212:215], v[36:39]
	v_mfma_f32_16x16x32_bf16 v[32:35], v[174:177], v[212:215], v[32:35]
	v_mfma_f32_16x16x32_bf16 v[20:23], v[148:151], v[220:223], v[20:23]
	v_mfma_f32_16x16x32_bf16 v[16:19], v[174:177], v[220:223], v[16:19]
	v_mfma_f32_16x16x32_bf16 v[4:7], v[148:151], v[228:231], v[4:7]
	v_mfma_f32_16x16x32_bf16 v[0:3], v[174:177], v[228:231], v[0:3]
	s_setprio 0
	s_barrier
	s_add_i32 s59, s59, 2
	s_add_u32 s38, s38, 0x100
	s_addc_u32 s39, s39, 0
	s_add_u32 s57, s57, 0x100
	s_addc_u32 s58, s58, 0
	s_cmp_gt_u32 s59, 13
	s_cbranch_scc0 .LBB0_840
	s_and_b64 vcc, exec, s[16:17]
	s_cbranch_vccz .LBB0_843
	s_barrier
.LBB0_843:
	v_lshl_or_b32 v130, s1, 8, v195
	v_lshl_add_u32 v128, s36, 8, v193
	v_ashrrev_i32_e32 v131, 31, v130
	v_lshlrev_b64 v[170:171], 1, v[130:131]
	v_ashrrev_i32_e32 v129, 31, v128
	v_lshl_add_u64 v[172:173], s[8:9], 0, v[170:171]
	v_lshlrev_b64 v[174:175], 12, v[128:129]
	v_lshl_add_u64 v[130:131], v[172:173], 0, v[174:175]
	global_load_dwordx4 v[200:203], v[130:131], off
	global_load_dwordx4 v[204:207], v[130:131], off offset:64
	v_or_b32_e32 v130, 16, v128
	v_or_b32_e32 v132, 32, v128
	v_or_b32_e32 v128, 48, v128
	v_ashrrev_i32_e32 v131, 31, v130
	v_ashrrev_i32_e32 v133, 31, v132
	v_ashrrev_i32_e32 v129, 31, v128
	v_lshlrev_b64 v[208:209], 12, v[130:131]
	v_lshlrev_b64 v[178:179], 12, v[132:133]
	v_lshlrev_b64 v[176:177], 12, v[128:129]
	v_lshl_add_u64 v[128:129], s[8:9], 0, v[174:175]
	v_lshl_add_u64 v[130:131], v[172:173], 0, v[208:209]
	v_lshl_add_u64 v[132:133], v[172:173], 0, v[178:179]
	v_lshl_add_u64 v[210:211], v[172:173], 0, v[176:177]
	v_lshl_add_u64 v[212:213], v[128:129], 0, v[170:171]
	global_load_dwordx4 v[148:151], v[130:131], off
	global_load_dwordx4 v[144:147], v[130:131], off offset:64
	global_load_dwordx4 v[140:143], v[132:133], off
	global_load_dwordx4 v[136:139], v[132:133], off offset:64
	s_nop 0
	global_load_dwordx4 v[132:135], v[210:211], off
	global_load_dwordx4 v[128:131], v[210:211], off offset:64
	s_andn2_b64 vcc, exec, s[4:5]
	s_mov_b64 s[4:5], -1
	s_waitcnt vmcnt(0)
; __device__ __forceinline__ unsigned pk2(float lo, float hi) { const f32x2 v = {lo, hi}; const bf16x2_t b = __builtin_convertvector(v, bf16x2_t); return __builtin_bit_cast(unsigned, b); }
; __device__ __forceinline__ float sigmoid_f(float v) { return __builtin_amdgcn_rcpf(1.f + __expf(-v)); }
;     __device__ __forceinline__ void operator()(const f32x4 (&acc)[2][2][4][2], const pg8::Unit& u, int wr, int wc, int fr, int fq) const {
;     ...
;             for (int m = 0; m < 4; ++m) { bf16_t* rowp = G + (size_t)(row0 + ai * 128 + m * 16) * 2048 + col0;
; #pragma unroll
;                 for (int bj = 0; bj < 2; ++bj) { const u32x4 g = gb[m][bj]; const f32x4 v0 = acc[ai][bj][m][0], v1 = acc[ai][bj][m][1];
;                     u32x4 w; w.x = pk2(sigmoid_f(bflo(g.x)) * v0[0], sigmoid_f(bfhi(g.x)) * v0[1]); w.y = pk2(sigmoid_f(bflo(g.y)) * v0[2], sigmoid_f(bfhi(g.y)) * v0[3]);
;                     w.z = pk2(sigmoid_f(bflo(g.z)) * v1[0], sigmoid_f(bfhi(g.z)) * v1[1]); w.w = pk2(sigmoid_f(bflo(g.w)) * v1[2], sigmoid_f(bfhi(g.w)) * v1[3]);
;                     *(u32x4*)(rowp + bj * 128) = w; } }
	v_lshlrev_b32_e32 v199, 16, v200
	v_and_b32_e32 v200, 0xffff0000, v200
	v_lshlrev_b32_e32 v210, 16, v201
	v_and_b32_e32 v201, 0xffff0000, v201
	v_lshlrev_b32_e32 v211, 16, v202
	v_and_b32_e32 v202, 0xffff0000, v202
	v_lshlrev_b32_e32 v214, 16, v203
	v_and_b32_e32 v203, 0xffff0000, v203
	v_lshlrev_b32_e32 v215, 16, v204
	v_and_b32_e32 v204, 0xffff0000, v204
	v_mul_f32_e32 v199, 0xbfb8aa3b, v199
	v_mul_f32_e32 v200, 0xbfb8aa3b, v200
	v_mul_f32_e32 v210, 0xbfb8aa3b, v210
	v_mul_f32_e32 v201, 0xbfb8aa3b, v201
	v_mul_f32_e32 v211, 0xbfb8aa3b, v211
	v_mul_f32_e32 v202, 0xbfb8aa3b, v202
	v_mul_f32_e32 v214, 0xbfb8aa3b, v214
	v_mul_f32_e32 v203, 0xbfb8aa3b, v203
	v_mul_f32_e32 v215, 0xbfb8aa3b, v215
	v_mul_f32_e32 v204, 0xbfb8aa3b, v204
	v_exp_f32_e32 v199, v199
	v_exp_f32_e32 v200, v200
	v_exp_f32_e32 v210, v210
	v_exp_f32_e32 v201, v201
	v_exp_f32_e32 v211, v211
	v_exp_f32_e32 v202, v202
	v_exp_f32_e32 v214, v214
	v_exp_f32_e32 v203, v203
	v_exp_f32_e32 v215, v215
	v_exp_f32_e32 v204, v204
	v_lshlrev_b32_e32 v216, 16, v205
	v_and_b32_e32 v205, 0xffff0000, v205
	v_mul_f32_e32 v205, 0xbfb8aa3b, v205
	v_exp_f32_e32 v217, v205
	v_add_f32_e32 v199, 1.0, v199
	v_add_f32_e32 v205, 1.0, v200
	v_add_f32_e32 v210, 1.0, v210
	v_add_f32_e32 v218, 1.0, v201
	v_add_f32_e32 v211, 1.0, v211
	v_add_f32_e32 v219, 1.0, v202
	v_add_f32_e32 v214, 1.0, v214
	v_add_f32_e32 v220, 1.0, v203
	v_add_f32_e32 v215, 1.0, v215
	v_add_f32_e32 v221, 1.0, v204
	v_rcp_f32_e32 v200, v199
	v_rcp_f32_e32 v201, v205
	v_rcp_f32_e32 v202, v210
	v_rcp_f32_e32 v203, v218
	v_rcp_f32_e32 v204, v211
	v_rcp_f32_e32 v205, v219
	v_rcp_f32_e32 v210, v214
	v_rcp_f32_e32 v211, v220
	v_rcp_f32_e32 v214, v215
	v_rcp_f32_e32 v215, v221
	v_mul_f32_e32 v216, 0xbfb8aa3b, v216
	v_exp_f32_e32 v216, v216
	v_pk_mul_f32 v[124:125], v[124:125], v[200:201]
	v_pk_mul_f32 v[126:127], v[126:127], v[202:203]
	v_pk_mul_f32 v[200:201], v[120:121], v[204:205]
	v_pk_mul_f32 v[202:203], v[122:123], v[210:211]
	v_pk_mul_f32 v[116:117], v[116:117], v[214:215]
	v_cvt_pk_bf16_f32 v120, v124, v125
	v_cvt_pk_bf16_f32 v121, v126, v127
	v_cvt_pk_bf16_f32 v122, v200, v201
	v_cvt_pk_bf16_f32 v123, v202, v203
	v_cvt_pk_bf16_f32 v116, v116, v117
	v_add_f32_e32 v117, 1.0, v217
	v_add_f32_e32 v216, 1.0, v216
	global_store_dwordx4 v[212:213], v[120:123], off
	s_nop 1
	v_rcp_f32_e32 v121, v117
	v_lshlrev_b32_e32 v117, 16, v206
	v_rcp_f32_e32 v120, v216
	v_mul_f32_e32 v117, 0xbfb8aa3b, v117
	v_and_b32_e32 v122, 0xffff0000, v206
	v_exp_f32_e32 v117, v117
	v_mul_f32_e32 v122, 0xbfb8aa3b, v122
	v_exp_f32_e32 v122, v122
	v_pk_mul_f32 v[118:119], v[118:119], v[120:121]
	v_lshlrev_b32_e32 v121, 16, v207
	v_add_f32_e32 v117, 1.0, v117
	v_mul_f32_e32 v121, 0xbfb8aa3b, v121
	v_rcp_f32_e32 v120, v117
	v_add_f32_e32 v117, 1.0, v122
	v_exp_f32_e32 v122, v121
	v_and_b32_e32 v121, 0xffff0000, v207
	v_mul_f32_e32 v121, 0xbfb8aa3b, v121
	v_exp_f32_e32 v123, v121
	v_rcp_f32_e32 v121, v117
	v_add_f32_e32 v117, 1.0, v122
	v_rcp_f32_e32 v122, v117
	v_add_f32_e32 v117, 1.0, v123
	v_rcp_f32_e32 v123, v117
	v_pk_mul_f32 v[112:113], v[112:113], v[120:121]
	v_cvt_pk_bf16_f32 v117, v118, v119
	v_cvt_pk_bf16_f32 v118, v112, v113
	v_pk_mul_f32 v[112:113], v[114:115], v[122:123]
	v_lshlrev_b32_e32 v114, 16, v148
	v_and_b32_e32 v115, 0xffff0000, v148
	v_mul_f32_e32 v114, 0xbfb8aa3b, v114
	v_mul_f32_e32 v115, 0xbfb8aa3b, v115
	v_exp_f32_e32 v114, v114
	v_exp_f32_e32 v115, v115
	v_cvt_pk_bf16_f32 v119, v112, v113
	global_store_dwordx4 v[212:213], v[116:119], off offset:64
	v_add_f32_e32 v114, 1.0, v114
	v_add_f32_e32 v115, 1.0, v115
	v_lshlrev_b32_e32 v116, 16, v149
	v_and_b32_e32 v117, 0xffff0000, v149
	v_mul_f32_e32 v116, 0xbfb8aa3b, v116
	v_mul_f32_e32 v117, 0xbfb8aa3b, v117
	v_rcp_f32_e32 v114, v114
	v_rcp_f32_e32 v115, v115
	v_exp_f32_e32 v116, v116
	v_exp_f32_e32 v117, v117
	v_lshl_add_u64 v[112:113], s[8:9], 0, v[208:209]
	v_pk_mul_f32 v[108:109], v[108:109], v[114:115]
	v_add_f32_e32 v114, 1.0, v116
	v_add_f32_e32 v115, 1.0, v117
	v_rcp_f32_e32 v114, v114
	v_lshlrev_b32_e32 v116, 16, v150
	v_and_b32_e32 v117, 0xffff0000, v150
	v_rcp_f32_e32 v115, v115
	v_mul_f32_e32 v116, 0xbfb8aa3b, v116
	v_mul_f32_e32 v117, 0xbfb8aa3b, v117
	v_exp_f32_e32 v116, v116
	v_exp_f32_e32 v117, v117
	v_pk_mul_f32 v[110:111], v[110:111], v[114:115]
	v_cvt_pk_bf16_f32 v108, v108, v109
	v_cvt_pk_bf16_f32 v109, v110, v111
	v_lshlrev_b32_e32 v110, 16, v151
	v_add_f32_e32 v116, 1.0, v116
	v_add_f32_e32 v117, 1.0, v117
	v_mul_f32_e32 v110, 0xbfb8aa3b, v110
	v_rcp_f32_e32 v116, v116
	v_rcp_f32_e32 v117, v117
	v_exp_f32_e32 v111, v110
	v_and_b32_e32 v110, 0xffff0000, v151
	v_mul_f32_e32 v110, 0xbfb8aa3b, v110
	v_exp_f32_e32 v114, v110
	v_pk_mul_f32 v[104:105], v[104:105], v[116:117]
	v_lshl_add_u64 v[112:113], v[112:113], 0, v[170:171]
	v_cvt_pk_bf16_f32 v110, v104, v105
	v_add_f32_e32 v104, 1.0, v111
	v_lshlrev_b32_e32 v111, 16, v144
	v_add_f32_e32 v105, 1.0, v114
	v_mul_f32_e32 v111, 0xbfb8aa3b, v111
	v_and_b32_e32 v114, 0xffff0000, v144
	v_exp_f32_e32 v111, v111
	v_mul_f32_e32 v114, 0xbfb8aa3b, v114
	v_rcp_f32_e32 v104, v104
	v_exp_f32_e32 v115, v114
	v_rcp_f32_e32 v105, v105
	v_add_f32_e32 v111, 1.0, v111
	v_rcp_f32_e32 v114, v111
	v_add_f32_e32 v111, 1.0, v115
	v_pk_mul_f32 v[104:105], v[106:107], v[104:105]
	v_rcp_f32_e32 v115, v111
	v_cvt_pk_bf16_f32 v111, v104, v105
	v_lshlrev_b32_e32 v104, 16, v145
	v_mul_f32_e32 v104, 0xbfb8aa3b, v104
	v_and_b32_e32 v105, 0xffff0000, v145
	v_exp_f32_e32 v104, v104
	v_mul_f32_e32 v105, 0xbfb8aa3b, v105
	v_exp_f32_e32 v105, v105
	v_pk_mul_f32 v[100:101], v[100:101], v[114:115]
	v_and_b32_e32 v106, 0xffff0000, v146
	v_cvt_pk_bf16_f32 v100, v100, v101
; __device__ __forceinline__ unsigned pk2(float lo, float hi) { const f32x2 v = {lo, hi}; const bf16x2_t b = __builtin_convertvector(v, bf16x2_t); return __builtin_bit_cast(unsigned, b); }
; __device__ __forceinline__ float sigmoid_f(float v) { return __builtin_amdgcn_rcpf(1.f + __expf(-v)); }
;     __device__ __forceinline__ void operator()(const f32x4 (&acc)[2][2][4][2], const pg8::Unit& u, int wr, int wc, int fr, int fq) const {
;     ...
;             for (int m = 0; m < 4; ++m) { bf16_t* rowp = G + (size_t)(row0 + ai * 128 + m * 16) * 2048 + col0;
; #pragma unroll
;                 for (int bj = 0; bj < 2; ++bj) { const u32x4 g = gb[m][bj]; const f32x4 v0 = acc[ai][bj][m][0], v1 = acc[ai][bj][m][1];
;                     u32x4 w; w.x = pk2(sigmoid_f(bflo(g.x)) * v0[0], sigmoid_f(bfhi(g.x)) * v0[1]); w.y = pk2(sigmoid_f(bflo(g.y)) * v0[2], sigmoid_f(bfhi(g.y)) * v0[3]);
;                     w.z = pk2(sigmoid_f(bflo(g.z)) * v1[0], sigmoid_f(bfhi(g.z)) * v1[1]); w.w = pk2(sigmoid_f(bflo(g.w)) * v1[2], sigmoid_f(bfhi(g.w)) * v1[3]);
;                     *(u32x4*)(rowp + bj * 128) = w; } }
	v_add_f32_e32 v101, 1.0, v104
	v_rcp_f32_e32 v104, v101
	v_add_f32_e32 v101, 1.0, v105
	v_rcp_f32_e32 v105, v101
	v_lshlrev_b32_e32 v101, 16, v146
	v_mul_f32_e32 v101, 0xbfb8aa3b, v101
	v_exp_f32_e32 v101, v101
	v_mul_f32_e32 v106, 0xbfb8aa3b, v106
	v_exp_f32_e32 v106, v106
	v_pk_mul_f32 v[102:103], v[102:103], v[104:105]
	v_lshlrev_b32_e32 v105, 16, v147
	v_add_f32_e32 v101, 1.0, v101
	v_mul_f32_e32 v105, 0xbfb8aa3b, v105
	v_rcp_f32_e32 v104, v101
	v_add_f32_e32 v101, 1.0, v106
	v_exp_f32_e32 v106, v105
	v_and_b32_e32 v105, 0xffff0000, v147
	v_mul_f32_e32 v105, 0xbfb8aa3b, v105
	v_exp_f32_e32 v107, v105
	v_rcp_f32_e32 v105, v101
	v_add_f32_e32 v101, 1.0, v106
	v_rcp_f32_e32 v106, v101
	v_add_f32_e32 v101, 1.0, v107
	v_rcp_f32_e32 v107, v101
	v_pk_mul_f32 v[96:97], v[96:97], v[104:105]
	v_cvt_pk_bf16_f32 v101, v102, v103
	v_cvt_pk_bf16_f32 v102, v96, v97
	v_pk_mul_f32 v[96:97], v[98:99], v[106:107]
	v_lshlrev_b32_e32 v98, 16, v140
	v_and_b32_e32 v99, 0xffff0000, v140
	v_mul_f32_e32 v98, 0xbfb8aa3b, v98
	v_mul_f32_e32 v99, 0xbfb8aa3b, v99
	v_exp_f32_e32 v98, v98
	v_exp_f32_e32 v99, v99
	v_cvt_pk_bf16_f32 v103, v96, v97
	global_store_dwordx4 v[112:113], v[100:103], off offset:64
	v_add_f32_e32 v98, 1.0, v98
	v_add_f32_e32 v99, 1.0, v99
	v_lshlrev_b32_e32 v100, 16, v141
	v_and_b32_e32 v101, 0xffff0000, v141
	v_mul_f32_e32 v100, 0xbfb8aa3b, v100
	v_mul_f32_e32 v101, 0xbfb8aa3b, v101
	v_rcp_f32_e32 v98, v98
	v_rcp_f32_e32 v99, v99
	v_exp_f32_e32 v100, v100
	v_exp_f32_e32 v101, v101
	v_lshl_add_u64 v[96:97], s[8:9], 0, v[178:179]
	v_pk_mul_f32 v[92:93], v[92:93], v[98:99]
	v_add_f32_e32 v98, 1.0, v100
	v_add_f32_e32 v99, 1.0, v101
	v_rcp_f32_e32 v98, v98
	v_lshlrev_b32_e32 v100, 16, v142
	v_and_b32_e32 v101, 0xffff0000, v142
	v_rcp_f32_e32 v99, v99
	v_mul_f32_e32 v100, 0xbfb8aa3b, v100
	v_mul_f32_e32 v101, 0xbfb8aa3b, v101
	v_exp_f32_e32 v100, v100
	v_exp_f32_e32 v101, v101
	v_pk_mul_f32 v[94:95], v[94:95], v[98:99]
	v_cvt_pk_bf16_f32 v92, v92, v93
	v_cvt_pk_bf16_f32 v93, v94, v95
	v_lshlrev_b32_e32 v94, 16, v143
	v_add_f32_e32 v100, 1.0, v100
	v_add_f32_e32 v101, 1.0, v101
	v_mul_f32_e32 v94, 0xbfb8aa3b, v94
	v_rcp_f32_e32 v100, v100
	v_rcp_f32_e32 v101, v101
	v_exp_f32_e32 v95, v94
	v_and_b32_e32 v94, 0xffff0000, v143
	v_mul_f32_e32 v94, 0xbfb8aa3b, v94
	v_exp_f32_e32 v98, v94
	v_pk_mul_f32 v[88:89], v[88:89], v[100:101]
	v_lshl_add_u64 v[96:97], v[96:97], 0, v[170:171]
	v_cvt_pk_bf16_f32 v94, v88, v89
	v_add_f32_e32 v88, 1.0, v95
	v_lshlrev_b32_e32 v95, 16, v136
	v_add_f32_e32 v89, 1.0, v98
	v_mul_f32_e32 v95, 0xbfb8aa3b, v95
	v_and_b32_e32 v98, 0xffff0000, v136
	v_exp_f32_e32 v95, v95
	v_mul_f32_e32 v98, 0xbfb8aa3b, v98
	v_rcp_f32_e32 v88, v88
	v_exp_f32_e32 v99, v98
	v_rcp_f32_e32 v89, v89
	v_add_f32_e32 v95, 1.0, v95
	v_rcp_f32_e32 v98, v95
	v_add_f32_e32 v95, 1.0, v99
	v_pk_mul_f32 v[88:89], v[90:91], v[88:89]
	v_rcp_f32_e32 v99, v95
	v_cvt_pk_bf16_f32 v95, v88, v89
	v_lshlrev_b32_e32 v88, 16, v137
	v_mul_f32_e32 v88, 0xbfb8aa3b, v88
	v_and_b32_e32 v89, 0xffff0000, v137
	v_exp_f32_e32 v88, v88
	v_mul_f32_e32 v89, 0xbfb8aa3b, v89
	v_exp_f32_e32 v89, v89
	v_pk_mul_f32 v[84:85], v[84:85], v[98:99]
	v_and_b32_e32 v90, 0xffff0000, v138
	v_cvt_pk_bf16_f32 v84, v84, v85
	v_add_f32_e32 v85, 1.0, v88
	v_rcp_f32_e32 v88, v85
	v_add_f32_e32 v85, 1.0, v89
	v_rcp_f32_e32 v89, v85
	v_lshlrev_b32_e32 v85, 16, v138
	v_mul_f32_e32 v85, 0xbfb8aa3b, v85
	v_exp_f32_e32 v85, v85
	v_mul_f32_e32 v90, 0xbfb8aa3b, v90
	v_exp_f32_e32 v90, v90
	v_pk_mul_f32 v[86:87], v[86:87], v[88:89]
	v_lshlrev_b32_e32 v89, 16, v139
	v_add_f32_e32 v85, 1.0, v85
	v_mul_f32_e32 v89, 0xbfb8aa3b, v89
	v_rcp_f32_e32 v88, v85
	v_add_f32_e32 v85, 1.0, v90
	v_exp_f32_e32 v90, v89
	v_and_b32_e32 v89, 0xffff0000, v139
	v_mul_f32_e32 v89, 0xbfb8aa3b, v89
	v_exp_f32_e32 v91, v89
	v_rcp_f32_e32 v89, v85
	v_add_f32_e32 v85, 1.0, v90
	v_rcp_f32_e32 v90, v85
	v_add_f32_e32 v85, 1.0, v91
	v_rcp_f32_e32 v91, v85
	v_pk_mul_f32 v[80:81], v[80:81], v[88:89]
	v_cvt_pk_bf16_f32 v85, v86, v87
	v_cvt_pk_bf16_f32 v86, v80, v81
	v_pk_mul_f32 v[80:81], v[82:83], v[90:91]
	v_lshlrev_b32_e32 v82, 16, v132
	v_and_b32_e32 v83, 0xffff0000, v132
	v_mul_f32_e32 v82, 0xbfb8aa3b, v82
	v_mul_f32_e32 v83, 0xbfb8aa3b, v83
	v_exp_f32_e32 v82, v82
	v_exp_f32_e32 v83, v83
	v_cvt_pk_bf16_f32 v87, v80, v81
	global_store_dwordx4 v[96:97], v[84:87], off offset:64
	v_add_f32_e32 v80, 1.0, v82
	v_add_f32_e32 v81, 1.0, v83
	v_rcp_f32_e32 v80, v80
	v_rcp_f32_e32 v81, v81
	v_and_b32_e32 v84, 0xffff0000, v134
	v_mul_f32_e32 v84, 0xbfb8aa3b, v84
	v_exp_f32_e32 v84, v84
	v_pk_mul_f32 v[76:77], v[76:77], v[80:81]
	v_lshlrev_b32_e32 v80, 16, v133
	v_mul_f32_e32 v80, 0xbfb8aa3b, v80
	v_and_b32_e32 v81, 0xffff0000, v133
	v_exp_f32_e32 v80, v80
	v_mul_f32_e32 v81, 0xbfb8aa3b, v81
	v_exp_f32_e32 v81, v81
	v_cvt_pk_bf16_f32 v76, v76, v77
	v_add_f32_e32 v77, 1.0, v80
	v_rcp_f32_e32 v80, v77
	v_add_f32_e32 v77, 1.0, v81
	v_rcp_f32_e32 v81, v77
	v_lshlrev_b32_e32 v77, 16, v134
	v_mul_f32_e32 v77, 0xbfb8aa3b, v77
	v_exp_f32_e32 v77, v77
	v_lshl_add_u64 v[100:101], v[174:175], 0, s[18:19]
	v_pk_mul_f32 v[78:79], v[78:79], v[80:81]
	v_lshlrev_b32_e32 v81, 16, v135
	v_add_f32_e32 v77, 1.0, v77
	v_rcp_f32_e32 v80, v77
	v_add_f32_e32 v77, 1.0, v84
	v_lshl_add_u64 v[84:85], v[172:173], 0, v[100:101]
	global_load_dwordx4 v[88:91], v[84:85], off
	v_mul_f32_e32 v81, 0xbfb8aa3b, v81
	v_exp_f32_e32 v86, v81
	v_and_b32_e32 v81, 0xffff0000, v135
	v_mul_f32_e32 v81, 0xbfb8aa3b, v81
	v_exp_f32_e32 v87, v81
	v_rcp_f32_e32 v81, v77
	v_add_f32_e32 v77, 1.0, v86
	v_rcp_f32_e32 v86, v77
	v_add_f32_e32 v77, 1.0, v87
	v_rcp_f32_e32 v87, v77
; __device__ __forceinline__ unsigned pk2(float lo, float hi) { const f32x2 v = {lo, hi}; const bf16x2_t b = __builtin_convertvector(v, bf16x2_t); return __builtin_bit_cast(unsigned, b); }
; __device__ __forceinline__ float sigmoid_f(float v) { return __builtin_amdgcn_rcpf(1.f + __expf(-v)); }
;     __device__ __forceinline__ void operator()(const f32x4 (&acc)[2][2][4][2], const pg8::Unit& u, int wr, int wc, int fr, int fq) const {
;     ...
;         for (int ai = 0; ai < 2; ++ai) {
;             u32x4 gb[4][2];
; #pragma unroll
;             for (int m = 0; m < 4; ++m)
; #pragma unroll
;                 for (int bj = 0; bj < 2; ++bj) gb[m][bj] = *(const u32x4*)(G + (size_t)(row0 + ai * 128 + m * 16) * 2048 + col0 + bj * 128);
;             asm volatile("" ::: "memory");
; #pragma unroll
;             for (int m = 0; m < 4; ++m) { bf16_t* rowp = G + (size_t)(row0 + ai * 128 + m * 16) * 2048 + col0;
; #pragma unroll
;                 for (int bj = 0; bj < 2; ++bj) { const u32x4 g = gb[m][bj]; const f32x4 v0 = acc[ai][bj][m][0], v1 = acc[ai][bj][m][1];
;                     u32x4 w; w.x = pk2(sigmoid_f(bflo(g.x)) * v0[0], sigmoid_f(bfhi(g.x)) * v0[1]); w.y = pk2(sigmoid_f(bflo(g.y)) * v0[2], sigmoid_f(bfhi(g.y)) * v0[3]);
;                     w.z = pk2(sigmoid_f(bflo(g.z)) * v1[0], sigmoid_f(bfhi(g.z)) * v1[1]); w.w = pk2(sigmoid_f(bflo(g.w)) * v1[2], sigmoid_f(bfhi(g.w)) * v1[3]);
;                     *(u32x4*)(rowp + bj * 128) = w; } }
	v_pk_mul_f32 v[72:73], v[72:73], v[80:81]
	global_store_dwordx4 v[96:97], v[92:95], off
	v_cvt_pk_bf16_f32 v77, v78, v79
	v_cvt_pk_bf16_f32 v78, v72, v73
	v_pk_mul_f32 v[72:73], v[74:75], v[86:87]
	v_lshlrev_b32_e32 v74, 16, v128
	v_and_b32_e32 v75, 0xffff0000, v128
	global_load_dwordx4 v[92:95], v[84:85], off offset:64
	v_mul_f32_e32 v74, 0xbfb8aa3b, v74
	v_mul_f32_e32 v75, 0xbfb8aa3b, v75
	v_exp_f32_e32 v74, v74
	v_exp_f32_e32 v75, v75
	v_cvt_pk_bf16_f32 v79, v72, v73
	v_lshl_add_u64 v[82:83], s[8:9], 0, v[176:177]
	v_add_f32_e32 v72, 1.0, v74
	v_add_f32_e32 v73, 1.0, v75
	v_rcp_f32_e32 v72, v72
	v_rcp_f32_e32 v73, v73
	v_lshlrev_b32_e32 v74, 16, v129
	v_and_b32_e32 v75, 0xffff0000, v129
	v_mul_f32_e32 v74, 0xbfb8aa3b, v74
	v_mul_f32_e32 v75, 0xbfb8aa3b, v75
	v_pk_mul_f32 v[68:69], v[68:69], v[72:73]
	v_exp_f32_e32 v74, v74
	v_exp_f32_e32 v75, v75
	v_cvt_pk_bf16_f32 v68, v68, v69
	v_lshlrev_b32_e32 v69, 16, v130
	v_mul_f32_e32 v69, 0xbfb8aa3b, v69
	v_and_b32_e32 v72, 0xffff0000, v130
	v_exp_f32_e32 v69, v69
	v_mul_f32_e32 v72, 0xbfb8aa3b, v72
	v_exp_f32_e32 v73, v72
	v_add_f32_e32 v74, 1.0, v74
	v_add_f32_e32 v75, 1.0, v75
	v_rcp_f32_e32 v74, v74
	v_rcp_f32_e32 v75, v75
	v_add_f32_e32 v69, 1.0, v69
	v_rcp_f32_e32 v72, v69
	v_add_f32_e32 v69, 1.0, v73
	v_lshlrev_b32_e32 v73, 16, v131
	v_mul_f32_e32 v73, 0xbfb8aa3b, v73
	v_pk_mul_f32 v[70:71], v[70:71], v[74:75]
	v_exp_f32_e32 v74, v73
	v_and_b32_e32 v73, 0xffff0000, v131
	v_mul_f32_e32 v73, 0xbfb8aa3b, v73
	v_exp_f32_e32 v75, v73
	v_rcp_f32_e32 v73, v69
	v_add_f32_e32 v69, 1.0, v74
	v_rcp_f32_e32 v74, v69
	v_add_f32_e32 v69, 1.0, v75
	v_rcp_f32_e32 v75, v69
	v_pk_mul_f32 v[64:65], v[64:65], v[72:73]
	v_cvt_pk_bf16_f32 v69, v70, v71
	v_cvt_pk_bf16_f32 v70, v64, v65
	v_pk_mul_f32 v[64:65], v[66:67], v[74:75]
	v_lshl_add_u64 v[82:83], v[82:83], 0, v[170:171]
	v_cvt_pk_bf16_f32 v71, v64, v65
	v_lshl_add_u64 v[102:103], v[174:175], 0, s[20:21]
	global_store_dwordx4 v[112:113], v[108:111], off
	global_store_dwordx4 v[82:83], v[76:79], off
	global_store_dwordx4 v[82:83], v[68:71], off offset:64
	v_lshl_add_u64 v[64:65], v[172:173], 0, v[102:103]
	global_load_dwordx4 v[96:99], v[64:65], off
	global_load_dwordx4 v[80:83], v[64:65], off offset:64
	v_lshl_add_u64 v[86:87], v[174:175], 0, s[22:23]
	v_lshl_add_u64 v[64:65], v[172:173], 0, v[86:87]
	global_load_dwordx4 v[76:79], v[64:65], off
	global_load_dwordx4 v[72:75], v[64:65], off offset:64
	v_lshl_add_u64 v[84:85], v[174:175], 0, s[24:25]
	v_lshl_add_u64 v[100:101], s[8:9], 0, v[100:101]
	v_lshl_add_u64 v[64:65], v[172:173], 0, v[84:85]
	s_waitcnt vmcnt(9)
	v_lshlrev_b32_e32 v104, 16, v88
	v_and_b32_e32 v88, 0xffff0000, v88
	v_mul_f32_e32 v88, 0xbfb8aa3b, v88
	v_exp_f32_e32 v88, v88
	v_mul_f32_e32 v104, 0xbfb8aa3b, v104
	v_exp_f32_e32 v104, v104
	v_lshl_add_u64 v[100:101], v[100:101], 0, v[170:171]
	v_add_f32_e32 v88, 1.0, v88
	v_rcp_f32_e32 v105, v88
	v_lshlrev_b32_e32 v88, 16, v89
	v_and_b32_e32 v89, 0xffff0000, v89
	v_mul_f32_e32 v88, 0xbfb8aa3b, v88
	v_mul_f32_e32 v89, 0xbfb8aa3b, v89
	v_add_f32_e32 v104, 1.0, v104
	v_exp_f32_e32 v88, v88
	v_exp_f32_e32 v89, v89
	v_rcp_f32_e32 v104, v104
	global_load_dwordx4 v[68:71], v[64:65], off
	s_nop 0
	global_load_dwordx4 v[64:67], v[64:65], off offset:64
	v_add_f32_e32 v88, 1.0, v88
	v_add_f32_e32 v89, 1.0, v89
	v_pk_mul_f32 v[60:61], v[60:61], v[104:105]
	v_rcp_f32_e32 v88, v88
	v_lshlrev_b32_e32 v104, 16, v90
	v_and_b32_e32 v90, 0xffff0000, v90
	v_rcp_f32_e32 v89, v89
	v_mul_f32_e32 v104, 0xbfb8aa3b, v104
	v_mul_f32_e32 v90, 0xbfb8aa3b, v90
	v_exp_f32_e32 v104, v104
	v_exp_f32_e32 v90, v90
	v_pk_mul_f32 v[62:63], v[62:63], v[88:89]
	v_cvt_pk_bf16_f32 v60, v60, v61
	v_cvt_pk_bf16_f32 v61, v62, v63
	v_lshlrev_b32_e32 v62, 16, v91
	v_add_f32_e32 v104, 1.0, v104
	v_add_f32_e32 v90, 1.0, v90
	v_mul_f32_e32 v62, 0xbfb8aa3b, v62
	v_rcp_f32_e32 v104, v104
	v_rcp_f32_e32 v105, v90
	v_exp_f32_e32 v63, v62
	v_and_b32_e32 v62, 0xffff0000, v91
	v_mul_f32_e32 v62, 0xbfb8aa3b, v62
	v_exp_f32_e32 v88, v62
	v_pk_mul_f32 v[56:57], v[56:57], v[104:105]
	s_nop 0
	v_cvt_pk_bf16_f32 v62, v56, v57
	v_add_f32_e32 v56, 1.0, v63
	s_waitcnt vmcnt(9)
	v_lshlrev_b32_e32 v63, 16, v92
	v_add_f32_e32 v57, 1.0, v88
	v_mul_f32_e32 v63, 0xbfb8aa3b, v63
	v_and_b32_e32 v88, 0xffff0000, v92
	v_exp_f32_e32 v63, v63
	v_mul_f32_e32 v88, 0xbfb8aa3b, v88
	v_rcp_f32_e32 v56, v56
	v_exp_f32_e32 v89, v88
	v_rcp_f32_e32 v57, v57
	v_add_f32_e32 v63, 1.0, v63
	v_rcp_f32_e32 v88, v63
	v_add_f32_e32 v63, 1.0, v89
	v_pk_mul_f32 v[56:57], v[58:59], v[56:57]
	v_rcp_f32_e32 v89, v63
	v_cvt_pk_bf16_f32 v63, v56, v57
	v_lshlrev_b32_e32 v56, 16, v93
	v_mul_f32_e32 v56, 0xbfb8aa3b, v56
	v_and_b32_e32 v57, 0xffff0000, v93
	v_exp_f32_e32 v56, v56
	v_mul_f32_e32 v57, 0xbfb8aa3b, v57
	v_exp_f32_e32 v57, v57
	v_pk_mul_f32 v[52:53], v[52:53], v[88:89]
	v_and_b32_e32 v58, 0xffff0000, v94
	v_cvt_pk_bf16_f32 v52, v52, v53
	v_add_f32_e32 v53, 1.0, v56
	v_rcp_f32_e32 v56, v53
	v_add_f32_e32 v53, 1.0, v57
	v_rcp_f32_e32 v57, v53
	v_lshlrev_b32_e32 v53, 16, v94
	v_mul_f32_e32 v53, 0xbfb8aa3b, v53
	v_exp_f32_e32 v53, v53
	v_mul_f32_e32 v58, 0xbfb8aa3b, v58
	v_exp_f32_e32 v58, v58
	v_pk_mul_f32 v[54:55], v[54:55], v[56:57]
	v_lshlrev_b32_e32 v57, 16, v95
	v_add_f32_e32 v53, 1.0, v53
	v_mul_f32_e32 v57, 0xbfb8aa3b, v57
	v_rcp_f32_e32 v56, v53
	v_add_f32_e32 v53, 1.0, v58
	v_exp_f32_e32 v58, v57
	v_and_b32_e32 v57, 0xffff0000, v95
	v_mul_f32_e32 v57, 0xbfb8aa3b, v57
	v_exp_f32_e32 v59, v57
	v_rcp_f32_e32 v57, v53
	v_add_f32_e32 v53, 1.0, v58
	v_rcp_f32_e32 v58, v53
	v_add_f32_e32 v53, 1.0, v59
	v_rcp_f32_e32 v59, v53
	v_pk_mul_f32 v[48:49], v[48:49], v[56:57]
	v_cvt_pk_bf16_f32 v53, v54, v55
	v_cvt_pk_bf16_f32 v54, v48, v49
	v_pk_mul_f32 v[48:49], v[50:51], v[58:59]
	s_waitcnt vmcnt(5)
; __device__ __forceinline__ unsigned pk2(float lo, float hi) { const f32x2 v = {lo, hi}; const bf16x2_t b = __builtin_convertvector(v, bf16x2_t); return __builtin_bit_cast(unsigned, b); }
; __device__ __forceinline__ float sigmoid_f(float v) { return __builtin_amdgcn_rcpf(1.f + __expf(-v)); }
;     __device__ __forceinline__ void operator()(const f32x4 (&acc)[2][2][4][2], const pg8::Unit& u, int wr, int wc, int fr, int fq) const {
;     ...
;             for (int m = 0; m < 4; ++m) { bf16_t* rowp = G + (size_t)(row0 + ai * 128 + m * 16) * 2048 + col0;
; #pragma unroll
;                 for (int bj = 0; bj < 2; ++bj) { const u32x4 g = gb[m][bj]; const f32x4 v0 = acc[ai][bj][m][0], v1 = acc[ai][bj][m][1];
;                     u32x4 w; w.x = pk2(sigmoid_f(bflo(g.x)) * v0[0], sigmoid_f(bfhi(g.x)) * v0[1]); w.y = pk2(sigmoid_f(bflo(g.y)) * v0[2], sigmoid_f(bfhi(g.y)) * v0[3]);
;                     w.z = pk2(sigmoid_f(bflo(g.z)) * v1[0], sigmoid_f(bfhi(g.z)) * v1[1]); w.w = pk2(sigmoid_f(bflo(g.w)) * v1[2], sigmoid_f(bfhi(g.w)) * v1[3]);
;                     *(u32x4*)(rowp + bj * 128) = w; } }
	v_lshlrev_b32_e32 v50, 16, v96
	v_and_b32_e32 v51, 0xffff0000, v96
	v_mul_f32_e32 v50, 0xbfb8aa3b, v50
	v_mul_f32_e32 v51, 0xbfb8aa3b, v51
	v_exp_f32_e32 v50, v50
	v_exp_f32_e32 v51, v51
	v_cvt_pk_bf16_f32 v55, v48, v49
	global_store_dwordx4 v[100:101], v[52:55], off offset:64
	v_add_f32_e32 v50, 1.0, v50
	v_add_f32_e32 v51, 1.0, v51
	v_lshlrev_b32_e32 v52, 16, v97
	v_and_b32_e32 v53, 0xffff0000, v97
	v_mul_f32_e32 v52, 0xbfb8aa3b, v52
	v_mul_f32_e32 v53, 0xbfb8aa3b, v53
	v_rcp_f32_e32 v50, v50
	v_rcp_f32_e32 v51, v51
	v_exp_f32_e32 v52, v52
	v_exp_f32_e32 v53, v53
	v_lshl_add_u64 v[48:49], s[8:9], 0, v[102:103]
	v_pk_mul_f32 v[44:45], v[44:45], v[50:51]
	v_add_f32_e32 v50, 1.0, v52
	v_add_f32_e32 v51, 1.0, v53
	v_rcp_f32_e32 v50, v50
	v_lshlrev_b32_e32 v52, 16, v98
	v_and_b32_e32 v53, 0xffff0000, v98
	v_rcp_f32_e32 v51, v51
	v_mul_f32_e32 v52, 0xbfb8aa3b, v52
	v_mul_f32_e32 v53, 0xbfb8aa3b, v53
	v_exp_f32_e32 v52, v52
	v_exp_f32_e32 v53, v53
	v_pk_mul_f32 v[46:47], v[46:47], v[50:51]
	v_cvt_pk_bf16_f32 v44, v44, v45
	v_cvt_pk_bf16_f32 v45, v46, v47
	v_lshlrev_b32_e32 v46, 16, v99
	v_add_f32_e32 v52, 1.0, v52
	v_add_f32_e32 v53, 1.0, v53
	v_mul_f32_e32 v46, 0xbfb8aa3b, v46
	v_rcp_f32_e32 v52, v52
	v_rcp_f32_e32 v53, v53
	v_exp_f32_e32 v47, v46
	v_and_b32_e32 v46, 0xffff0000, v99
	v_mul_f32_e32 v46, 0xbfb8aa3b, v46
	v_exp_f32_e32 v50, v46
	v_pk_mul_f32 v[40:41], v[40:41], v[52:53]
	v_lshl_add_u64 v[48:49], v[48:49], 0, v[170:171]
	v_cvt_pk_bf16_f32 v46, v40, v41
	v_add_f32_e32 v40, 1.0, v47
	s_waitcnt vmcnt(5)
	v_lshlrev_b32_e32 v47, 16, v80
	v_add_f32_e32 v41, 1.0, v50
	v_mul_f32_e32 v47, 0xbfb8aa3b, v47
	v_and_b32_e32 v50, 0xffff0000, v80
	v_exp_f32_e32 v47, v47
	v_mul_f32_e32 v50, 0xbfb8aa3b, v50
	v_rcp_f32_e32 v40, v40
	v_exp_f32_e32 v51, v50
	v_rcp_f32_e32 v41, v41
	v_add_f32_e32 v47, 1.0, v47
	v_rcp_f32_e32 v50, v47
	v_add_f32_e32 v47, 1.0, v51
	v_pk_mul_f32 v[40:41], v[42:43], v[40:41]
	v_rcp_f32_e32 v51, v47
	v_cvt_pk_bf16_f32 v47, v40, v41
	v_lshlrev_b32_e32 v40, 16, v81
	v_mul_f32_e32 v40, 0xbfb8aa3b, v40
	v_and_b32_e32 v41, 0xffff0000, v81
	v_exp_f32_e32 v40, v40
	v_mul_f32_e32 v41, 0xbfb8aa3b, v41
	v_exp_f32_e32 v41, v41
	v_pk_mul_f32 v[36:37], v[36:37], v[50:51]
	v_and_b32_e32 v42, 0xffff0000, v82
	v_cvt_pk_bf16_f32 v36, v36, v37
	v_add_f32_e32 v37, 1.0, v40
	v_rcp_f32_e32 v40, v37
	v_add_f32_e32 v37, 1.0, v41
	v_rcp_f32_e32 v41, v37
	v_lshlrev_b32_e32 v37, 16, v82
	v_mul_f32_e32 v37, 0xbfb8aa3b, v37
	v_exp_f32_e32 v37, v37
	v_mul_f32_e32 v42, 0xbfb8aa3b, v42
	v_exp_f32_e32 v42, v42
	v_pk_mul_f32 v[38:39], v[38:39], v[40:41]
	v_lshlrev_b32_e32 v41, 16, v83
	v_add_f32_e32 v37, 1.0, v37
	v_mul_f32_e32 v41, 0xbfb8aa3b, v41
	v_rcp_f32_e32 v40, v37
	v_add_f32_e32 v37, 1.0, v42
	v_exp_f32_e32 v42, v41
	v_and_b32_e32 v41, 0xffff0000, v83
	v_mul_f32_e32 v41, 0xbfb8aa3b, v41
	v_exp_f32_e32 v43, v41
	v_rcp_f32_e32 v41, v37
	v_add_f32_e32 v37, 1.0, v42
	v_rcp_f32_e32 v42, v37
	v_add_f32_e32 v37, 1.0, v43
	v_rcp_f32_e32 v43, v37
	v_pk_mul_f32 v[32:33], v[32:33], v[40:41]
	v_cvt_pk_bf16_f32 v37, v38, v39
	v_cvt_pk_bf16_f32 v38, v32, v33
	v_pk_mul_f32 v[32:33], v[34:35], v[42:43]
	s_waitcnt vmcnt(4)
	v_lshlrev_b32_e32 v34, 16, v76
	v_and_b32_e32 v35, 0xffff0000, v76
	v_mul_f32_e32 v34, 0xbfb8aa3b, v34
	v_mul_f32_e32 v35, 0xbfb8aa3b, v35
	v_exp_f32_e32 v34, v34
	v_exp_f32_e32 v35, v35
	v_cvt_pk_bf16_f32 v39, v32, v33
	global_store_dwordx4 v[48:49], v[36:39], off offset:64
	v_add_f32_e32 v34, 1.0, v34
	v_add_f32_e32 v35, 1.0, v35
	v_lshlrev_b32_e32 v36, 16, v77
	v_and_b32_e32 v37, 0xffff0000, v77
	v_mul_f32_e32 v36, 0xbfb8aa3b, v36
	v_mul_f32_e32 v37, 0xbfb8aa3b, v37
	v_rcp_f32_e32 v34, v34
	v_rcp_f32_e32 v35, v35
	v_exp_f32_e32 v36, v36
	v_exp_f32_e32 v37, v37
	v_lshl_add_u64 v[32:33], s[8:9], 0, v[86:87]
	v_pk_mul_f32 v[28:29], v[28:29], v[34:35]
	v_add_f32_e32 v34, 1.0, v36
	v_add_f32_e32 v35, 1.0, v37
	v_rcp_f32_e32 v34, v34
	v_lshlrev_b32_e32 v36, 16, v78
	v_and_b32_e32 v37, 0xffff0000, v78
	v_rcp_f32_e32 v35, v35
	v_mul_f32_e32 v36, 0xbfb8aa3b, v36
	v_mul_f32_e32 v37, 0xbfb8aa3b, v37
	v_exp_f32_e32 v36, v36
	v_exp_f32_e32 v37, v37
	v_pk_mul_f32 v[30:31], v[30:31], v[34:35]
	v_cvt_pk_bf16_f32 v28, v28, v29
	v_cvt_pk_bf16_f32 v29, v30, v31
	v_lshlrev_b32_e32 v30, 16, v79
	v_add_f32_e32 v36, 1.0, v36
	v_add_f32_e32 v37, 1.0, v37
	v_mul_f32_e32 v30, 0xbfb8aa3b, v30
	v_rcp_f32_e32 v36, v36
	v_rcp_f32_e32 v37, v37
	v_exp_f32_e32 v31, v30
	v_and_b32_e32 v30, 0xffff0000, v79
	v_mul_f32_e32 v30, 0xbfb8aa3b, v30
	v_exp_f32_e32 v34, v30
	v_pk_mul_f32 v[24:25], v[24:25], v[36:37]
	v_lshl_add_u64 v[32:33], v[32:33], 0, v[170:171]
	v_cvt_pk_bf16_f32 v30, v24, v25
	v_add_f32_e32 v24, 1.0, v31
	s_waitcnt vmcnt(4)
; __device__ __forceinline__ unsigned pk2(float lo, float hi) { const f32x2 v = {lo, hi}; const bf16x2_t b = __builtin_convertvector(v, bf16x2_t); return __builtin_bit_cast(unsigned, b); }
; __device__ __forceinline__ float sigmoid_f(float v) { return __builtin_amdgcn_rcpf(1.f + __expf(-v)); }
;     __device__ __forceinline__ void operator()(const f32x4 (&acc)[2][2][4][2], const pg8::Unit& u, int wr, int wc, int fr, int fq) const {
;     ...
;             for (int m = 0; m < 4; ++m) { bf16_t* rowp = G + (size_t)(row0 + ai * 128 + m * 16) * 2048 + col0;
; #pragma unroll
;                 for (int bj = 0; bj < 2; ++bj) { const u32x4 g = gb[m][bj]; const f32x4 v0 = acc[ai][bj][m][0], v1 = acc[ai][bj][m][1];
;                     u32x4 w; w.x = pk2(sigmoid_f(bflo(g.x)) * v0[0], sigmoid_f(bfhi(g.x)) * v0[1]); w.y = pk2(sigmoid_f(bflo(g.y)) * v0[2], sigmoid_f(bfhi(g.y)) * v0[3]);
;                     w.z = pk2(sigmoid_f(bflo(g.z)) * v1[0], sigmoid_f(bfhi(g.z)) * v1[1]); w.w = pk2(sigmoid_f(bflo(g.w)) * v1[2], sigmoid_f(bfhi(g.w)) * v1[3]);
;                     *(u32x4*)(rowp + bj * 128) = w; } }
	v_lshlrev_b32_e32 v31, 16, v72
	v_add_f32_e32 v25, 1.0, v34
	v_mul_f32_e32 v31, 0xbfb8aa3b, v31
	v_and_b32_e32 v34, 0xffff0000, v72
	v_exp_f32_e32 v31, v31
	v_mul_f32_e32 v34, 0xbfb8aa3b, v34
	v_rcp_f32_e32 v24, v24
	v_exp_f32_e32 v35, v34
	v_rcp_f32_e32 v25, v25
	v_add_f32_e32 v31, 1.0, v31
	v_rcp_f32_e32 v34, v31
	v_add_f32_e32 v31, 1.0, v35
	v_pk_mul_f32 v[24:25], v[26:27], v[24:25]
	v_rcp_f32_e32 v35, v31
	v_cvt_pk_bf16_f32 v31, v24, v25
	v_lshlrev_b32_e32 v24, 16, v73
	v_mul_f32_e32 v24, 0xbfb8aa3b, v24
	v_and_b32_e32 v25, 0xffff0000, v73
	v_exp_f32_e32 v24, v24
	v_mul_f32_e32 v25, 0xbfb8aa3b, v25
	v_exp_f32_e32 v25, v25
	v_pk_mul_f32 v[20:21], v[20:21], v[34:35]
	v_and_b32_e32 v26, 0xffff0000, v74
	v_cvt_pk_bf16_f32 v20, v20, v21
	v_add_f32_e32 v21, 1.0, v24
	v_rcp_f32_e32 v24, v21
	v_add_f32_e32 v21, 1.0, v25
	v_rcp_f32_e32 v25, v21
	v_lshlrev_b32_e32 v21, 16, v74
	v_mul_f32_e32 v21, 0xbfb8aa3b, v21
	v_exp_f32_e32 v21, v21
	v_mul_f32_e32 v26, 0xbfb8aa3b, v26
	v_exp_f32_e32 v26, v26
	v_pk_mul_f32 v[22:23], v[22:23], v[24:25]
	v_lshlrev_b32_e32 v25, 16, v75
	v_add_f32_e32 v21, 1.0, v21
	v_mul_f32_e32 v25, 0xbfb8aa3b, v25
	v_rcp_f32_e32 v24, v21
	v_add_f32_e32 v21, 1.0, v26
	v_exp_f32_e32 v26, v25
	v_and_b32_e32 v25, 0xffff0000, v75
	v_mul_f32_e32 v25, 0xbfb8aa3b, v25
	v_exp_f32_e32 v27, v25
	v_rcp_f32_e32 v25, v21
	v_add_f32_e32 v21, 1.0, v26
	v_rcp_f32_e32 v26, v21
	v_add_f32_e32 v21, 1.0, v27
	v_rcp_f32_e32 v27, v21
	v_pk_mul_f32 v[16:17], v[16:17], v[24:25]
	v_cvt_pk_bf16_f32 v21, v22, v23
	v_cvt_pk_bf16_f32 v22, v16, v17
	v_pk_mul_f32 v[16:17], v[18:19], v[26:27]
	s_waitcnt vmcnt(3)
	v_lshlrev_b32_e32 v18, 16, v68
	v_and_b32_e32 v19, 0xffff0000, v68
	v_mul_f32_e32 v18, 0xbfb8aa3b, v18
	v_mul_f32_e32 v19, 0xbfb8aa3b, v19
	v_exp_f32_e32 v18, v18
	v_exp_f32_e32 v19, v19
	v_cvt_pk_bf16_f32 v23, v16, v17
	global_store_dwordx4 v[32:33], v[20:23], off offset:64
	v_add_f32_e32 v18, 1.0, v18
	v_add_f32_e32 v19, 1.0, v19
	v_lshlrev_b32_e32 v20, 16, v69
	v_and_b32_e32 v21, 0xffff0000, v69
	v_mul_f32_e32 v20, 0xbfb8aa3b, v20
	v_mul_f32_e32 v21, 0xbfb8aa3b, v21
	v_rcp_f32_e32 v18, v18
	v_rcp_f32_e32 v19, v19
	v_exp_f32_e32 v20, v20
	v_exp_f32_e32 v21, v21
	v_lshl_add_u64 v[16:17], s[8:9], 0, v[84:85]
	v_pk_mul_f32 v[12:13], v[12:13], v[18:19]
	v_add_f32_e32 v18, 1.0, v20
	v_add_f32_e32 v19, 1.0, v21
	v_rcp_f32_e32 v18, v18
	v_lshlrev_b32_e32 v20, 16, v70
	v_and_b32_e32 v21, 0xffff0000, v70
	v_rcp_f32_e32 v19, v19
	v_mul_f32_e32 v20, 0xbfb8aa3b, v20
	v_mul_f32_e32 v21, 0xbfb8aa3b, v21
	v_exp_f32_e32 v20, v20
	v_exp_f32_e32 v21, v21
	v_pk_mul_f32 v[14:15], v[14:15], v[18:19]
	v_cvt_pk_bf16_f32 v12, v12, v13
	v_cvt_pk_bf16_f32 v13, v14, v15
	v_lshlrev_b32_e32 v14, 16, v71
	v_add_f32_e32 v20, 1.0, v20
	v_add_f32_e32 v21, 1.0, v21
	v_mul_f32_e32 v14, 0xbfb8aa3b, v14
	v_rcp_f32_e32 v20, v20
	v_rcp_f32_e32 v21, v21
	v_exp_f32_e32 v15, v14
	v_and_b32_e32 v14, 0xffff0000, v71
	v_mul_f32_e32 v14, 0xbfb8aa3b, v14
	v_exp_f32_e32 v18, v14
	v_pk_mul_f32 v[8:9], v[8:9], v[20:21]
	v_lshl_add_u64 v[16:17], v[16:17], 0, v[170:171]
	v_cvt_pk_bf16_f32 v14, v8, v9
	v_add_f32_e32 v8, 1.0, v15
	s_waitcnt vmcnt(3)
	v_lshlrev_b32_e32 v15, 16, v64
	v_add_f32_e32 v9, 1.0, v18
	v_mul_f32_e32 v15, 0xbfb8aa3b, v15
	v_and_b32_e32 v18, 0xffff0000, v64
	v_exp_f32_e32 v15, v15
	v_mul_f32_e32 v18, 0xbfb8aa3b, v18
	v_rcp_f32_e32 v8, v8
	v_exp_f32_e32 v19, v18
	v_rcp_f32_e32 v9, v9
	v_add_f32_e32 v15, 1.0, v15
	v_rcp_f32_e32 v18, v15
	v_add_f32_e32 v15, 1.0, v19
	v_pk_mul_f32 v[8:9], v[10:11], v[8:9]
	v_rcp_f32_e32 v19, v15
	v_cvt_pk_bf16_f32 v15, v8, v9
	v_lshlrev_b32_e32 v8, 16, v65
	v_mul_f32_e32 v8, 0xbfb8aa3b, v8
	v_and_b32_e32 v9, 0xffff0000, v65
	v_exp_f32_e32 v8, v8
	v_mul_f32_e32 v9, 0xbfb8aa3b, v9
	v_exp_f32_e32 v9, v9
	v_pk_mul_f32 v[4:5], v[4:5], v[18:19]
	v_and_b32_e32 v10, 0xffff0000, v66
	v_cvt_pk_bf16_f32 v4, v4, v5
	v_add_f32_e32 v5, 1.0, v8
	v_rcp_f32_e32 v8, v5
	v_add_f32_e32 v5, 1.0, v9
	v_rcp_f32_e32 v9, v5
	v_lshlrev_b32_e32 v5, 16, v66
	v_mul_f32_e32 v5, 0xbfb8aa3b, v5
	v_exp_f32_e32 v5, v5
	v_mul_f32_e32 v10, 0xbfb8aa3b, v10
	v_exp_f32_e32 v10, v10
	v_pk_mul_f32 v[6:7], v[6:7], v[8:9]
	v_lshlrev_b32_e32 v9, 16, v67
	v_add_f32_e32 v5, 1.0, v5
	v_mul_f32_e32 v9, 0xbfb8aa3b, v9
	v_rcp_f32_e32 v8, v5
	v_add_f32_e32 v5, 1.0, v10
	v_exp_f32_e32 v10, v9
	v_and_b32_e32 v9, 0xffff0000, v67
	v_mul_f32_e32 v9, 0xbfb8aa3b, v9
	v_exp_f32_e32 v11, v9
	v_rcp_f32_e32 v9, v5
	v_add_f32_e32 v5, 1.0, v10
	v_rcp_f32_e32 v10, v5
	v_add_f32_e32 v5, 1.0, v11
	v_rcp_f32_e32 v11, v5
	v_pk_mul_f32 v[0:1], v[0:1], v[8:9]
	v_cvt_pk_bf16_f32 v5, v6, v7
	v_cvt_pk_bf16_f32 v6, v0, v1
	v_pk_mul_f32 v[0:1], v[2:3], v[10:11]
	global_store_dwordx4 v[100:101], v[60:63], off
	v_cvt_pk_bf16_f32 v7, v0, v1
	global_store_dwordx4 v[48:49], v[44:47], off
	global_store_dwordx4 v[32:33], v[28:31], off
	global_store_dwordx4 v[16:17], v[12:15], off
	global_store_dwordx4 v[16:17], v[4:7], off offset:64
	s_cbranch_vccnz .LBB0_832
	s_andn2_b64 vcc, exec, s[12:13]
	s_cbranch_vccnz .LBB0_831
	s_barrier
	s_branch .LBB0_831

; #define PG8_STAGE(bufoff, gbase, voff) do { _Pragma("unroll") for (int _i = 0; _i < 2; ++_i) \
;         __builtin_amdgcn_global_load_lds((const unsigned*)((const char*)(gbase) + (voff)[_i]), (PG8_LAS unsigned*)(lds + (bufoff) + ldsw + _i * 8192), 16, 0, 0); } while (0)
; #define PG8_WAIT_V(n) asm volatile("s_waitcnt vmcnt(" #n ")" ::: "memory")
; #define PG8_BAR __builtin_amdgcn_s_barrier()
; template <class Epi, class Sched, bool ALIGN_EPI = false, bool SP2 = false>
; __device__ __forceinline__ void gemm_phase(PG8_LAS unsigned char* lds, const Gemm g, const Sched& S, const Epi& E) {
;     const int tid = threadIdx.x, wid = __builtin_amdgcn_readfirstlane(tid >> 6), lane = tid & 63, wr = wid >> 2, wc = wid & 3, fr = lane & 15, fq = lane >> 4;
;     const int K = g.K, nt = K / BK;
;     unsigned voffA[2], voffB[2];
; #pragma unroll
;     for (int i = 0; i < 2; ++i) { int R, C; stage_rc(tid * 16 + i * 8192, R, C); const int Rb = Epi::PERM ? ((R & ~31) + perm32(R & 31)) : R;
;         voffA[i] = (unsigned)(R * K + C) * 2u; voffB[i] = (unsigned)(Rb * K + C) * 2u; }
;     const size_t kstep = (size_t)(BK * 2);
;     const size_t hstep = (size_t)HALF * K * 2;
;     const size_t tstep = 2 * hstep;
;     const unsigned ldsw = (unsigned)wid * 1024u;
;     const int aoff = lds_byte(wr * 64 + fr, fq * 8), boff = lds_byte(wc * 32 + fr, fq * 8);
;     ...
;         PG8_WAIT_V(2); PG8_BAR;
;         PG8_STAGE(PG8_SB(1, 0), cB + kstep, voffB); PG8_STAGE(PG8_SA(1, 0), cA + kstep, voffA); PG8_STAGE(PG8_SB(1, 1), cB + hstep + kstep, voffB);
;         PG8_WAIT_V(6); PG8_BAR;
.LBB0_854:
	s_add_u32 s12, s94, 0x30d00000
	s_addc_u32 s13, s95, 0
	s_add_u32 s14, s94, 0x4200000
	s_mov_b64 s[16:17], 0x80
	s_addc_u32 s15, s95, 0
	s_lshl_b32 s1, s1, 5
	s_add_i32 m0, s29, 0x18000
	v_lshl_add_u64 v[6:7], v[6:7], 0, s[16:17]
	s_lshl_b32 s20, s5, 13
	s_and_b32 s21, s1, 0x60
	s_waitcnt vmcnt(2)
	s_barrier
	global_load_lds_dwordx4 v[6:7], off
	v_lshl_add_u64 v[4:5], v[4:5], 0, s[16:17]
	s_add_i32 m0, s29, 0x1a000
	s_add_i32 s48, s29, 0x8000
	s_add_i32 s49, s29, 0xa000
	global_load_lds_dwordx4 v[4:5], off
	v_lshl_add_u64 v[0:1], v[0:1], 0, s[16:17]
	s_mov_b32 m0, s48
	s_add_u32 s18, s34, 0x80080
	global_load_lds_dwordx4 v[0:1], off
	v_lshl_add_u64 v[0:1], v[2:3], 0, s[16:17]
	s_mov_b32 m0, s49
	s_addc_u32 s19, s35, 0
	global_load_lds_dwordx4 v[0:1], off
	s_add_i32 m0, s29, 0x1c000
	v_lshl_add_u64 v[0:1], s[18:19], 0, v[138:139]
	global_load_lds_dwordx4 v[0:1], off
	v_lshl_add_u64 v[0:1], s[18:19], 0, v[142:143]
	s_add_i32 m0, s29, 0x1e000
	v_lshlrev_b32_e32 v2, 12, v182
	global_load_lds_dwordx4 v[0:1], off
	v_lshlrev_b32_e32 v1, 2, v185
	v_lshl_or_b32 v0, v185, 6, v186
	v_and_b32_e32 v1, 32, v1
	v_bitop3_b32 v0, v0, s20, v1 bitop3:0xde
	v_lshlrev_b32_e32 v1, 9, v161
	v_and_b32_e32 v1, 0x70000, v1
	v_or3_b32 v1, v180, v1, v2
	v_add_u32_e32 v144, v1, v181
	v_lshlrev_b32_e32 v1, 5, v183
	s_waitcnt vmcnt(6)
	s_cmpk_lt_u32 s3, 0x100
	v_and_b32_e32 v1, 0xf0000, v1
	v_lshl_or_b32 v163, s21, 8, v187
	s_cselect_b64 s[18:19], -1, 0
	v_or3_b32 v1, v180, v1, v2
	s_add_i32 s51, 0, 0x10000
	s_add_i32 s52, 0, 0x14000
	s_sext_i32_i8 s1, s4
	v_lshl_or_b32 v162, s5, 6, v185
	s_ashr_i32 s50, s33, 31
	v_lshl_add_u32 v164, s21, 1, v184
	v_mov_b32_e32 v145, v139
	v_add_u32_e32 v146, v1, v181
	v_mov_b32_e32 v147, v139
	v_mov_b64_e32 v[148:149], 0x400
	v_mov_b64_e32 v[150:151], 0x3ff
	v_add_u32_e32 v165, s51, v163
	v_add_u32_e32 v166, 0x11000, v163
	v_add_u32_e32 v167, 0, v0
	s_barrier
	s_branch .LBB0_857

; #define PG8_STAGE(bufoff, gbase, voff) do { _Pragma("unroll") for (int _i = 0; _i < 2; ++_i) \
;         __builtin_amdgcn_global_load_lds((const unsigned*)((const char*)(gbase) + (voff)[_i]), (PG8_LAS unsigned*)(lds + (bufoff) + ldsw + _i * 8192), 16, 0, 0); } while (0)
; #define PG8_LDA(dst, b, h) do { _Pragma("unroll") for (int m = 0; m < 4; ++m) _Pragma("unroll") for (int k = 0; k < 2; ++k) dst[m][k] = *(const PG8_LAS bf16x8*)(lds + PG8_SA(b, h) + aoff + m * 2048 + k * 1024); } while (0)
; #define PG8_LDB(dst, b, h) do { _Pragma("unroll") for (int n = 0; n < 2; ++n) _Pragma("unroll") for (int k = 0; k < 2; ++k) dst[n][k] = *(const PG8_LAS bf16x8*)(lds + PG8_SB(b, h) + boff + n * 2048 + k * 1024); } while (0)
; #define PG8_MMA(ai, bj, At, Bt) do { __builtin_amdgcn_s_setprio(1); _Pragma("unroll") for (int m = 0; m < 4; ++m) _Pragma("unroll") for (int n = 0; n < 2; ++n) _Pragma("unroll") for (int k = 0; k < 2; ++k) \
;         acc[ai][bj][m][n] = __builtin_amdgcn_mfma_f32_16x16x32_bf16(Bt[n][k], At[m][k], acc[ai][bj][m][n], 0, 0, 0); __builtin_amdgcn_s_setprio(0); } while (0)
; #define PG8_WAIT_V(n) asm volatile("s_waitcnt vmcnt(" #n ")" ::: "memory")
; #define PG8_BAR __builtin_amdgcn_s_barrier()
; template <class Epi, class Sched, bool ALIGN_EPI = false, bool SP2 = false>
; __device__ __forceinline__ void gemm_phase(PG8_LAS unsigned char* lds, const Gemm g, const Sched& S, const Epi& E) {
;     ...
;         for (int t = 0; t < nt; t += 2) {
;             const bool last = (t == nt - 2);
;             const char* a1 = cA + (size_t)(t + 1) * kstep;
;             const char* a2 = last ? nA : cA + (size_t)(t + 2) * kstep; const char* b2 = last ? nB : cB + (size_t)(t + 2) * kstep;
;             const char* a3 = a2 + kstep; const char* b3 = b2 + kstep;
;             if (last && has_next) S.a_ready(nxt);
;             if constexpr (SP2) {
;             PG8_LDB(B0, 0, 0); PG8_LDB(B1, 0, 1); PG8_SCHED; PG8_LDA(At, 0, 0); PG8_STAGE(PG8_SA(1, 1), a1 + hstep, voffA);
;             PG8_WAIT_V(8); PG8_WAIT_L(0); PG8_BAR; PG8_MMA(0, 0, At, B0); PG8_MMA(0, 1, At, B1); PG8_BAR; PG8_SCHED;
;             PG8_LDA(At, 0, 1); PG8_STAGE(PG8_SB(0, 0), b2, voffB); PG8_STAGE(PG8_SB(0, 1), b2 + hstep, voffB); PG8_STAGE(PG8_SA(0, 0), a2, voffA);
;             PG8_WAIT_V(8); PG8_WAIT_L(0); PG8_BAR; PG8_MMA(1, 0, At, B0); PG8_MMA(1, 1, At, B1); PG8_BAR; PG8_SCHED;
.LBB0_864:
	ds_read_b128 v[128:131], v165
	ds_read_b128 v[132:135], v165 offset:1024
	ds_read_b128 v[152:155], v165 offset:2048
	ds_read_b128 v[156:159], v165 offset:3072
	ds_read_b128 v[168:171], v166
	ds_read_b128 v[172:175], v166 offset:1024
	ds_read_b128 v[176:179], v166 offset:2048
	ds_read_b128 v[180:183], v166 offset:3072
	s_add_u32 s34, s30, 0xfff80080
	s_addc_u32 s35, s31, -1
	s_cmp_eq_u32 s56, 28
	s_cselect_b32 s37, s3, s35
	s_cselect_b32 s36, s23, s34
	s_cselect_b32 s35, s21, s55
	s_cselect_b32 s34, s53, s54
	v_lshl_add_u64 v[216:217], s[30:31], 0, v[144:145]
	s_add_i32 m0, s29, 0xc000
	ds_read_b128 v[184:187], v167
	ds_read_b128 v[188:191], v167 offset:1024
	ds_read_b128 v[192:195], v167 offset:2048
	ds_read_b128 v[196:199], v167 offset:3072
	ds_read_b128 v[200:203], v167 offset:4096
	ds_read_b128 v[204:207], v167 offset:5120
	ds_read_b128 v[208:211], v167 offset:6144
	ds_read_b128 v[212:215], v167 offset:7168
	global_load_lds_dwordx4 v[216:217], off
	v_lshl_add_u64 v[216:217], s[30:31], 0, v[146:147]
	s_add_i32 m0, s29, 0xe000
	s_nop 0
	global_load_lds_dwordx4 v[216:217], off
	s_waitcnt vmcnt(8)
	s_waitcnt lgkmcnt(0)
	s_barrier
	s_setprio 1
	s_waitcnt lgkmcnt(0)
	v_mfma_f32_16x16x32_bf16 v[124:127], v[128:131], v[184:187], v[124:127]
	v_mfma_f32_16x16x32_bf16 v[120:123], v[152:155], v[184:187], v[120:123]
	v_mfma_f32_16x16x32_bf16 v[108:111], v[128:131], v[192:195], v[108:111]
	v_mfma_f32_16x16x32_bf16 v[104:107], v[152:155], v[192:195], v[104:107]
	v_mfma_f32_16x16x32_bf16 v[92:95], v[128:131], v[200:203], v[92:95]
	v_mfma_f32_16x16x32_bf16 v[88:91], v[152:155], v[200:203], v[88:91]
	v_mfma_f32_16x16x32_bf16 v[76:79], v[128:131], v[208:211], v[76:79]
	v_mfma_f32_16x16x32_bf16 v[72:75], v[152:155], v[208:211], v[72:75]
	v_mfma_f32_16x16x32_bf16 v[124:127], v[132:135], v[188:191], v[124:127]
	v_mfma_f32_16x16x32_bf16 v[120:123], v[156:159], v[188:191], v[120:123]
	v_mfma_f32_16x16x32_bf16 v[108:111], v[132:135], v[196:199], v[108:111]
	v_mfma_f32_16x16x32_bf16 v[104:107], v[156:159], v[196:199], v[104:107]
	v_mfma_f32_16x16x32_bf16 v[92:95], v[132:135], v[204:207], v[92:95]
	v_mfma_f32_16x16x32_bf16 v[88:91], v[156:159], v[204:207], v[88:91]
	v_mfma_f32_16x16x32_bf16 v[76:79], v[132:135], v[212:215], v[76:79]
	v_mfma_f32_16x16x32_bf16 v[72:75], v[156:159], v[212:215], v[72:75]
	s_setprio 0
	s_setprio 1
	v_mfma_f32_16x16x32_bf16 v[116:119], v[168:171], v[184:187], v[116:119]
	v_mfma_f32_16x16x32_bf16 v[112:115], v[176:179], v[184:187], v[112:115]
	v_mfma_f32_16x16x32_bf16 v[100:103], v[168:171], v[192:195], v[100:103]
	v_mfma_f32_16x16x32_bf16 v[96:99], v[176:179], v[192:195], v[96:99]
	v_mfma_f32_16x16x32_bf16 v[84:87], v[168:171], v[200:203], v[84:87]
	v_mfma_f32_16x16x32_bf16 v[80:83], v[176:179], v[200:203], v[80:83]
	v_mfma_f32_16x16x32_bf16 v[68:71], v[168:171], v[208:211], v[68:71]
	v_mfma_f32_16x16x32_bf16 v[64:67], v[176:179], v[208:211], v[64:67]
	v_mfma_f32_16x16x32_bf16 v[116:119], v[172:175], v[188:191], v[116:119]
	v_mfma_f32_16x16x32_bf16 v[112:115], v[180:183], v[188:191], v[112:115]
	v_mfma_f32_16x16x32_bf16 v[100:103], v[172:175], v[196:199], v[100:103]
	v_mfma_f32_16x16x32_bf16 v[96:99], v[180:183], v[196:199], v[96:99]
	v_mfma_f32_16x16x32_bf16 v[84:87], v[172:175], v[204:207], v[84:87]
	v_mfma_f32_16x16x32_bf16 v[80:83], v[180:183], v[204:207], v[80:83]
	v_mfma_f32_16x16x32_bf16 v[68:71], v[172:175], v[212:215], v[68:71]
	v_mfma_f32_16x16x32_bf16 v[64:67], v[180:183], v[212:215], v[64:67]
	s_setprio 0
	s_barrier
	s_add_i32 s57, s51, s43
	v_lshl_add_u64 v[216:217], s[34:35], 0, v[138:139]
	s_mov_b32 m0, s57
	ds_read_b128 v[184:187], v167 offset:16384
	ds_read_b128 v[188:191], v167 offset:17408
	ds_read_b128 v[192:195], v167 offset:18432
	ds_read_b128 v[196:199], v167 offset:19456
	ds_read_b128 v[200:203], v167 offset:20480
	ds_read_b128 v[204:207], v167 offset:21504
	ds_read_b128 v[208:211], v167 offset:22528
	ds_read_b128 v[212:215], v167 offset:23552
	global_load_lds_dwordx4 v[216:217], off
	s_add_i32 m0, s57, 0x2000
	s_add_u32 s58, s34, 0x80000
	v_lshl_add_u64 v[218:219], s[34:35], 0, v[142:143]
	s_addc_u32 s59, s35, 0
	s_add_i32 s57, s52, s43
	global_load_lds_dwordx4 v[218:219], off
	v_lshl_add_u64 v[220:221], s[58:59], 0, v[138:139]
	s_mov_b32 m0, s57
	v_lshl_add_u64 v[222:223], s[36:37], 0, v[140:141]
	global_load_lds_dwordx4 v[220:221], off
	v_lshl_add_u64 v[220:221], s[58:59], 0, v[142:143]
	s_add_i32 m0, s57, 0x2000
	s_nop 0
	global_load_lds_dwordx4 v[220:221], off
	v_lshl_add_u64 v[220:221], s[36:37], 0, v[136:137]
	s_mov_b32 m0, s29
	s_nop 0
	global_load_lds_dwordx4 v[220:221], off
	s_mov_b32 m0, s44
	s_nop 0
	global_load_lds_dwordx4 v[222:223], off
	s_waitcnt vmcnt(8)
	s_waitcnt lgkmcnt(0)
	s_barrier
; #define PG8_STAGE(bufoff, gbase, voff) do { _Pragma("unroll") for (int _i = 0; _i < 2; ++_i) \
;         __builtin_amdgcn_global_load_lds((const unsigned*)((const char*)(gbase) + (voff)[_i]), (PG8_LAS unsigned*)(lds + (bufoff) + ldsw + _i * 8192), 16, 0, 0); } while (0)
; #define PG8_LDA(dst, b, h) do { _Pragma("unroll") for (int m = 0; m < 4; ++m) _Pragma("unroll") for (int k = 0; k < 2; ++k) dst[m][k] = *(const PG8_LAS bf16x8*)(lds + PG8_SA(b, h) + aoff + m * 2048 + k * 1024); } while (0)
; #define PG8_LDB(dst, b, h) do { _Pragma("unroll") for (int n = 0; n < 2; ++n) _Pragma("unroll") for (int k = 0; k < 2; ++k) dst[n][k] = *(const PG8_LAS bf16x8*)(lds + PG8_SB(b, h) + boff + n * 2048 + k * 1024); } while (0)
; #define PG8_MMA(ai, bj, At, Bt) do { __builtin_amdgcn_s_setprio(1); _Pragma("unroll") for (int m = 0; m < 4; ++m) _Pragma("unroll") for (int n = 0; n < 2; ++n) _Pragma("unroll") for (int k = 0; k < 2; ++k) \
;         acc[ai][bj][m][n] = __builtin_amdgcn_mfma_f32_16x16x32_bf16(Bt[n][k], At[m][k], acc[ai][bj][m][n], 0, 0, 0); __builtin_amdgcn_s_setprio(0); } while (0)
; #define PG8_WAIT_V(n) asm volatile("s_waitcnt vmcnt(" #n ")" ::: "memory")
; #define PG8_WAIT_L(n) asm volatile("s_waitcnt lgkmcnt(" #n ")" ::: "memory")
; #define PG8_BAR __builtin_amdgcn_s_barrier()
; #define PG8_SCHED __builtin_amdgcn_sched_barrier(0)
; template <class Epi, class Sched, bool ALIGN_EPI = false, bool SP2 = false>
; __device__ __forceinline__ void gemm_phase(PG8_LAS unsigned char* lds, const Gemm g, const Sched& S, const Epi& E) {
;     ...
;             PG8_WAIT_V(8); PG8_WAIT_L(0); PG8_BAR; PG8_MMA(1, 0, At, B0); PG8_MMA(1, 1, At, B1); PG8_BAR; PG8_SCHED;
;             PG8_LDB(B0, 1, 0); PG8_LDB(B1, 1, 1); PG8_SCHED; PG8_LDA(At, 1, 0); PG8_STAGE(PG8_SA(0, 1), a2 + hstep, voffA);
;             PG8_WAIT_V(8); PG8_WAIT_L(0); PG8_BAR; PG8_MMA(0, 0, At, B0); PG8_MMA(0, 1, At, B1); PG8_BAR; PG8_SCHED;
;             PG8_LDA(At, 1, 1); PG8_STAGE(PG8_SB(1, 0), b3, voffB); PG8_STAGE(PG8_SB(1, 1), b3 + hstep, voffB); PG8_STAGE(PG8_SA(1, 0), a3, voffA);
;             PG8_WAIT_V(8); PG8_WAIT_L(0); PG8_BAR; PG8_MMA(1, 0, At, B0); PG8_MMA(1, 1, At, B1); PG8_BAR; PG8_SCHED;
	s_setprio 1
	s_waitcnt lgkmcnt(0)
	v_mfma_f32_16x16x32_bf16 v[60:63], v[128:131], v[184:187], v[60:63]
	v_mfma_f32_16x16x32_bf16 v[56:59], v[152:155], v[184:187], v[56:59]
	v_mfma_f32_16x16x32_bf16 v[44:47], v[128:131], v[192:195], v[44:47]
	v_mfma_f32_16x16x32_bf16 v[40:43], v[152:155], v[192:195], v[40:43]
	v_mfma_f32_16x16x32_bf16 v[28:31], v[128:131], v[200:203], v[28:31]
	v_mfma_f32_16x16x32_bf16 v[24:27], v[152:155], v[200:203], v[24:27]
	v_mfma_f32_16x16x32_bf16 v[12:15], v[128:131], v[208:211], v[12:15]
	v_mfma_f32_16x16x32_bf16 v[8:11], v[152:155], v[208:211], v[8:11]
	v_mfma_f32_16x16x32_bf16 v[60:63], v[132:135], v[188:191], v[60:63]
	v_mfma_f32_16x16x32_bf16 v[56:59], v[156:159], v[188:191], v[56:59]
	v_mfma_f32_16x16x32_bf16 v[44:47], v[132:135], v[196:199], v[44:47]
	v_mfma_f32_16x16x32_bf16 v[40:43], v[156:159], v[196:199], v[40:43]
	v_mfma_f32_16x16x32_bf16 v[28:31], v[132:135], v[204:207], v[28:31]
	v_mfma_f32_16x16x32_bf16 v[24:27], v[156:159], v[204:207], v[24:27]
	v_mfma_f32_16x16x32_bf16 v[12:15], v[132:135], v[212:215], v[12:15]
	v_mfma_f32_16x16x32_bf16 v[8:11], v[156:159], v[212:215], v[8:11]
	s_setprio 0
	s_setprio 1
	v_mfma_f32_16x16x32_bf16 v[52:55], v[168:171], v[184:187], v[52:55]
	v_mfma_f32_16x16x32_bf16 v[48:51], v[176:179], v[184:187], v[48:51]
	v_mfma_f32_16x16x32_bf16 v[36:39], v[168:171], v[192:195], v[36:39]
	v_mfma_f32_16x16x32_bf16 v[32:35], v[176:179], v[192:195], v[32:35]
	v_mfma_f32_16x16x32_bf16 v[20:23], v[168:171], v[200:203], v[20:23]
	v_mfma_f32_16x16x32_bf16 v[16:19], v[176:179], v[200:203], v[16:19]
	v_mfma_f32_16x16x32_bf16 v[4:7], v[168:171], v[208:211], v[4:7]
	v_mfma_f32_16x16x32_bf16 v[0:3], v[176:179], v[208:211], v[0:3]
	v_mfma_f32_16x16x32_bf16 v[52:55], v[172:175], v[188:191], v[52:55]
	v_mfma_f32_16x16x32_bf16 v[48:51], v[180:183], v[188:191], v[48:51]
	v_mfma_f32_16x16x32_bf16 v[36:39], v[172:175], v[196:199], v[36:39]
	v_mfma_f32_16x16x32_bf16 v[32:35], v[180:183], v[196:199], v[32:35]
	v_mfma_f32_16x16x32_bf16 v[20:23], v[172:175], v[204:207], v[20:23]
	v_mfma_f32_16x16x32_bf16 v[16:19], v[180:183], v[204:207], v[16:19]
	v_mfma_f32_16x16x32_bf16 v[4:7], v[172:175], v[212:215], v[4:7]
	v_mfma_f32_16x16x32_bf16 v[0:3], v[180:183], v[212:215], v[0:3]
	s_setprio 0
	s_barrier
	s_add_i32 s57, 0, 0x18000
	s_add_i32 s58, 0, 0x1c000
	v_add_u32_e32 v156, s57, v163
	v_add_u32_e32 v180, 0x19000, v163
	ds_read_b128 v[128:131], v156
	ds_read_b128 v[132:135], v156 offset:1024
	ds_read_b128 v[152:155], v156 offset:2048
	ds_read_b128 v[156:159], v156 offset:3072
	ds_read_b128 v[168:171], v180
	ds_read_b128 v[172:175], v180 offset:1024
	ds_read_b128 v[176:179], v180 offset:2048
	ds_read_b128 v[180:183], v180 offset:3072
	s_add_u32 s36, s36, 0x80000
	s_addc_u32 s37, s37, 0
	s_mov_b32 m0, s45
	v_lshl_add_u64 v[224:225], s[36:37], 0, v[136:137]
	ds_read_b128 v[184:187], v167 offset:32768
	ds_read_b128 v[188:191], v167 offset:33792
	ds_read_b128 v[192:195], v167 offset:34816
	ds_read_b128 v[196:199], v167 offset:35840
	ds_read_b128 v[200:203], v167 offset:36864
	ds_read_b128 v[204:207], v167 offset:37888
	ds_read_b128 v[208:211], v167 offset:38912
	ds_read_b128 v[212:215], v167 offset:39936
	global_load_lds_dwordx4 v[224:225], off
	v_lshl_add_u64 v[224:225], s[36:37], 0, v[140:141]
	s_mov_b32 m0, s46
	s_nop 0
	global_load_lds_dwordx4 v[224:225], off
	s_waitcnt vmcnt(8)
	s_waitcnt lgkmcnt(0)
	s_barrier
	s_setprio 1
	s_waitcnt lgkmcnt(0)
	v_mfma_f32_16x16x32_bf16 v[124:127], v[128:131], v[184:187], v[124:127]
	v_mfma_f32_16x16x32_bf16 v[120:123], v[152:155], v[184:187], v[120:123]
	v_mfma_f32_16x16x32_bf16 v[108:111], v[128:131], v[192:195], v[108:111]
	v_mfma_f32_16x16x32_bf16 v[104:107], v[152:155], v[192:195], v[104:107]
	v_mfma_f32_16x16x32_bf16 v[92:95], v[128:131], v[200:203], v[92:95]
	v_mfma_f32_16x16x32_bf16 v[88:91], v[152:155], v[200:203], v[88:91]
	v_mfma_f32_16x16x32_bf16 v[76:79], v[128:131], v[208:211], v[76:79]
	v_mfma_f32_16x16x32_bf16 v[72:75], v[152:155], v[208:211], v[72:75]
	v_mfma_f32_16x16x32_bf16 v[124:127], v[132:135], v[188:191], v[124:127]
	v_mfma_f32_16x16x32_bf16 v[120:123], v[156:159], v[188:191], v[120:123]
	v_mfma_f32_16x16x32_bf16 v[108:111], v[132:135], v[196:199], v[108:111]
	v_mfma_f32_16x16x32_bf16 v[104:107], v[156:159], v[196:199], v[104:107]
	v_mfma_f32_16x16x32_bf16 v[92:95], v[132:135], v[204:207], v[92:95]
	v_mfma_f32_16x16x32_bf16 v[88:91], v[156:159], v[204:207], v[88:91]
	v_mfma_f32_16x16x32_bf16 v[76:79], v[132:135], v[212:215], v[76:79]
	v_mfma_f32_16x16x32_bf16 v[72:75], v[156:159], v[212:215], v[72:75]
	s_setprio 0
	s_setprio 1
	v_mfma_f32_16x16x32_bf16 v[116:119], v[168:171], v[184:187], v[116:119]
	v_mfma_f32_16x16x32_bf16 v[112:115], v[176:179], v[184:187], v[112:115]
	v_mfma_f32_16x16x32_bf16 v[100:103], v[168:171], v[192:195], v[100:103]
	v_mfma_f32_16x16x32_bf16 v[96:99], v[176:179], v[192:195], v[96:99]
	v_mfma_f32_16x16x32_bf16 v[84:87], v[168:171], v[200:203], v[84:87]
	v_mfma_f32_16x16x32_bf16 v[80:83], v[176:179], v[200:203], v[80:83]
	v_mfma_f32_16x16x32_bf16 v[68:71], v[168:171], v[208:211], v[68:71]
	v_mfma_f32_16x16x32_bf16 v[64:67], v[176:179], v[208:211], v[64:67]
	v_mfma_f32_16x16x32_bf16 v[116:119], v[172:175], v[188:191], v[116:119]
	v_mfma_f32_16x16x32_bf16 v[112:115], v[180:183], v[188:191], v[112:115]
	v_mfma_f32_16x16x32_bf16 v[100:103], v[172:175], v[196:199], v[100:103]
	v_mfma_f32_16x16x32_bf16 v[96:99], v[180:183], v[196:199], v[96:99]
	v_mfma_f32_16x16x32_bf16 v[84:87], v[172:175], v[204:207], v[84:87]
	v_mfma_f32_16x16x32_bf16 v[80:83], v[180:183], v[204:207], v[80:83]
	v_mfma_f32_16x16x32_bf16 v[68:71], v[172:175], v[212:215], v[68:71]
	v_mfma_f32_16x16x32_bf16 v[64:67], v[180:183], v[212:215], v[64:67]
	s_setprio 0
	s_barrier
; #define PG8_STAGE(bufoff, gbase, voff) do { _Pragma("unroll") for (int _i = 0; _i < 2; ++_i) \
;         __builtin_amdgcn_global_load_lds((const unsigned*)((const char*)(gbase) + (voff)[_i]), (PG8_LAS unsigned*)(lds + (bufoff) + ldsw + _i * 8192), 16, 0, 0); } while (0)
; #define PG8_LDA(dst, b, h) do { _Pragma("unroll") for (int m = 0; m < 4; ++m) _Pragma("unroll") for (int k = 0; k < 2; ++k) dst[m][k] = *(const PG8_LAS bf16x8*)(lds + PG8_SA(b, h) + aoff + m * 2048 + k * 1024); } while (0)
; #define PG8_MMA(ai, bj, At, Bt) do { __builtin_amdgcn_s_setprio(1); _Pragma("unroll") for (int m = 0; m < 4; ++m) _Pragma("unroll") for (int n = 0; n < 2; ++n) _Pragma("unroll") for (int k = 0; k < 2; ++k) \
;         acc[ai][bj][m][n] = __builtin_amdgcn_mfma_f32_16x16x32_bf16(Bt[n][k], At[m][k], acc[ai][bj][m][n], 0, 0, 0); __builtin_amdgcn_s_setprio(0); } while (0)
; #define PG8_WAIT_V(n) asm volatile("s_waitcnt vmcnt(" #n ")" ::: "memory")
; #define PG8_WAIT_L(n) asm volatile("s_waitcnt lgkmcnt(" #n ")" ::: "memory")
; #define PG8_BAR __builtin_amdgcn_s_barrier()
; template <class Epi, class Sched, bool ALIGN_EPI = false, bool SP2 = false>
; __device__ __forceinline__ void gemm_phase(PG8_LAS unsigned char* lds, const Gemm g, const Sched& S, const Epi& E) {
;     ...
;             PG8_WAIT_V(8); PG8_WAIT_L(0); PG8_BAR; PG8_MMA(0, 0, At, B0); PG8_MMA(0, 1, At, B1); PG8_BAR; PG8_SCHED;
;             PG8_LDA(At, 1, 1); PG8_STAGE(PG8_SB(1, 0), b3, voffB); PG8_STAGE(PG8_SB(1, 1), b3 + hstep, voffB); PG8_STAGE(PG8_SA(1, 0), a3, voffA);
;             PG8_WAIT_V(8); PG8_WAIT_L(0); PG8_BAR; PG8_MMA(1, 0, At, B0); PG8_MMA(1, 1, At, B1); PG8_BAR; PG8_SCHED;
;     __device__ __forceinline__ void operator()(const f32x4 (&acc)[2][2][4][2], const pg8::Unit& u, int wr, int wc, int fr, int fq) const {
;         const int row0 = u.pm * 256 + wr * 64 + fr, col0 = u.pn * 256 + wc * 32 + 8 * fq;
; #pragma unroll
;         for (int ai = 0; ai < 2; ++ai)
; #pragma unroll
;           for (int mp = 0; mp < 2; ++mp) {
;             u32x4 gb[2][2], tb[2][2];
; #pragma unroll
;             for (int mm = 0; mm < 2; ++mm)
; #pragma unroll
;                 for (int bj = 0; bj < 2; ++bj) { const size_t ro = (size_t)(row0 + ai * 128 + (mp * 2 + mm) * 16) * 2048 + col0 + bj * 128; gb[mm][bj] = *(const u32x4*)(G + ro); tb[mm][bj] = *(const u32x4*)(T + ro); }
	s_add_i32 s36, s57, s43
	v_lshl_add_u64 v[216:217], v[216:217], 0, s[16:17]
	s_mov_b32 m0, s36
	ds_read_b128 v[184:187], v167 offset:49152
	ds_read_b128 v[188:191], v167 offset:50176
	ds_read_b128 v[192:195], v167 offset:51200
	ds_read_b128 v[196:199], v167 offset:52224
	ds_read_b128 v[200:203], v167 offset:53248
	ds_read_b128 v[204:207], v167 offset:54272
	ds_read_b128 v[208:211], v167 offset:55296
	ds_read_b128 v[212:215], v167 offset:56320
	global_load_lds_dwordx4 v[216:217], off
	s_add_i32 m0, s36, 0x2000
	s_add_u32 s34, s34, 0x80080
	v_lshl_add_u64 v[216:217], v[218:219], 0, s[16:17]
	s_addc_u32 s35, s35, 0
	s_add_i32 s36, s58, s43
	global_load_lds_dwordx4 v[216:217], off
	v_lshl_add_u64 v[216:217], s[34:35], 0, v[138:139]
	s_mov_b32 m0, s36
	s_nop 0
	global_load_lds_dwordx4 v[216:217], off
	v_lshl_add_u64 v[216:217], s[34:35], 0, v[142:143]
	s_add_i32 m0, s36, 0x2000
	s_nop 0
	global_load_lds_dwordx4 v[216:217], off
	v_lshl_add_u64 v[216:217], v[220:221], 0, s[16:17]
	s_mov_b32 m0, s48
	s_nop 0
	global_load_lds_dwordx4 v[216:217], off
	v_lshl_add_u64 v[216:217], v[222:223], 0, s[16:17]
	s_mov_b32 m0, s49
	s_nop 0
	global_load_lds_dwordx4 v[216:217], off
	s_waitcnt vmcnt(8)
	s_waitcnt lgkmcnt(0)
	s_barrier
	s_setprio 1
	s_waitcnt lgkmcnt(0)
	v_mfma_f32_16x16x32_bf16 v[60:63], v[128:131], v[184:187], v[60:63]
	v_mfma_f32_16x16x32_bf16 v[56:59], v[152:155], v[184:187], v[56:59]
	v_mfma_f32_16x16x32_bf16 v[44:47], v[128:131], v[192:195], v[44:47]
	v_mfma_f32_16x16x32_bf16 v[40:43], v[152:155], v[192:195], v[40:43]
	v_mfma_f32_16x16x32_bf16 v[28:31], v[128:131], v[200:203], v[28:31]
	v_mfma_f32_16x16x32_bf16 v[24:27], v[152:155], v[200:203], v[24:27]
	v_mfma_f32_16x16x32_bf16 v[12:15], v[128:131], v[208:211], v[12:15]
	v_mfma_f32_16x16x32_bf16 v[8:11], v[152:155], v[208:211], v[8:11]
	v_mfma_f32_16x16x32_bf16 v[60:63], v[132:135], v[188:191], v[60:63]
	v_mfma_f32_16x16x32_bf16 v[56:59], v[156:159], v[188:191], v[56:59]
	v_mfma_f32_16x16x32_bf16 v[44:47], v[132:135], v[196:199], v[44:47]
	v_mfma_f32_16x16x32_bf16 v[40:43], v[156:159], v[196:199], v[40:43]
	v_mfma_f32_16x16x32_bf16 v[28:31], v[132:135], v[204:207], v[28:31]
	v_mfma_f32_16x16x32_bf16 v[24:27], v[156:159], v[204:207], v[24:27]
	v_mfma_f32_16x16x32_bf16 v[12:15], v[132:135], v[212:215], v[12:15]
	v_mfma_f32_16x16x32_bf16 v[8:11], v[156:159], v[212:215], v[8:11]
	s_setprio 0
	s_setprio 1
	v_mfma_f32_16x16x32_bf16 v[52:55], v[168:171], v[184:187], v[52:55]
	v_mfma_f32_16x16x32_bf16 v[48:51], v[176:179], v[184:187], v[48:51]
	v_mfma_f32_16x16x32_bf16 v[36:39], v[168:171], v[192:195], v[36:39]
	v_mfma_f32_16x16x32_bf16 v[32:35], v[176:179], v[192:195], v[32:35]
	v_mfma_f32_16x16x32_bf16 v[20:23], v[168:171], v[200:203], v[20:23]
	v_mfma_f32_16x16x32_bf16 v[16:19], v[176:179], v[200:203], v[16:19]
	v_mfma_f32_16x16x32_bf16 v[4:7], v[168:171], v[208:211], v[4:7]
	v_mfma_f32_16x16x32_bf16 v[0:3], v[176:179], v[208:211], v[0:3]
	v_mfma_f32_16x16x32_bf16 v[52:55], v[172:175], v[188:191], v[52:55]
	v_mfma_f32_16x16x32_bf16 v[48:51], v[180:183], v[188:191], v[48:51]
	v_mfma_f32_16x16x32_bf16 v[36:39], v[172:175], v[196:199], v[36:39]
	v_mfma_f32_16x16x32_bf16 v[32:35], v[180:183], v[196:199], v[32:35]
	v_mfma_f32_16x16x32_bf16 v[20:23], v[172:175], v[204:207], v[20:23]
	v_mfma_f32_16x16x32_bf16 v[16:19], v[180:183], v[204:207], v[16:19]
	v_mfma_f32_16x16x32_bf16 v[4:7], v[172:175], v[212:215], v[4:7]
	v_mfma_f32_16x16x32_bf16 v[0:3], v[180:183], v[212:215], v[0:3]
	s_setprio 0
	s_barrier
	s_add_i32 s56, s56, 2
	s_add_u32 s30, s30, 0x100
	s_addc_u32 s31, s31, 0
	s_add_u32 s54, s54, 0x100
	s_addc_u32 s55, s55, 0
	s_cmp_gt_u32 s56, 29
	s_cbranch_scc0 .LBB0_864
	s_and_b64 vcc, exec, s[18:19]
	s_cbranch_vccz .LBB0_867
	s_barrier
.LBB0_867:
	v_lshl_add_u32 v156, s28, 8, v162
	v_lshl_or_b32 v154, s1, 8, v164
	v_ashrrev_i32_e32 v157, 31, v156
	v_ashrrev_i32_e32 v155, 31, v154
	v_lshlrev_b64 v[128:129], 11, v[156:157]
	v_lshl_add_u64 v[128:129], v[128:129], 0, v[154:155]
	v_lshlrev_b64 v[128:129], 1, v[128:129]
	v_lshl_add_u64 v[130:131], s[12:13], 0, v[128:129]
	global_load_dwordx4 v[168:171], v[130:131], off
	v_lshl_add_u64 v[130:131], s[8:9], 0, v[128:129]
	global_load_dwordx4 v[172:175], v[130:131], off
	v_or_b32_e32 v128, 64, v128
	v_lshl_add_u64 v[130:131], s[12:13], 0, v[128:129]
	global_load_dwordx4 v[176:179], v[130:131], off
	v_lshl_add_u64 v[128:129], s[8:9], 0, v[128:129]
	global_load_dwordx4 v[180:183], v[128:129], off
	v_or_b32_e32 v158, 16, v156
	v_ashrrev_i32_e32 v159, 31, v158
	v_lshlrev_b64 v[132:133], 11, v[158:159]
	v_lshlrev_b64 v[130:131], 12, v[156:157]
	v_lshl_add_u64 v[132:133], v[132:133], 0, v[154:155]
	v_lshlrev_b64 v[152:153], 1, v[154:155]
	v_lshl_add_u64 v[130:131], s[14:15], 0, v[130:131]
	v_lshlrev_b64 v[128:129], 1, v[132:133]
	v_lshl_add_u64 v[192:193], v[130:131], 0, v[152:153]
	v_lshl_add_u64 v[130:131], s[12:13], 0, v[128:129]
	v_lshl_add_u64 v[132:133], s[8:9], 0, v[128:129]
	global_load_dwordx4 v[184:187], v[130:131], off
	global_load_dwordx4 v[188:191], v[132:133], off
	v_or_b32_e32 v128, 64, v128
	v_lshl_add_u64 v[130:131], s[12:13], 0, v[128:129]
	v_lshl_add_u64 v[128:129], s[8:9], 0, v[128:129]
	global_load_dwordx4 v[132:135], v[130:131], off
	s_nop 0
	global_load_dwordx4 v[128:131], v[128:129], off
	s_andn2_b64 vcc, exec, s[4:5]
	s_mov_b64 s[4:5], -1
	s_waitcnt vmcnt(0)
; __device__ __forceinline__ unsigned pk2(float lo, float hi) { const f32x2 v = {lo, hi}; const bf16x2_t b = __builtin_convertvector(v, bf16x2_t); return __builtin_bit_cast(unsigned, b); }
; __device__ __forceinline__ float sigmoid_f(float v) { return __builtin_amdgcn_rcpf(1.f + __expf(-v)); }
;     __device__ __forceinline__ void operator()(const f32x4 (&acc)[2][2][4][2], const pg8::Unit& u, int wr, int wc, int fr, int fq) const {
;     ...
;             for (int mm = 0; mm < 2; ++mm) { const int m = mp * 2 + mm; const size_t ro = (size_t)(row0 + ai * 128 + m * 16) * 2048 + col0;
; #pragma unroll
;                 for (int bj = 0; bj < 2; ++bj) { const u32x4 g = gb[mm][bj]; const u32x4 t = tb[mm][bj];
;                     const f32x4 v0 = acc[ai][bj][m][0], v1 = acc[ai][bj][m][1];
;                     u32x4 w; w.x = pk2(bflo(t.x) + sigmoid_f(bflo(g.x)) * v0[0], bfhi(t.x) + sigmoid_f(bfhi(g.x)) * v0[1]);
;                     w.y = pk2(bflo(t.y) + sigmoid_f(bflo(g.y)) * v0[2], bfhi(t.y) + sigmoid_f(bfhi(g.y)) * v0[3]);
;                     w.z = pk2(bflo(t.z) + sigmoid_f(bflo(g.z)) * v1[0], bfhi(t.z) + sigmoid_f(bfhi(g.z)) * v1[1]);
;                     w.w = pk2(bflo(t.w) + sigmoid_f(bflo(g.w)) * v1[2], bfhi(t.w) + sigmoid_f(bfhi(g.w)) * v1[3]);
;                     *(u32x4*)(O + ro + bj * 128) = w; } }
	v_lshlrev_b32_e32 v157, 16, v168
	v_and_b32_e32 v196, 0xffff0000, v168
	v_lshlrev_b32_e32 v194, 16, v172
	v_and_b32_e32 v195, 0xffff0000, v172
	v_lshlrev_b32_e32 v197, 16, v169
	v_and_b32_e32 v198, 0xffff0000, v169
	v_lshlrev_b32_e32 v168, 16, v173
	v_and_b32_e32 v169, 0xffff0000, v173
	v_lshlrev_b32_e32 v199, 16, v170
	v_and_b32_e32 v200, 0xffff0000, v170
	v_lshlrev_b32_e32 v172, 16, v174
	v_and_b32_e32 v173, 0xffff0000, v174
	v_lshlrev_b32_e32 v174, 16, v171
	v_and_b32_e32 v201, 0xffff0000, v171
	v_lshlrev_b32_e32 v170, 16, v175
	v_and_b32_e32 v171, 0xffff0000, v175
	v_mul_f32_e32 v157, 0xbfb8aa3b, v157
	v_mul_f32_e32 v175, 0xbfb8aa3b, v196
	v_mul_f32_e32 v196, 0xbfb8aa3b, v197
	v_mul_f32_e32 v197, 0xbfb8aa3b, v198
	v_mul_f32_e32 v198, 0xbfb8aa3b, v199
	v_mul_f32_e32 v199, 0xbfb8aa3b, v200
	v_mul_f32_e32 v174, 0xbfb8aa3b, v174
	v_mul_f32_e32 v200, 0xbfb8aa3b, v201
	v_exp_f32_e32 v157, v157
	v_exp_f32_e32 v175, v175
	v_exp_f32_e32 v196, v196
	v_exp_f32_e32 v197, v197
	v_exp_f32_e32 v198, v198
	v_exp_f32_e32 v199, v199
	v_exp_f32_e32 v174, v174
	v_exp_f32_e32 v200, v200
	v_lshlrev_b32_e32 v201, 16, v176
	v_mul_f32_e32 v201, 0xbfb8aa3b, v201
	v_exp_f32_e32 v202, v201
	v_add_f32_e32 v157, 1.0, v157
	v_add_f32_e32 v175, 1.0, v175
	v_add_f32_e32 v196, 1.0, v196
	v_add_f32_e32 v197, 1.0, v197
	v_add_f32_e32 v198, 1.0, v198
	v_add_f32_e32 v199, 1.0, v199
	v_add_f32_e32 v201, 1.0, v174
	v_add_f32_e32 v203, 1.0, v200
	v_rcp_f32_e32 v174, v157
	v_rcp_f32_e32 v175, v175
	v_rcp_f32_e32 v196, v196
	v_rcp_f32_e32 v197, v197
	v_rcp_f32_e32 v198, v198
	v_rcp_f32_e32 v199, v199
	v_rcp_f32_e32 v200, v201
	v_rcp_f32_e32 v201, v203
	v_and_b32_e32 v176, 0xffff0000, v176
	v_mul_f32_e32 v176, 0xbfb8aa3b, v176
	v_exp_f32_e32 v176, v176
	v_pk_fma_f32 v[124:125], v[124:125], v[174:175], v[194:195]
	v_pk_fma_f32 v[126:127], v[126:127], v[196:197], v[168:169]
	v_pk_fma_f32 v[168:169], v[120:121], v[198:199], v[172:173]
	v_pk_fma_f32 v[170:171], v[122:123], v[200:201], v[170:171]
	v_cvt_pk_bf16_f32 v120, v124, v125
	v_cvt_pk_bf16_f32 v121, v126, v127
	v_cvt_pk_bf16_f32 v122, v168, v169
	v_cvt_pk_bf16_f32 v123, v170, v171
	global_store_dwordx4 v[192:193], v[120:123], off
	v_add_f32_e32 v157, 1.0, v202
	v_rcp_f32_e32 v202, v157
	v_lshlrev_b32_e32 v122, 16, v177
	v_and_b32_e32 v123, 0xffff0000, v177
	v_add_f32_e32 v120, 1.0, v176
	v_mul_f32_e32 v122, 0xbfb8aa3b, v122
	v_mul_f32_e32 v123, 0xbfb8aa3b, v123
	v_rcp_f32_e32 v203, v120
	v_exp_f32_e32 v122, v122
	v_exp_f32_e32 v123, v123
	v_lshlrev_b32_e32 v120, 16, v180
	v_and_b32_e32 v121, 0xffff0000, v180
	v_pk_fma_f32 v[116:117], v[116:117], v[202:203], v[120:121]
	v_add_f32_e32 v120, 1.0, v122
	v_add_f32_e32 v121, 1.0, v123
	v_rcp_f32_e32 v120, v120
	v_rcp_f32_e32 v121, v121
	v_cvt_pk_bf16_f32 v116, v116, v117
	v_lshlrev_b32_e32 v117, 16, v178
	v_lshlrev_b32_e32 v122, 16, v181
	v_and_b32_e32 v123, 0xffff0000, v181
	v_mul_f32_e32 v117, 0xbfb8aa3b, v117
	v_pk_fma_f32 v[118:119], v[118:119], v[120:121], v[122:123]
	v_exp_f32_e32 v120, v117
	v_and_b32_e32 v117, 0xffff0000, v178
	v_mul_f32_e32 v117, 0xbfb8aa3b, v117
	v_exp_f32_e32 v121, v117
	v_lshlrev_b32_e32 v122, 16, v179
	v_cvt_pk_bf16_f32 v117, v118, v119
	v_add_f32_e32 v118, 1.0, v120
	v_add_f32_e32 v119, 1.0, v121
	v_mul_f32_e32 v122, 0xbfb8aa3b, v122
	v_and_b32_e32 v123, 0xffff0000, v179
	v_rcp_f32_e32 v118, v118
	v_rcp_f32_e32 v119, v119
	v_exp_f32_e32 v122, v122
	v_mul_f32_e32 v123, 0xbfb8aa3b, v123
	v_exp_f32_e32 v123, v123
	v_lshlrev_b32_e32 v120, 16, v182
	v_and_b32_e32 v121, 0xffff0000, v182
	v_pk_fma_f32 v[112:113], v[112:113], v[118:119], v[120:121]
	v_add_f32_e32 v118, 1.0, v122
	v_rcp_f32_e32 v120, v118
	v_add_f32_e32 v118, 1.0, v123
	v_rcp_f32_e32 v121, v118
	v_cvt_pk_bf16_f32 v118, v112, v113
	v_lshlrev_b32_e32 v112, 16, v183
	v_and_b32_e32 v113, 0xffff0000, v183
	v_pk_fma_f32 v[112:113], v[114:115], v[120:121], v[112:113]
	s_nop 0
	v_cvt_pk_bf16_f32 v119, v112, v113
	v_lshlrev_b32_e32 v112, 16, v184
	v_mul_f32_e32 v112, 0xbfb8aa3b, v112
	v_exp_f32_e32 v114, v112
	v_and_b32_e32 v112, 0xffff0000, v184
	v_mul_f32_e32 v112, 0xbfb8aa3b, v112
	v_exp_f32_e32 v115, v112
	global_store_dwordx4 v[192:193], v[116:119], off offset:64
	v_add_f32_e32 v114, 1.0, v114
	v_rcp_f32_e32 v114, v114
	v_lshlrev_b32_e32 v118, 16, v185
	v_and_b32_e32 v119, 0xffff0000, v185
	v_add_f32_e32 v115, 1.0, v115
	v_mul_f32_e32 v118, 0xbfb8aa3b, v118
	v_mul_f32_e32 v119, 0xbfb8aa3b, v119
	v_rcp_f32_e32 v115, v115
	v_exp_f32_e32 v118, v118
	v_exp_f32_e32 v119, v119
	v_lshlrev_b32_e32 v116, 16, v188
	v_and_b32_e32 v117, 0xffff0000, v188
	v_pk_fma_f32 v[108:109], v[108:109], v[114:115], v[116:117]
	v_add_f32_e32 v114, 1.0, v118
	v_add_f32_e32 v115, 1.0, v119
	v_rcp_f32_e32 v114, v114
	v_rcp_f32_e32 v115, v115
	v_cvt_pk_bf16_f32 v108, v108, v109
	v_lshlrev_b32_e32 v109, 16, v186
	v_lshlrev_b32_e32 v116, 16, v189
	v_and_b32_e32 v117, 0xffff0000, v189
	v_mul_f32_e32 v109, 0xbfb8aa3b, v109
	v_pk_fma_f32 v[110:111], v[110:111], v[114:115], v[116:117]
	v_exp_f32_e32 v114, v109
	v_and_b32_e32 v109, 0xffff0000, v186
	v_mul_f32_e32 v109, 0xbfb8aa3b, v109
	v_exp_f32_e32 v115, v109
	v_lshlrev_b32_e32 v116, 16, v187
	v_cvt_pk_bf16_f32 v109, v110, v111
	v_add_f32_e32 v110, 1.0, v114
	v_add_f32_e32 v111, 1.0, v115
	v_mul_f32_e32 v116, 0xbfb8aa3b, v116
	v_and_b32_e32 v117, 0xffff0000, v187
	v_rcp_f32_e32 v110, v110
	v_rcp_f32_e32 v111, v111
	v_exp_f32_e32 v116, v116
	v_mul_f32_e32 v117, 0xbfb8aa3b, v117
	v_exp_f32_e32 v117, v117
	v_lshlrev_b32_e32 v114, 16, v190
	v_and_b32_e32 v115, 0xffff0000, v190
	v_pk_fma_f32 v[104:105], v[104:105], v[110:111], v[114:115]
	v_add_f32_e32 v110, 1.0, v116
; __device__ __forceinline__ unsigned pk2(float lo, float hi) { const f32x2 v = {lo, hi}; const bf16x2_t b = __builtin_convertvector(v, bf16x2_t); return __builtin_bit_cast(unsigned, b); }
; __device__ __forceinline__ float sigmoid_f(float v) { return __builtin_amdgcn_rcpf(1.f + __expf(-v)); }
;     __device__ __forceinline__ void operator()(const f32x4 (&acc)[2][2][4][2], const pg8::Unit& u, int wr, int wc, int fr, int fq) const {
;     ...
;           for (int mp = 0; mp < 2; ++mp) {
;             u32x4 gb[2][2], tb[2][2];
; #pragma unroll
;             for (int mm = 0; mm < 2; ++mm)
; #pragma unroll
;                 for (int bj = 0; bj < 2; ++bj) { const size_t ro = (size_t)(row0 + ai * 128 + (mp * 2 + mm) * 16) * 2048 + col0 + bj * 128; gb[mm][bj] = *(const u32x4*)(G + ro); tb[mm][bj] = *(const u32x4*)(T + ro); }
;             asm volatile("" ::: "memory");
; #pragma unroll
;             for (int mm = 0; mm < 2; ++mm) { const int m = mp * 2 + mm; const size_t ro = (size_t)(row0 + ai * 128 + m * 16) * 2048 + col0;
; #pragma unroll
;                 for (int bj = 0; bj < 2; ++bj) { const u32x4 g = gb[mm][bj]; const u32x4 t = tb[mm][bj];
;                     const f32x4 v0 = acc[ai][bj][m][0], v1 = acc[ai][bj][m][1];
;                     u32x4 w; w.x = pk2(bflo(t.x) + sigmoid_f(bflo(g.x)) * v0[0], bfhi(t.x) + sigmoid_f(bfhi(g.x)) * v0[1]);
;                     w.y = pk2(bflo(t.y) + sigmoid_f(bflo(g.y)) * v0[2], bfhi(t.y) + sigmoid_f(bfhi(g.y)) * v0[3]);
;                     w.z = pk2(bflo(t.z) + sigmoid_f(bflo(g.z)) * v1[0], bfhi(t.z) + sigmoid_f(bfhi(g.z)) * v1[1]);
;                     w.w = pk2(bflo(t.w) + sigmoid_f(bflo(g.w)) * v1[2], bfhi(t.w) + sigmoid_f(bfhi(g.w)) * v1[3]);
;                     *(u32x4*)(O + ro + bj * 128) = w; } }
	v_rcp_f32_e32 v114, v110
	v_add_f32_e32 v110, 1.0, v117
	v_rcp_f32_e32 v115, v110
	v_cvt_pk_bf16_f32 v110, v104, v105
	v_lshlrev_b32_e32 v104, 16, v191
	v_and_b32_e32 v105, 0xffff0000, v191
	v_pk_fma_f32 v[104:105], v[106:107], v[114:115], v[104:105]
	v_lshlrev_b32_e32 v106, 16, v132
	v_and_b32_e32 v107, 0xffff0000, v132
	v_mul_f32_e32 v106, 0xbfb8aa3b, v106
	v_mul_f32_e32 v107, 0xbfb8aa3b, v107
	v_lshlrev_b64 v[112:113], 12, v[158:159]
	v_exp_f32_e32 v106, v106
	v_exp_f32_e32 v107, v107
	v_cvt_pk_bf16_f32 v111, v104, v105
	v_lshl_add_u64 v[104:105], s[14:15], 0, v[112:113]
	v_lshl_add_u64 v[104:105], v[104:105], 0, v[152:153]
	global_store_dwordx4 v[104:105], v[108:111], off
	v_add_f32_e32 v106, 1.0, v106
	v_add_f32_e32 v107, 1.0, v107
	v_lshlrev_b32_e32 v110, 16, v133
	v_and_b32_e32 v111, 0xffff0000, v133
	v_mul_f32_e32 v110, 0xbfb8aa3b, v110
	v_mul_f32_e32 v111, 0xbfb8aa3b, v111
	v_rcp_f32_e32 v106, v106
	v_rcp_f32_e32 v107, v107
	v_exp_f32_e32 v110, v110
	v_exp_f32_e32 v111, v111
	v_lshlrev_b32_e32 v108, 16, v128
	v_and_b32_e32 v109, 0xffff0000, v128
	v_pk_fma_f32 v[100:101], v[100:101], v[106:107], v[108:109]
	v_add_f32_e32 v106, 1.0, v110
	v_add_f32_e32 v107, 1.0, v111
	v_rcp_f32_e32 v106, v106
	v_rcp_f32_e32 v107, v107
	v_cvt_pk_bf16_f32 v100, v100, v101
	v_lshlrev_b32_e32 v101, 16, v134
	v_lshlrev_b32_e32 v108, 16, v129
	v_and_b32_e32 v109, 0xffff0000, v129
	v_mul_f32_e32 v101, 0xbfb8aa3b, v101
	v_pk_fma_f32 v[102:103], v[102:103], v[106:107], v[108:109]
	v_exp_f32_e32 v106, v101
	v_and_b32_e32 v101, 0xffff0000, v134
	v_mul_f32_e32 v101, 0xbfb8aa3b, v101
	v_exp_f32_e32 v107, v101
	v_lshlrev_b32_e32 v108, 16, v135
	v_cvt_pk_bf16_f32 v101, v102, v103
	v_add_f32_e32 v102, 1.0, v106
	v_add_f32_e32 v103, 1.0, v107
	v_mul_f32_e32 v108, 0xbfb8aa3b, v108
	v_and_b32_e32 v109, 0xffff0000, v135
	v_rcp_f32_e32 v102, v102
	v_rcp_f32_e32 v103, v103
	v_exp_f32_e32 v108, v108
	v_mul_f32_e32 v109, 0xbfb8aa3b, v109
	v_exp_f32_e32 v109, v109
	v_lshlrev_b32_e32 v106, 16, v130
	v_and_b32_e32 v107, 0xffff0000, v130
	v_pk_fma_f32 v[96:97], v[96:97], v[102:103], v[106:107]
	v_add_f32_e32 v102, 1.0, v108
	v_rcp_f32_e32 v106, v102
	v_add_f32_e32 v102, 1.0, v109
	v_rcp_f32_e32 v107, v102
	v_cvt_pk_bf16_f32 v102, v96, v97
	v_lshlrev_b32_e32 v96, 16, v131
	v_and_b32_e32 v97, 0xffff0000, v131
	v_or_b32_e32 v128, 32, v156
	v_pk_fma_f32 v[96:97], v[98:99], v[106:107], v[96:97]
	v_ashrrev_i32_e32 v129, 31, v128
	v_cvt_pk_bf16_f32 v103, v96, v97
	v_lshlrev_b64 v[96:97], 11, v[128:129]
	v_lshl_add_u64 v[96:97], v[96:97], 0, v[154:155]
	v_lshlrev_b64 v[96:97], 1, v[96:97]
	global_store_dwordx4 v[104:105], v[100:103], off offset:64
	v_lshl_add_u64 v[98:99], s[12:13], 0, v[96:97]
	global_load_dwordx4 v[112:115], v[98:99], off
	v_lshl_add_u64 v[98:99], s[8:9], 0, v[96:97]
	global_load_dwordx4 v[116:119], v[98:99], off
	v_or_b32_e32 v96, 64, v96
	v_lshl_add_u64 v[98:99], s[12:13], 0, v[96:97]
	global_load_dwordx4 v[120:123], v[98:99], off
	v_lshl_add_u64 v[96:97], s[8:9], 0, v[96:97]
	global_load_dwordx4 v[124:127], v[96:97], off
	v_or_b32_e32 v130, 48, v156
	v_ashrrev_i32_e32 v131, 31, v130
	v_lshlrev_b64 v[96:97], 11, v[130:131]
	v_lshl_add_u64 v[96:97], v[96:97], 0, v[154:155]
	v_lshlrev_b64 v[96:97], 1, v[96:97]
	v_lshl_add_u64 v[98:99], s[12:13], 0, v[96:97]
	v_lshl_add_u64 v[100:101], s[8:9], 0, v[96:97]
	global_load_dwordx4 v[108:111], v[98:99], off
	global_load_dwordx4 v[104:107], v[100:101], off
	v_or_b32_e32 v96, 64, v96
	v_lshl_add_u64 v[98:99], s[12:13], 0, v[96:97]
	v_lshl_add_u64 v[96:97], s[8:9], 0, v[96:97]
	global_load_dwordx4 v[100:103], v[98:99], off
	s_nop 0
	global_load_dwordx4 v[96:99], v[96:97], off
	v_lshlrev_b64 v[128:129], 12, v[128:129]
	s_waitcnt vmcnt(7)
	v_lshlrev_b32_e32 v132, 16, v112
	v_and_b32_e32 v112, 0xffff0000, v112
	v_mul_f32_e32 v112, 0xbfb8aa3b, v112
	v_exp_f32_e32 v112, v112
	v_mul_f32_e32 v132, 0xbfb8aa3b, v132
	v_exp_f32_e32 v132, v132
	s_waitcnt vmcnt(6)
	v_lshlrev_b32_e32 v134, 16, v116
	v_add_f32_e32 v112, 1.0, v112
	v_rcp_f32_e32 v133, v112
	v_lshlrev_b32_e32 v112, 16, v113
	v_and_b32_e32 v113, 0xffff0000, v113
	v_mul_f32_e32 v112, 0xbfb8aa3b, v112
	v_mul_f32_e32 v113, 0xbfb8aa3b, v113
	v_exp_f32_e32 v112, v112
	v_exp_f32_e32 v113, v113
	v_add_f32_e32 v132, 1.0, v132
	v_rcp_f32_e32 v132, v132
	v_add_f32_e32 v112, 1.0, v112
	v_add_f32_e32 v113, 1.0, v113
	v_and_b32_e32 v135, 0xffff0000, v116
	v_rcp_f32_e32 v112, v112
	v_rcp_f32_e32 v113, v113
	v_pk_fma_f32 v[92:93], v[92:93], v[132:133], v[134:135]
	v_lshlrev_b32_e32 v116, 16, v117
	v_cvt_pk_bf16_f32 v92, v92, v93
	v_lshlrev_b32_e32 v93, 16, v114
	v_and_b32_e32 v117, 0xffff0000, v117
	v_mul_f32_e32 v93, 0xbfb8aa3b, v93
	v_pk_fma_f32 v[94:95], v[94:95], v[112:113], v[116:117]
	v_exp_f32_e32 v112, v93
	v_and_b32_e32 v93, 0xffff0000, v114
	v_mul_f32_e32 v93, 0xbfb8aa3b, v93
	v_exp_f32_e32 v113, v93
	v_lshlrev_b32_e32 v114, 16, v115
	v_cvt_pk_bf16_f32 v93, v94, v95
	v_add_f32_e32 v94, 1.0, v112
	v_add_f32_e32 v95, 1.0, v113
	v_mul_f32_e32 v114, 0xbfb8aa3b, v114
	v_and_b32_e32 v115, 0xffff0000, v115
	v_rcp_f32_e32 v94, v94
	v_rcp_f32_e32 v95, v95
	v_exp_f32_e32 v114, v114
	v_mul_f32_e32 v115, 0xbfb8aa3b, v115
	v_exp_f32_e32 v115, v115
	v_lshlrev_b32_e32 v112, 16, v118
	v_and_b32_e32 v113, 0xffff0000, v118
	v_pk_fma_f32 v[88:89], v[88:89], v[94:95], v[112:113]
	v_add_f32_e32 v94, 1.0, v114
	v_rcp_f32_e32 v112, v94
	v_add_f32_e32 v94, 1.0, v115
	v_rcp_f32_e32 v113, v94
	v_cvt_pk_bf16_f32 v94, v88, v89
	v_lshlrev_b32_e32 v88, 16, v119
	v_and_b32_e32 v89, 0xffff0000, v119
	v_pk_fma_f32 v[88:89], v[90:91], v[112:113], v[88:89]
	s_waitcnt vmcnt(5)
; __device__ __forceinline__ unsigned pk2(float lo, float hi) { const f32x2 v = {lo, hi}; const bf16x2_t b = __builtin_convertvector(v, bf16x2_t); return __builtin_bit_cast(unsigned, b); }
; __device__ __forceinline__ float sigmoid_f(float v) { return __builtin_amdgcn_rcpf(1.f + __expf(-v)); }
;     __device__ __forceinline__ void operator()(const f32x4 (&acc)[2][2][4][2], const pg8::Unit& u, int wr, int wc, int fr, int fq) const {
;     ...
;             for (int mm = 0; mm < 2; ++mm) { const int m = mp * 2 + mm; const size_t ro = (size_t)(row0 + ai * 128 + m * 16) * 2048 + col0;
; #pragma unroll
;                 for (int bj = 0; bj < 2; ++bj) { const u32x4 g = gb[mm][bj]; const u32x4 t = tb[mm][bj];
;                     const f32x4 v0 = acc[ai][bj][m][0], v1 = acc[ai][bj][m][1];
;                     u32x4 w; w.x = pk2(bflo(t.x) + sigmoid_f(bflo(g.x)) * v0[0], bfhi(t.x) + sigmoid_f(bfhi(g.x)) * v0[1]);
;                     w.y = pk2(bflo(t.y) + sigmoid_f(bflo(g.y)) * v0[2], bfhi(t.y) + sigmoid_f(bfhi(g.y)) * v0[3]);
;                     w.z = pk2(bflo(t.z) + sigmoid_f(bflo(g.z)) * v1[0], bfhi(t.z) + sigmoid_f(bfhi(g.z)) * v1[1]);
;                     w.w = pk2(bflo(t.w) + sigmoid_f(bflo(g.w)) * v1[2], bfhi(t.w) + sigmoid_f(bfhi(g.w)) * v1[3]);
;                     *(u32x4*)(O + ro + bj * 128) = w; } }
	v_lshlrev_b32_e32 v90, 16, v120
	v_and_b32_e32 v91, 0xffff0000, v120
	v_mul_f32_e32 v90, 0xbfb8aa3b, v90
	v_mul_f32_e32 v91, 0xbfb8aa3b, v91
	v_exp_f32_e32 v90, v90
	v_exp_f32_e32 v91, v91
	v_cvt_pk_bf16_f32 v95, v88, v89
	v_lshl_add_u64 v[88:89], s[14:15], 0, v[128:129]
	v_lshl_add_u64 v[88:89], v[88:89], 0, v[152:153]
	global_store_dwordx4 v[88:89], v[92:95], off
	v_add_f32_e32 v90, 1.0, v90
	v_add_f32_e32 v91, 1.0, v91
	v_lshlrev_b32_e32 v94, 16, v121
	v_and_b32_e32 v95, 0xffff0000, v121
	v_mul_f32_e32 v94, 0xbfb8aa3b, v94
	v_mul_f32_e32 v95, 0xbfb8aa3b, v95
	v_rcp_f32_e32 v90, v90
	v_rcp_f32_e32 v91, v91
	v_exp_f32_e32 v94, v94
	v_exp_f32_e32 v95, v95
	s_waitcnt vmcnt(5)
	v_lshlrev_b32_e32 v92, 16, v124
	v_and_b32_e32 v93, 0xffff0000, v124
	v_pk_fma_f32 v[84:85], v[84:85], v[90:91], v[92:93]
	v_add_f32_e32 v90, 1.0, v94
	v_add_f32_e32 v91, 1.0, v95
	v_rcp_f32_e32 v90, v90
	v_rcp_f32_e32 v91, v91
	v_cvt_pk_bf16_f32 v84, v84, v85
	v_lshlrev_b32_e32 v85, 16, v122
	v_lshlrev_b32_e32 v92, 16, v125
	v_and_b32_e32 v93, 0xffff0000, v125
	v_mul_f32_e32 v85, 0xbfb8aa3b, v85
	v_pk_fma_f32 v[86:87], v[86:87], v[90:91], v[92:93]
	v_exp_f32_e32 v90, v85
	v_and_b32_e32 v85, 0xffff0000, v122
	v_mul_f32_e32 v85, 0xbfb8aa3b, v85
	v_exp_f32_e32 v91, v85
	v_lshlrev_b32_e32 v92, 16, v123
	v_cvt_pk_bf16_f32 v85, v86, v87
	v_add_f32_e32 v86, 1.0, v90
	v_add_f32_e32 v87, 1.0, v91
	v_mul_f32_e32 v92, 0xbfb8aa3b, v92
	v_and_b32_e32 v93, 0xffff0000, v123
	v_rcp_f32_e32 v86, v86
	v_rcp_f32_e32 v87, v87
	v_exp_f32_e32 v92, v92
	v_mul_f32_e32 v93, 0xbfb8aa3b, v93
	v_exp_f32_e32 v93, v93
	v_lshlrev_b32_e32 v90, 16, v126
	v_and_b32_e32 v91, 0xffff0000, v126
	v_pk_fma_f32 v[80:81], v[80:81], v[86:87], v[90:91]
	v_add_f32_e32 v86, 1.0, v92
	v_rcp_f32_e32 v90, v86
	v_add_f32_e32 v86, 1.0, v93
	v_rcp_f32_e32 v91, v86
	v_cvt_pk_bf16_f32 v86, v80, v81
	v_lshlrev_b32_e32 v80, 16, v127
	v_and_b32_e32 v81, 0xffff0000, v127
	v_pk_fma_f32 v[80:81], v[82:83], v[90:91], v[80:81]
	s_nop 0
	v_cvt_pk_bf16_f32 v87, v80, v81
	s_waitcnt vmcnt(4)
	v_lshlrev_b32_e32 v80, 16, v108
	v_mul_f32_e32 v80, 0xbfb8aa3b, v80
	v_exp_f32_e32 v82, v80
	v_and_b32_e32 v80, 0xffff0000, v108
	v_mul_f32_e32 v80, 0xbfb8aa3b, v80
	v_exp_f32_e32 v83, v80
	global_store_dwordx4 v[88:89], v[84:87], off offset:64
	v_add_f32_e32 v82, 1.0, v82
	v_rcp_f32_e32 v82, v82
	v_lshlrev_b32_e32 v86, 16, v109
	v_and_b32_e32 v87, 0xffff0000, v109
	v_add_f32_e32 v83, 1.0, v83
	v_mul_f32_e32 v86, 0xbfb8aa3b, v86
	v_mul_f32_e32 v87, 0xbfb8aa3b, v87
	v_rcp_f32_e32 v83, v83
	v_exp_f32_e32 v86, v86
	v_exp_f32_e32 v87, v87
	s_waitcnt vmcnt(4)
	v_lshlrev_b32_e32 v84, 16, v104
	v_and_b32_e32 v85, 0xffff0000, v104
	v_pk_fma_f32 v[76:77], v[76:77], v[82:83], v[84:85]
	v_add_f32_e32 v82, 1.0, v86
	v_add_f32_e32 v83, 1.0, v87
	v_rcp_f32_e32 v82, v82
	v_rcp_f32_e32 v83, v83
	v_cvt_pk_bf16_f32 v76, v76, v77
	v_lshlrev_b32_e32 v77, 16, v110
	v_lshlrev_b32_e32 v84, 16, v105
	v_and_b32_e32 v85, 0xffff0000, v105
	v_mul_f32_e32 v77, 0xbfb8aa3b, v77
	v_pk_fma_f32 v[78:79], v[78:79], v[82:83], v[84:85]
	v_exp_f32_e32 v82, v77
	v_and_b32_e32 v77, 0xffff0000, v110
	v_mul_f32_e32 v77, 0xbfb8aa3b, v77
	v_exp_f32_e32 v83, v77
	v_lshlrev_b32_e32 v84, 16, v111
	v_cvt_pk_bf16_f32 v77, v78, v79
	v_add_f32_e32 v78, 1.0, v82
	v_add_f32_e32 v79, 1.0, v83
	v_mul_f32_e32 v84, 0xbfb8aa3b, v84
	v_and_b32_e32 v85, 0xffff0000, v111
	v_rcp_f32_e32 v78, v78
	v_rcp_f32_e32 v79, v79
	v_exp_f32_e32 v84, v84
	v_mul_f32_e32 v85, 0xbfb8aa3b, v85
	v_exp_f32_e32 v85, v85
	v_lshlrev_b32_e32 v82, 16, v106
	v_and_b32_e32 v83, 0xffff0000, v106
	v_pk_fma_f32 v[72:73], v[72:73], v[78:79], v[82:83]
	v_add_f32_e32 v78, 1.0, v84
	v_rcp_f32_e32 v82, v78
	v_add_f32_e32 v78, 1.0, v85
	v_rcp_f32_e32 v83, v78
	v_cvt_pk_bf16_f32 v78, v72, v73
	v_lshlrev_b32_e32 v72, 16, v107
	v_and_b32_e32 v73, 0xffff0000, v107
	v_pk_fma_f32 v[72:73], v[74:75], v[82:83], v[72:73]
	s_waitcnt vmcnt(3)
	v_lshlrev_b32_e32 v74, 16, v100
	v_and_b32_e32 v75, 0xffff0000, v100
	v_mul_f32_e32 v74, 0xbfb8aa3b, v74
	v_mul_f32_e32 v75, 0xbfb8aa3b, v75
	v_lshlrev_b64 v[80:81], 12, v[130:131]
	v_exp_f32_e32 v74, v74
	v_exp_f32_e32 v75, v75
	v_cvt_pk_bf16_f32 v79, v72, v73
	v_lshl_add_u64 v[72:73], s[14:15], 0, v[80:81]
	v_lshl_add_u64 v[72:73], v[72:73], 0, v[152:153]
	global_store_dwordx4 v[72:73], v[76:79], off
	v_add_f32_e32 v74, 1.0, v74
	v_add_f32_e32 v75, 1.0, v75
	v_lshlrev_b32_e32 v78, 16, v101
	v_and_b32_e32 v79, 0xffff0000, v101
	v_mul_f32_e32 v78, 0xbfb8aa3b, v78
	v_mul_f32_e32 v79, 0xbfb8aa3b, v79
	v_rcp_f32_e32 v74, v74
	v_rcp_f32_e32 v75, v75
	v_exp_f32_e32 v78, v78
	v_exp_f32_e32 v79, v79
	s_waitcnt vmcnt(3)
; __device__ __forceinline__ unsigned pk2(float lo, float hi) { const f32x2 v = {lo, hi}; const bf16x2_t b = __builtin_convertvector(v, bf16x2_t); return __builtin_bit_cast(unsigned, b); }
; __device__ __forceinline__ float sigmoid_f(float v) { return __builtin_amdgcn_rcpf(1.f + __expf(-v)); }
;     __device__ __forceinline__ void operator()(const f32x4 (&acc)[2][2][4][2], const pg8::Unit& u, int wr, int wc, int fr, int fq) const {
;     ...
;           for (int mp = 0; mp < 2; ++mp) {
;             u32x4 gb[2][2], tb[2][2];
; #pragma unroll
;             for (int mm = 0; mm < 2; ++mm)
; #pragma unroll
;                 for (int bj = 0; bj < 2; ++bj) { const size_t ro = (size_t)(row0 + ai * 128 + (mp * 2 + mm) * 16) * 2048 + col0 + bj * 128; gb[mm][bj] = *(const u32x4*)(G + ro); tb[mm][bj] = *(const u32x4*)(T + ro); }
;             asm volatile("" ::: "memory");
; #pragma unroll
;             for (int mm = 0; mm < 2; ++mm) { const int m = mp * 2 + mm; const size_t ro = (size_t)(row0 + ai * 128 + m * 16) * 2048 + col0;
; #pragma unroll
;                 for (int bj = 0; bj < 2; ++bj) { const u32x4 g = gb[mm][bj]; const u32x4 t = tb[mm][bj];
;                     const f32x4 v0 = acc[ai][bj][m][0], v1 = acc[ai][bj][m][1];
;                     u32x4 w; w.x = pk2(bflo(t.x) + sigmoid_f(bflo(g.x)) * v0[0], bfhi(t.x) + sigmoid_f(bfhi(g.x)) * v0[1]);
;                     w.y = pk2(bflo(t.y) + sigmoid_f(bflo(g.y)) * v0[2], bfhi(t.y) + sigmoid_f(bfhi(g.y)) * v0[3]);
;                     w.z = pk2(bflo(t.z) + sigmoid_f(bflo(g.z)) * v1[0], bfhi(t.z) + sigmoid_f(bfhi(g.z)) * v1[1]);
;                     w.w = pk2(bflo(t.w) + sigmoid_f(bflo(g.w)) * v1[2], bfhi(t.w) + sigmoid_f(bfhi(g.w)) * v1[3]);
;                     *(u32x4*)(O + ro + bj * 128) = w; } }
	v_lshlrev_b32_e32 v76, 16, v96
	v_and_b32_e32 v77, 0xffff0000, v96
	v_pk_fma_f32 v[68:69], v[68:69], v[74:75], v[76:77]
	v_add_f32_e32 v74, 1.0, v78
	v_add_f32_e32 v75, 1.0, v79
	v_rcp_f32_e32 v74, v74
	v_rcp_f32_e32 v75, v75
	v_cvt_pk_bf16_f32 v68, v68, v69
	v_lshlrev_b32_e32 v69, 16, v102
	v_lshlrev_b32_e32 v76, 16, v97
	v_and_b32_e32 v77, 0xffff0000, v97
	v_mul_f32_e32 v69, 0xbfb8aa3b, v69
	v_pk_fma_f32 v[70:71], v[70:71], v[74:75], v[76:77]
	v_exp_f32_e32 v74, v69
	v_and_b32_e32 v69, 0xffff0000, v102
	v_mul_f32_e32 v69, 0xbfb8aa3b, v69
	v_exp_f32_e32 v75, v69
	v_lshlrev_b32_e32 v76, 16, v103
	v_cvt_pk_bf16_f32 v69, v70, v71
	v_add_f32_e32 v70, 1.0, v74
	v_add_f32_e32 v71, 1.0, v75
	v_mul_f32_e32 v76, 0xbfb8aa3b, v76
	v_and_b32_e32 v77, 0xffff0000, v103
	v_rcp_f32_e32 v70, v70
	v_rcp_f32_e32 v71, v71
	v_exp_f32_e32 v76, v76
	v_mul_f32_e32 v77, 0xbfb8aa3b, v77
	v_exp_f32_e32 v77, v77
	v_lshlrev_b32_e32 v74, 16, v98
	v_and_b32_e32 v75, 0xffff0000, v98
	v_pk_fma_f32 v[64:65], v[64:65], v[70:71], v[74:75]
	v_add_f32_e32 v70, 1.0, v76
	v_rcp_f32_e32 v74, v70
	v_add_f32_e32 v70, 1.0, v77
	v_rcp_f32_e32 v75, v70
	v_cvt_pk_bf16_f32 v70, v64, v65
	v_lshlrev_b32_e32 v64, 16, v99
	v_and_b32_e32 v65, 0xffff0000, v99
	v_add_u32_e32 v96, 0x80, v156
	v_pk_fma_f32 v[64:65], v[66:67], v[74:75], v[64:65]
	v_ashrrev_i32_e32 v97, 31, v96
	v_cvt_pk_bf16_f32 v71, v64, v65
	v_lshlrev_b64 v[64:65], 11, v[96:97]
	v_lshl_add_u64 v[64:65], v[64:65], 0, v[154:155]
	v_lshlrev_b64 v[64:65], 1, v[64:65]
	global_store_dwordx4 v[72:73], v[68:71], off offset:64
	v_lshl_add_u64 v[66:67], s[12:13], 0, v[64:65]
	global_load_dwordx4 v[80:83], v[66:67], off
	v_lshl_add_u64 v[66:67], s[8:9], 0, v[64:65]
	global_load_dwordx4 v[84:87], v[66:67], off
	v_or_b32_e32 v64, 64, v64
	v_lshl_add_u64 v[66:67], s[12:13], 0, v[64:65]
	global_load_dwordx4 v[88:91], v[66:67], off
	v_lshl_add_u64 v[64:65], s[8:9], 0, v[64:65]
	global_load_dwordx4 v[92:95], v[64:65], off
	v_add_u32_e32 v98, 0x90, v156
	v_ashrrev_i32_e32 v99, 31, v98
	v_lshlrev_b64 v[64:65], 11, v[98:99]
	v_lshl_add_u64 v[64:65], v[64:65], 0, v[154:155]
	v_lshlrev_b64 v[64:65], 1, v[64:65]
	v_lshl_add_u64 v[66:67], s[12:13], 0, v[64:65]
	v_lshl_add_u64 v[68:69], s[8:9], 0, v[64:65]
	global_load_dwordx4 v[76:79], v[66:67], off
	global_load_dwordx4 v[72:75], v[68:69], off
	v_or_b32_e32 v64, 64, v64
	v_lshl_add_u64 v[66:67], s[12:13], 0, v[64:65]
	v_lshl_add_u64 v[64:65], s[8:9], 0, v[64:65]
	global_load_dwordx4 v[68:71], v[66:67], off
	s_nop 0
	global_load_dwordx4 v[64:67], v[64:65], off
	v_lshlrev_b64 v[96:97], 12, v[96:97]
	s_waitcnt vmcnt(7)
	v_lshlrev_b32_e32 v100, 16, v80
	v_and_b32_e32 v80, 0xffff0000, v80
	v_mul_f32_e32 v80, 0xbfb8aa3b, v80
	v_exp_f32_e32 v80, v80
	v_mul_f32_e32 v100, 0xbfb8aa3b, v100
	v_exp_f32_e32 v100, v100
	s_waitcnt vmcnt(6)
	v_lshlrev_b32_e32 v102, 16, v84
	v_add_f32_e32 v80, 1.0, v80
	v_rcp_f32_e32 v101, v80
	v_lshlrev_b32_e32 v80, 16, v81
	v_and_b32_e32 v81, 0xffff0000, v81
	v_mul_f32_e32 v80, 0xbfb8aa3b, v80
	v_mul_f32_e32 v81, 0xbfb8aa3b, v81
	v_exp_f32_e32 v80, v80
	v_exp_f32_e32 v81, v81
	v_add_f32_e32 v100, 1.0, v100
	v_rcp_f32_e32 v100, v100
	v_add_f32_e32 v80, 1.0, v80
	v_add_f32_e32 v81, 1.0, v81
	v_and_b32_e32 v103, 0xffff0000, v84
	v_rcp_f32_e32 v80, v80
	v_rcp_f32_e32 v81, v81
	v_pk_fma_f32 v[60:61], v[60:61], v[100:101], v[102:103]
	v_lshlrev_b32_e32 v84, 16, v85
	v_cvt_pk_bf16_f32 v60, v60, v61
	v_lshlrev_b32_e32 v61, 16, v82
	v_and_b32_e32 v85, 0xffff0000, v85
	v_mul_f32_e32 v61, 0xbfb8aa3b, v61
	v_pk_fma_f32 v[62:63], v[62:63], v[80:81], v[84:85]
	v_exp_f32_e32 v80, v61
	v_and_b32_e32 v61, 0xffff0000, v82
	v_mul_f32_e32 v61, 0xbfb8aa3b, v61
	v_exp_f32_e32 v81, v61
	v_lshlrev_b32_e32 v82, 16, v83
	v_cvt_pk_bf16_f32 v61, v62, v63
	v_add_f32_e32 v62, 1.0, v80
	v_add_f32_e32 v63, 1.0, v81
	v_mul_f32_e32 v82, 0xbfb8aa3b, v82
	v_and_b32_e32 v83, 0xffff0000, v83
	v_rcp_f32_e32 v62, v62
	v_rcp_f32_e32 v63, v63
	v_exp_f32_e32 v82, v82
	v_mul_f32_e32 v83, 0xbfb8aa3b, v83
	v_exp_f32_e32 v83, v83
	v_lshlrev_b32_e32 v80, 16, v86
	v_and_b32_e32 v81, 0xffff0000, v86
	v_pk_fma_f32 v[56:57], v[56:57], v[62:63], v[80:81]
	v_add_f32_e32 v62, 1.0, v82
	v_rcp_f32_e32 v80, v62
	v_add_f32_e32 v62, 1.0, v83
	v_rcp_f32_e32 v81, v62
	v_cvt_pk_bf16_f32 v62, v56, v57
	v_lshlrev_b32_e32 v56, 16, v87
	v_and_b32_e32 v57, 0xffff0000, v87
	v_pk_fma_f32 v[56:57], v[58:59], v[80:81], v[56:57]
	s_waitcnt vmcnt(5)
	v_lshlrev_b32_e32 v58, 16, v88
	v_and_b32_e32 v59, 0xffff0000, v88
	v_mul_f32_e32 v58, 0xbfb8aa3b, v58
	v_mul_f32_e32 v59, 0xbfb8aa3b, v59
	v_exp_f32_e32 v58, v58
	v_exp_f32_e32 v59, v59
	v_cvt_pk_bf16_f32 v63, v56, v57
	v_lshl_add_u64 v[56:57], s[14:15], 0, v[96:97]
	v_lshl_add_u64 v[56:57], v[56:57], 0, v[152:153]
	global_store_dwordx4 v[56:57], v[60:63], off
	v_add_f32_e32 v58, 1.0, v58
	v_add_f32_e32 v59, 1.0, v59
	v_lshlrev_b32_e32 v62, 16, v89
	v_and_b32_e32 v63, 0xffff0000, v89
	v_mul_f32_e32 v62, 0xbfb8aa3b, v62
	v_mul_f32_e32 v63, 0xbfb8aa3b, v63
	v_rcp_f32_e32 v58, v58
	v_rcp_f32_e32 v59, v59
	v_exp_f32_e32 v62, v62
	v_exp_f32_e32 v63, v63
	s_waitcnt vmcnt(5)
; __device__ __forceinline__ unsigned pk2(float lo, float hi) { const f32x2 v = {lo, hi}; const bf16x2_t b = __builtin_convertvector(v, bf16x2_t); return __builtin_bit_cast(unsigned, b); }
; __device__ __forceinline__ float sigmoid_f(float v) { return __builtin_amdgcn_rcpf(1.f + __expf(-v)); }
;     __device__ __forceinline__ void operator()(const f32x4 (&acc)[2][2][4][2], const pg8::Unit& u, int wr, int wc, int fr, int fq) const {
;     ...
;           for (int mp = 0; mp < 2; ++mp) {
;             u32x4 gb[2][2], tb[2][2];
; #pragma unroll
;             for (int mm = 0; mm < 2; ++mm)
; #pragma unroll
;                 for (int bj = 0; bj < 2; ++bj) { const size_t ro = (size_t)(row0 + ai * 128 + (mp * 2 + mm) * 16) * 2048 + col0 + bj * 128; gb[mm][bj] = *(const u32x4*)(G + ro); tb[mm][bj] = *(const u32x4*)(T + ro); }
;             asm volatile("" ::: "memory");
; #pragma unroll
;             for (int mm = 0; mm < 2; ++mm) { const int m = mp * 2 + mm; const size_t ro = (size_t)(row0 + ai * 128 + m * 16) * 2048 + col0;
; #pragma unroll
;                 for (int bj = 0; bj < 2; ++bj) { const u32x4 g = gb[mm][bj]; const u32x4 t = tb[mm][bj];
;                     const f32x4 v0 = acc[ai][bj][m][0], v1 = acc[ai][bj][m][1];
;                     u32x4 w; w.x = pk2(bflo(t.x) + sigmoid_f(bflo(g.x)) * v0[0], bfhi(t.x) + sigmoid_f(bfhi(g.x)) * v0[1]);
;                     w.y = pk2(bflo(t.y) + sigmoid_f(bflo(g.y)) * v0[2], bfhi(t.y) + sigmoid_f(bfhi(g.y)) * v0[3]);
;                     w.z = pk2(bflo(t.z) + sigmoid_f(bflo(g.z)) * v1[0], bfhi(t.z) + sigmoid_f(bfhi(g.z)) * v1[1]);
;                     w.w = pk2(bflo(t.w) + sigmoid_f(bflo(g.w)) * v1[2], bfhi(t.w) + sigmoid_f(bfhi(g.w)) * v1[3]);
;                     *(u32x4*)(O + ro + bj * 128) = w; } }
	v_lshlrev_b32_e32 v60, 16, v92
	v_and_b32_e32 v61, 0xffff0000, v92
	v_pk_fma_f32 v[52:53], v[52:53], v[58:59], v[60:61]
	v_add_f32_e32 v58, 1.0, v62
	v_add_f32_e32 v59, 1.0, v63
	v_rcp_f32_e32 v58, v58
	v_rcp_f32_e32 v59, v59
	v_cvt_pk_bf16_f32 v52, v52, v53
	v_lshlrev_b32_e32 v53, 16, v90
	v_lshlrev_b32_e32 v60, 16, v93
	v_and_b32_e32 v61, 0xffff0000, v93
	v_mul_f32_e32 v53, 0xbfb8aa3b, v53
	v_pk_fma_f32 v[54:55], v[54:55], v[58:59], v[60:61]
	v_exp_f32_e32 v58, v53
	v_and_b32_e32 v53, 0xffff0000, v90
	v_mul_f32_e32 v53, 0xbfb8aa3b, v53
	v_exp_f32_e32 v59, v53
	v_lshlrev_b32_e32 v60, 16, v91
	v_cvt_pk_bf16_f32 v53, v54, v55
	v_add_f32_e32 v54, 1.0, v58
	v_add_f32_e32 v55, 1.0, v59
	v_mul_f32_e32 v60, 0xbfb8aa3b, v60
	v_and_b32_e32 v61, 0xffff0000, v91
	v_rcp_f32_e32 v54, v54
	v_rcp_f32_e32 v55, v55
	v_exp_f32_e32 v60, v60
	v_mul_f32_e32 v61, 0xbfb8aa3b, v61
	v_exp_f32_e32 v61, v61
	v_lshlrev_b32_e32 v58, 16, v94
	v_and_b32_e32 v59, 0xffff0000, v94
	v_pk_fma_f32 v[48:49], v[48:49], v[54:55], v[58:59]
	v_add_f32_e32 v54, 1.0, v60
	v_rcp_f32_e32 v58, v54
	v_add_f32_e32 v54, 1.0, v61
	v_rcp_f32_e32 v59, v54
	v_cvt_pk_bf16_f32 v54, v48, v49
	v_lshlrev_b32_e32 v48, 16, v95
	v_and_b32_e32 v49, 0xffff0000, v95
	v_pk_fma_f32 v[48:49], v[50:51], v[58:59], v[48:49]
	s_nop 0
	v_cvt_pk_bf16_f32 v55, v48, v49
	s_waitcnt vmcnt(4)
	v_lshlrev_b32_e32 v48, 16, v76
	v_mul_f32_e32 v48, 0xbfb8aa3b, v48
	v_exp_f32_e32 v50, v48
	v_and_b32_e32 v48, 0xffff0000, v76
	v_mul_f32_e32 v48, 0xbfb8aa3b, v48
	v_exp_f32_e32 v51, v48
	global_store_dwordx4 v[56:57], v[52:55], off offset:64
	v_add_f32_e32 v50, 1.0, v50
	v_rcp_f32_e32 v50, v50
	v_lshlrev_b32_e32 v54, 16, v77
	v_and_b32_e32 v55, 0xffff0000, v77
	v_add_f32_e32 v51, 1.0, v51
	v_mul_f32_e32 v54, 0xbfb8aa3b, v54
	v_mul_f32_e32 v55, 0xbfb8aa3b, v55
	v_rcp_f32_e32 v51, v51
	v_exp_f32_e32 v54, v54
	v_exp_f32_e32 v55, v55
	s_waitcnt vmcnt(4)
	v_lshlrev_b32_e32 v52, 16, v72
	v_and_b32_e32 v53, 0xffff0000, v72
	v_pk_fma_f32 v[44:45], v[44:45], v[50:51], v[52:53]
	v_add_f32_e32 v50, 1.0, v54
	v_add_f32_e32 v51, 1.0, v55
	v_rcp_f32_e32 v50, v50
	v_rcp_f32_e32 v51, v51
	v_cvt_pk_bf16_f32 v44, v44, v45
	v_lshlrev_b32_e32 v45, 16, v78
	v_lshlrev_b32_e32 v52, 16, v73
	v_and_b32_e32 v53, 0xffff0000, v73
	v_mul_f32_e32 v45, 0xbfb8aa3b, v45
	v_pk_fma_f32 v[46:47], v[46:47], v[50:51], v[52:53]
	v_exp_f32_e32 v50, v45
	v_and_b32_e32 v45, 0xffff0000, v78
	v_mul_f32_e32 v45, 0xbfb8aa3b, v45
	v_exp_f32_e32 v51, v45
	v_lshlrev_b32_e32 v52, 16, v79
	v_cvt_pk_bf16_f32 v45, v46, v47
	v_add_f32_e32 v46, 1.0, v50
	v_add_f32_e32 v47, 1.0, v51
	v_mul_f32_e32 v52, 0xbfb8aa3b, v52
	v_and_b32_e32 v53, 0xffff0000, v79
	v_rcp_f32_e32 v46, v46
	v_rcp_f32_e32 v47, v47
	v_exp_f32_e32 v52, v52
	v_mul_f32_e32 v53, 0xbfb8aa3b, v53
	v_exp_f32_e32 v53, v53
	v_lshlrev_b32_e32 v50, 16, v74
	v_and_b32_e32 v51, 0xffff0000, v74
	v_pk_fma_f32 v[40:41], v[40:41], v[46:47], v[50:51]
	v_add_f32_e32 v46, 1.0, v52
	v_rcp_f32_e32 v50, v46
	v_add_f32_e32 v46, 1.0, v53
	v_rcp_f32_e32 v51, v46
	v_cvt_pk_bf16_f32 v46, v40, v41
	v_lshlrev_b32_e32 v40, 16, v75
	v_and_b32_e32 v41, 0xffff0000, v75
	v_pk_fma_f32 v[40:41], v[42:43], v[50:51], v[40:41]
	s_waitcnt vmcnt(3)
	v_lshlrev_b32_e32 v42, 16, v68
	v_and_b32_e32 v43, 0xffff0000, v68
	v_mul_f32_e32 v42, 0xbfb8aa3b, v42
	v_mul_f32_e32 v43, 0xbfb8aa3b, v43
	v_lshlrev_b64 v[48:49], 12, v[98:99]
	v_exp_f32_e32 v42, v42
	v_exp_f32_e32 v43, v43
	v_cvt_pk_bf16_f32 v47, v40, v41
	v_lshl_add_u64 v[40:41], s[14:15], 0, v[48:49]
	v_lshl_add_u64 v[40:41], v[40:41], 0, v[152:153]
	global_store_dwordx4 v[40:41], v[44:47], off
	v_add_f32_e32 v42, 1.0, v42
	v_add_f32_e32 v43, 1.0, v43
	v_lshlrev_b32_e32 v46, 16, v69
	v_and_b32_e32 v47, 0xffff0000, v69
	v_mul_f32_e32 v46, 0xbfb8aa3b, v46
	v_mul_f32_e32 v47, 0xbfb8aa3b, v47
	v_rcp_f32_e32 v42, v42
	v_rcp_f32_e32 v43, v43
	v_exp_f32_e32 v46, v46
	v_exp_f32_e32 v47, v47
	s_waitcnt vmcnt(3)
	v_lshlrev_b32_e32 v44, 16, v64
	v_and_b32_e32 v45, 0xffff0000, v64
	v_pk_fma_f32 v[36:37], v[36:37], v[42:43], v[44:45]
	v_add_f32_e32 v42, 1.0, v46
	v_add_f32_e32 v43, 1.0, v47
	v_rcp_f32_e32 v42, v42
	v_rcp_f32_e32 v43, v43
	v_cvt_pk_bf16_f32 v36, v36, v37
	v_lshlrev_b32_e32 v37, 16, v70
	v_lshlrev_b32_e32 v44, 16, v65
	v_and_b32_e32 v45, 0xffff0000, v65
	v_mul_f32_e32 v37, 0xbfb8aa3b, v37
	v_pk_fma_f32 v[38:39], v[38:39], v[42:43], v[44:45]
	v_exp_f32_e32 v42, v37
	v_and_b32_e32 v37, 0xffff0000, v70
	v_mul_f32_e32 v37, 0xbfb8aa3b, v37
	v_exp_f32_e32 v43, v37
	v_lshlrev_b32_e32 v44, 16, v71
	v_cvt_pk_bf16_f32 v37, v38, v39
	v_add_f32_e32 v38, 1.0, v42
	v_add_f32_e32 v39, 1.0, v43
	v_mul_f32_e32 v44, 0xbfb8aa3b, v44
	v_and_b32_e32 v45, 0xffff0000, v71
	v_rcp_f32_e32 v38, v38
	v_rcp_f32_e32 v39, v39
	v_exp_f32_e32 v44, v44
	v_mul_f32_e32 v45, 0xbfb8aa3b, v45
	v_exp_f32_e32 v45, v45
	v_lshlrev_b32_e32 v42, 16, v66
	v_and_b32_e32 v43, 0xffff0000, v66
	v_pk_fma_f32 v[32:33], v[32:33], v[38:39], v[42:43]
	v_add_f32_e32 v38, 1.0, v44
	v_rcp_f32_e32 v42, v38
	v_add_f32_e32 v38, 1.0, v45
	v_rcp_f32_e32 v43, v38
	v_cvt_pk_bf16_f32 v38, v32, v33
	v_lshlrev_b32_e32 v32, 16, v67
	v_and_b32_e32 v33, 0xffff0000, v67
	v_add_u32_e32 v64, 0xa0, v156
	v_pk_fma_f32 v[32:33], v[34:35], v[42:43], v[32:33]
	v_ashrrev_i32_e32 v65, 31, v64
	v_cvt_pk_bf16_f32 v39, v32, v33
	v_lshlrev_b64 v[32:33], 11, v[64:65]
	v_lshl_add_u64 v[32:33], v[32:33], 0, v[154:155]
	v_lshlrev_b64 v[32:33], 1, v[32:33]
	global_store_dwordx4 v[40:41], v[36:39], off offset:64
	v_lshl_add_u64 v[34:35], s[12:13], 0, v[32:33]
	global_load_dwordx4 v[48:51], v[34:35], off
	v_lshl_add_u64 v[34:35], s[8:9], 0, v[32:33]
	global_load_dwordx4 v[52:55], v[34:35], off
	v_or_b32_e32 v32, 64, v32
	v_lshl_add_u64 v[34:35], s[12:13], 0, v[32:33]
	global_load_dwordx4 v[56:59], v[34:35], off
	v_lshl_add_u64 v[32:33], s[8:9], 0, v[32:33]
	global_load_dwordx4 v[60:63], v[32:33], off
	v_add_u32_e32 v66, 0xb0, v156
	v_ashrrev_i32_e32 v67, 31, v66
	v_lshlrev_b64 v[32:33], 11, v[66:67]
	v_lshl_add_u64 v[32:33], v[32:33], 0, v[154:155]
	v_lshlrev_b64 v[32:33], 1, v[32:33]
	v_lshl_add_u64 v[34:35], s[12:13], 0, v[32:33]
	v_lshl_add_u64 v[36:37], s[8:9], 0, v[32:33]
	global_load_dwordx4 v[44:47], v[34:35], off
	global_load_dwordx4 v[40:43], v[36:37], off
	v_or_b32_e32 v32, 64, v32
	v_lshl_add_u64 v[34:35], s[12:13], 0, v[32:33]
	v_lshl_add_u64 v[32:33], s[8:9], 0, v[32:33]
	global_load_dwordx4 v[36:39], v[34:35], off
	s_nop 0
	global_load_dwordx4 v[32:35], v[32:33], off
	v_lshlrev_b64 v[64:65], 12, v[64:65]
	s_waitcnt vmcnt(7)
; __device__ __forceinline__ unsigned pk2(float lo, float hi) { const f32x2 v = {lo, hi}; const bf16x2_t b = __builtin_convertvector(v, bf16x2_t); return __builtin_bit_cast(unsigned, b); }
; __device__ __forceinline__ float sigmoid_f(float v) { return __builtin_amdgcn_rcpf(1.f + __expf(-v)); }
;     __device__ __forceinline__ void operator()(const f32x4 (&acc)[2][2][4][2], const pg8::Unit& u, int wr, int wc, int fr, int fq) const {
;     ...
;             for (int mm = 0; mm < 2; ++mm) { const int m = mp * 2 + mm; const size_t ro = (size_t)(row0 + ai * 128 + m * 16) * 2048 + col0;
; #pragma unroll
;                 for (int bj = 0; bj < 2; ++bj) { const u32x4 g = gb[mm][bj]; const u32x4 t = tb[mm][bj];
;                     const f32x4 v0 = acc[ai][bj][m][0], v1 = acc[ai][bj][m][1];
;                     u32x4 w; w.x = pk2(bflo(t.x) + sigmoid_f(bflo(g.x)) * v0[0], bfhi(t.x) + sigmoid_f(bfhi(g.x)) * v0[1]);
;                     w.y = pk2(bflo(t.y) + sigmoid_f(bflo(g.y)) * v0[2], bfhi(t.y) + sigmoid_f(bfhi(g.y)) * v0[3]);
;                     w.z = pk2(bflo(t.z) + sigmoid_f(bflo(g.z)) * v1[0], bfhi(t.z) + sigmoid_f(bfhi(g.z)) * v1[1]);
;                     w.w = pk2(bflo(t.w) + sigmoid_f(bflo(g.w)) * v1[2], bfhi(t.w) + sigmoid_f(bfhi(g.w)) * v1[3]);
;                     *(u32x4*)(O + ro + bj * 128) = w; } }
	v_lshlrev_b32_e32 v68, 16, v48
	v_and_b32_e32 v48, 0xffff0000, v48
	v_mul_f32_e32 v48, 0xbfb8aa3b, v48
	v_exp_f32_e32 v48, v48
	v_mul_f32_e32 v68, 0xbfb8aa3b, v68
	v_exp_f32_e32 v68, v68
	s_waitcnt vmcnt(6)
	v_lshlrev_b32_e32 v70, 16, v52
	v_add_f32_e32 v48, 1.0, v48
	v_rcp_f32_e32 v69, v48
	v_lshlrev_b32_e32 v48, 16, v49
	v_and_b32_e32 v49, 0xffff0000, v49
	v_mul_f32_e32 v48, 0xbfb8aa3b, v48
	v_mul_f32_e32 v49, 0xbfb8aa3b, v49
	v_exp_f32_e32 v48, v48
	v_exp_f32_e32 v49, v49
	v_add_f32_e32 v68, 1.0, v68
	v_rcp_f32_e32 v68, v68
	v_add_f32_e32 v48, 1.0, v48
	v_add_f32_e32 v49, 1.0, v49
	v_and_b32_e32 v71, 0xffff0000, v52
	v_rcp_f32_e32 v48, v48
	v_rcp_f32_e32 v49, v49
	v_pk_fma_f32 v[28:29], v[28:29], v[68:69], v[70:71]
	v_lshlrev_b32_e32 v52, 16, v53
	v_cvt_pk_bf16_f32 v28, v28, v29
	v_lshlrev_b32_e32 v29, 16, v50
	v_and_b32_e32 v53, 0xffff0000, v53
	v_mul_f32_e32 v29, 0xbfb8aa3b, v29
	v_pk_fma_f32 v[30:31], v[30:31], v[48:49], v[52:53]
	v_exp_f32_e32 v48, v29
	v_and_b32_e32 v29, 0xffff0000, v50
	v_mul_f32_e32 v29, 0xbfb8aa3b, v29
	v_exp_f32_e32 v49, v29
	v_lshlrev_b32_e32 v50, 16, v51
	v_cvt_pk_bf16_f32 v29, v30, v31
	v_add_f32_e32 v30, 1.0, v48
	v_add_f32_e32 v31, 1.0, v49
	v_mul_f32_e32 v50, 0xbfb8aa3b, v50
	v_and_b32_e32 v51, 0xffff0000, v51
	v_rcp_f32_e32 v30, v30
	v_rcp_f32_e32 v31, v31
	v_exp_f32_e32 v50, v50
	v_mul_f32_e32 v51, 0xbfb8aa3b, v51
	v_exp_f32_e32 v51, v51
	v_lshlrev_b32_e32 v48, 16, v54
	v_and_b32_e32 v49, 0xffff0000, v54
	v_pk_fma_f32 v[24:25], v[24:25], v[30:31], v[48:49]
	v_add_f32_e32 v30, 1.0, v50
	v_rcp_f32_e32 v48, v30
	v_add_f32_e32 v30, 1.0, v51
	v_rcp_f32_e32 v49, v30
	v_cvt_pk_bf16_f32 v30, v24, v25
	v_lshlrev_b32_e32 v24, 16, v55
	v_and_b32_e32 v25, 0xffff0000, v55
	v_pk_fma_f32 v[24:25], v[26:27], v[48:49], v[24:25]
	s_waitcnt vmcnt(5)
	v_lshlrev_b32_e32 v26, 16, v56
	v_and_b32_e32 v27, 0xffff0000, v56
	v_mul_f32_e32 v26, 0xbfb8aa3b, v26
	v_mul_f32_e32 v27, 0xbfb8aa3b, v27
	v_exp_f32_e32 v26, v26
	v_exp_f32_e32 v27, v27
	v_cvt_pk_bf16_f32 v31, v24, v25
	v_lshl_add_u64 v[24:25], s[14:15], 0, v[64:65]
	v_lshl_add_u64 v[24:25], v[24:25], 0, v[152:153]
	global_store_dwordx4 v[24:25], v[28:31], off
	v_add_f32_e32 v26, 1.0, v26
	v_add_f32_e32 v27, 1.0, v27
	v_lshlrev_b32_e32 v30, 16, v57
	v_and_b32_e32 v31, 0xffff0000, v57
	v_mul_f32_e32 v30, 0xbfb8aa3b, v30
	v_mul_f32_e32 v31, 0xbfb8aa3b, v31
	v_rcp_f32_e32 v26, v26
	v_rcp_f32_e32 v27, v27
	v_exp_f32_e32 v30, v30
	v_exp_f32_e32 v31, v31
	s_waitcnt vmcnt(5)
	v_lshlrev_b32_e32 v28, 16, v60
	v_and_b32_e32 v29, 0xffff0000, v60
	v_pk_fma_f32 v[20:21], v[20:21], v[26:27], v[28:29]
	v_add_f32_e32 v26, 1.0, v30
	v_add_f32_e32 v27, 1.0, v31
	v_rcp_f32_e32 v26, v26
	v_rcp_f32_e32 v27, v27
	v_cvt_pk_bf16_f32 v20, v20, v21
	v_lshlrev_b32_e32 v21, 16, v58
	v_lshlrev_b32_e32 v28, 16, v61
	v_and_b32_e32 v29, 0xffff0000, v61
	v_mul_f32_e32 v21, 0xbfb8aa3b, v21
	v_pk_fma_f32 v[22:23], v[22:23], v[26:27], v[28:29]
	v_exp_f32_e32 v26, v21
	v_and_b32_e32 v21, 0xffff0000, v58
	v_mul_f32_e32 v21, 0xbfb8aa3b, v21
	v_exp_f32_e32 v27, v21
	v_lshlrev_b32_e32 v28, 16, v59
	v_cvt_pk_bf16_f32 v21, v22, v23
	v_add_f32_e32 v22, 1.0, v26
	v_add_f32_e32 v23, 1.0, v27
	v_mul_f32_e32 v28, 0xbfb8aa3b, v28
	v_and_b32_e32 v29, 0xffff0000, v59
	v_rcp_f32_e32 v22, v22
	v_rcp_f32_e32 v23, v23
	v_exp_f32_e32 v28, v28
	v_mul_f32_e32 v29, 0xbfb8aa3b, v29
	v_exp_f32_e32 v29, v29
	v_lshlrev_b32_e32 v26, 16, v62
	v_and_b32_e32 v27, 0xffff0000, v62
	v_pk_fma_f32 v[16:17], v[16:17], v[22:23], v[26:27]
	v_add_f32_e32 v22, 1.0, v28
	v_rcp_f32_e32 v26, v22
	v_add_f32_e32 v22, 1.0, v29
	v_rcp_f32_e32 v27, v22
	v_cvt_pk_bf16_f32 v22, v16, v17
	v_lshlrev_b32_e32 v16, 16, v63
	v_and_b32_e32 v17, 0xffff0000, v63
	v_pk_fma_f32 v[16:17], v[18:19], v[26:27], v[16:17]
	s_nop 0
	v_cvt_pk_bf16_f32 v23, v16, v17
	s_waitcnt vmcnt(4)
; __device__ __forceinline__ unsigned pk2(float lo, float hi) { const f32x2 v = {lo, hi}; const bf16x2_t b = __builtin_convertvector(v, bf16x2_t); return __builtin_bit_cast(unsigned, b); }
; __device__ __forceinline__ float sigmoid_f(float v) { return __builtin_amdgcn_rcpf(1.f + __expf(-v)); }
;     __device__ __forceinline__ void operator()(const f32x4 (&acc)[2][2][4][2], const pg8::Unit& u, int wr, int wc, int fr, int fq) const {
;     ...
;             for (int mm = 0; mm < 2; ++mm) { const int m = mp * 2 + mm; const size_t ro = (size_t)(row0 + ai * 128 + m * 16) * 2048 + col0;
; #pragma unroll
;                 for (int bj = 0; bj < 2; ++bj) { const u32x4 g = gb[mm][bj]; const u32x4 t = tb[mm][bj];
;                     const f32x4 v0 = acc[ai][bj][m][0], v1 = acc[ai][bj][m][1];
;                     u32x4 w; w.x = pk2(bflo(t.x) + sigmoid_f(bflo(g.x)) * v0[0], bfhi(t.x) + sigmoid_f(bfhi(g.x)) * v0[1]);
;                     w.y = pk2(bflo(t.y) + sigmoid_f(bflo(g.y)) * v0[2], bfhi(t.y) + sigmoid_f(bfhi(g.y)) * v0[3]);
;                     w.z = pk2(bflo(t.z) + sigmoid_f(bflo(g.z)) * v1[0], bfhi(t.z) + sigmoid_f(bfhi(g.z)) * v1[1]);
;                     w.w = pk2(bflo(t.w) + sigmoid_f(bflo(g.w)) * v1[2], bfhi(t.w) + sigmoid_f(bfhi(g.w)) * v1[3]);
;                     *(u32x4*)(O + ro + bj * 128) = w; } }
	v_lshlrev_b32_e32 v16, 16, v44
	v_mul_f32_e32 v16, 0xbfb8aa3b, v16
	v_exp_f32_e32 v18, v16
	v_and_b32_e32 v16, 0xffff0000, v44
	v_mul_f32_e32 v16, 0xbfb8aa3b, v16
	v_exp_f32_e32 v19, v16
	global_store_dwordx4 v[24:25], v[20:23], off offset:64
	v_add_f32_e32 v18, 1.0, v18
	v_rcp_f32_e32 v18, v18
	v_lshlrev_b32_e32 v22, 16, v45
	v_and_b32_e32 v23, 0xffff0000, v45
	v_add_f32_e32 v19, 1.0, v19
	v_mul_f32_e32 v22, 0xbfb8aa3b, v22
	v_mul_f32_e32 v23, 0xbfb8aa3b, v23
	v_rcp_f32_e32 v19, v19
	v_exp_f32_e32 v22, v22
	v_exp_f32_e32 v23, v23
	s_waitcnt vmcnt(4)
	v_lshlrev_b32_e32 v20, 16, v40
	v_and_b32_e32 v21, 0xffff0000, v40
	v_pk_fma_f32 v[12:13], v[12:13], v[18:19], v[20:21]
	v_add_f32_e32 v18, 1.0, v22
	v_add_f32_e32 v19, 1.0, v23
	v_rcp_f32_e32 v18, v18
	v_rcp_f32_e32 v19, v19
	v_cvt_pk_bf16_f32 v12, v12, v13
	v_lshlrev_b32_e32 v13, 16, v46
	v_lshlrev_b32_e32 v20, 16, v41
	v_and_b32_e32 v21, 0xffff0000, v41
	v_mul_f32_e32 v13, 0xbfb8aa3b, v13
	v_pk_fma_f32 v[14:15], v[14:15], v[18:19], v[20:21]
	v_exp_f32_e32 v18, v13
	v_and_b32_e32 v13, 0xffff0000, v46
	v_mul_f32_e32 v13, 0xbfb8aa3b, v13
	v_exp_f32_e32 v19, v13
	v_lshlrev_b32_e32 v20, 16, v47
	v_cvt_pk_bf16_f32 v13, v14, v15
	v_add_f32_e32 v14, 1.0, v18
	v_add_f32_e32 v15, 1.0, v19
	v_mul_f32_e32 v20, 0xbfb8aa3b, v20
	v_and_b32_e32 v21, 0xffff0000, v47
	v_rcp_f32_e32 v14, v14
	v_rcp_f32_e32 v15, v15
	v_exp_f32_e32 v20, v20
	v_mul_f32_e32 v21, 0xbfb8aa3b, v21
	v_exp_f32_e32 v21, v21
	v_lshlrev_b32_e32 v18, 16, v42
	v_and_b32_e32 v19, 0xffff0000, v42
	v_pk_fma_f32 v[8:9], v[8:9], v[14:15], v[18:19]
	v_add_f32_e32 v14, 1.0, v20
	v_rcp_f32_e32 v18, v14
	v_add_f32_e32 v14, 1.0, v21
	v_rcp_f32_e32 v19, v14
	v_cvt_pk_bf16_f32 v14, v8, v9
	v_lshlrev_b32_e32 v8, 16, v43
	v_and_b32_e32 v9, 0xffff0000, v43
	v_pk_fma_f32 v[8:9], v[10:11], v[18:19], v[8:9]
	s_waitcnt vmcnt(3)
	v_lshlrev_b32_e32 v10, 16, v36
	v_and_b32_e32 v11, 0xffff0000, v36
	v_mul_f32_e32 v10, 0xbfb8aa3b, v10
	v_mul_f32_e32 v11, 0xbfb8aa3b, v11
	v_lshlrev_b64 v[16:17], 12, v[66:67]
	v_exp_f32_e32 v10, v10
	v_exp_f32_e32 v11, v11
	v_cvt_pk_bf16_f32 v15, v8, v9
	v_lshl_add_u64 v[8:9], s[14:15], 0, v[16:17]
	v_lshl_add_u64 v[8:9], v[8:9], 0, v[152:153]
	global_store_dwordx4 v[8:9], v[12:15], off
	v_add_f32_e32 v10, 1.0, v10
	v_add_f32_e32 v11, 1.0, v11
	v_lshlrev_b32_e32 v14, 16, v37
	v_and_b32_e32 v15, 0xffff0000, v37
	v_mul_f32_e32 v14, 0xbfb8aa3b, v14
	v_mul_f32_e32 v15, 0xbfb8aa3b, v15
	v_rcp_f32_e32 v10, v10
	v_rcp_f32_e32 v11, v11
	v_exp_f32_e32 v14, v14
	v_exp_f32_e32 v15, v15
	s_waitcnt vmcnt(3)
	v_lshlrev_b32_e32 v12, 16, v32
	v_and_b32_e32 v13, 0xffff0000, v32
	v_pk_fma_f32 v[4:5], v[4:5], v[10:11], v[12:13]
	v_add_f32_e32 v10, 1.0, v14
	v_add_f32_e32 v11, 1.0, v15
	v_rcp_f32_e32 v10, v10
	v_rcp_f32_e32 v11, v11
	v_cvt_pk_bf16_f32 v4, v4, v5
	v_lshlrev_b32_e32 v5, 16, v38
	v_lshlrev_b32_e32 v12, 16, v33
	v_and_b32_e32 v13, 0xffff0000, v33
	v_mul_f32_e32 v5, 0xbfb8aa3b, v5
	v_pk_fma_f32 v[6:7], v[6:7], v[10:11], v[12:13]
	v_exp_f32_e32 v10, v5
	v_and_b32_e32 v5, 0xffff0000, v38
	v_mul_f32_e32 v5, 0xbfb8aa3b, v5
	v_exp_f32_e32 v11, v5
	v_lshlrev_b32_e32 v12, 16, v39
	v_cvt_pk_bf16_f32 v5, v6, v7
	v_add_f32_e32 v6, 1.0, v10
	v_add_f32_e32 v7, 1.0, v11
	v_mul_f32_e32 v12, 0xbfb8aa3b, v12
	v_and_b32_e32 v13, 0xffff0000, v39
	v_rcp_f32_e32 v6, v6
	v_rcp_f32_e32 v7, v7
	v_exp_f32_e32 v12, v12
	v_mul_f32_e32 v13, 0xbfb8aa3b, v13
	v_exp_f32_e32 v13, v13
	v_lshlrev_b32_e32 v10, 16, v34
	v_and_b32_e32 v11, 0xffff0000, v34
	v_pk_fma_f32 v[0:1], v[0:1], v[6:7], v[10:11]
	v_add_f32_e32 v6, 1.0, v12
	v_rcp_f32_e32 v10, v6
	v_add_f32_e32 v6, 1.0, v13
	v_rcp_f32_e32 v11, v6
	v_cvt_pk_bf16_f32 v6, v0, v1
	v_lshlrev_b32_e32 v0, 16, v35
	v_and_b32_e32 v1, 0xffff0000, v35
	v_pk_fma_f32 v[0:1], v[2:3], v[10:11], v[0:1]
	s_nop 0
	v_cvt_pk_bf16_f32 v7, v0, v1
	global_store_dwordx4 v[8:9], v[4:7], off offset:64
	s_cbranch_vccnz .LBB0_856
	s_andn2_b64 vcc, exec, s[10:11]
	s_cbranch_vccnz .LBB0_855
	s_barrier
	s_branch .LBB0_855

; #define PG8_STAGE(bufoff, gbase, voff) do { _Pragma("unroll") for (int _i = 0; _i < 2; ++_i) \
;         __builtin_amdgcn_global_load_lds((const unsigned*)((const char*)(gbase) + (voff)[_i]), (PG8_LAS unsigned*)(lds + (bufoff) + ldsw + _i * 8192), 16, 0, 0); } while (0)
; #define PG8_WAIT_V(n) asm volatile("s_waitcnt vmcnt(" #n ")" ::: "memory")
; #define PG8_BAR __builtin_amdgcn_s_barrier()
; template <class Epi, class Sched, bool ALIGN_EPI = false, bool SP2 = false>
; __device__ __forceinline__ void gemm_phase(PG8_LAS unsigned char* lds, const Gemm g, const Sched& S, const Epi& E) {
;     const int tid = threadIdx.x, wid = __builtin_amdgcn_readfirstlane(tid >> 6), lane = tid & 63, wr = wid >> 2, wc = wid & 3, fr = lane & 15, fq = lane >> 4;
;     const int K = g.K, nt = K / BK;
;     unsigned voffA[2], voffB[2];
; #pragma unroll
;     for (int i = 0; i < 2; ++i) { int R, C; stage_rc(tid * 16 + i * 8192, R, C); const int Rb = Epi::PERM ? ((R & ~31) + perm32(R & 31)) : R;
;         voffA[i] = (unsigned)(R * K + C) * 2u; voffB[i] = (unsigned)(Rb * K + C) * 2u; }
;     const size_t kstep = (size_t)(BK * 2);
;     const size_t hstep = (size_t)HALF * K * 2;
;     const size_t tstep = 2 * hstep;
;     const unsigned ldsw = (unsigned)wid * 1024u;
;     const int aoff = lds_byte(wr * 64 + fr, fq * 8), boff = lds_byte(wc * 32 + fr, fq * 8);
;     ...
;         PG8_WAIT_V(2); PG8_BAR;
;         PG8_STAGE(PG8_SB(1, 0), cB + kstep, voffB); PG8_STAGE(PG8_SA(1, 0), cA + kstep, voffA); PG8_STAGE(PG8_SB(1, 1), cB + hstep + kstep, voffB);
;         PG8_WAIT_V(6); PG8_BAR;
.LBB0_933:
	s_add_u32 s10, s94, 0x10500000
	s_addc_u32 s11, s95, 0
	s_lshl_b32 s1, s1, 5
	s_mov_b64 s[12:13], 0x80
	s_and_b32 s20, s1, 0x60
	s_add_i32 m0, s31, 0x18000
	v_lshl_add_u64 v[6:7], v[6:7], 0, s[12:13]
	s_lshl_b32 s16, s5, 13
	s_lshl_b32 s17, s20, 8
	s_waitcnt vmcnt(2)
	s_barrier
	global_load_lds_dwordx4 v[6:7], off
	v_lshl_add_u64 v[4:5], v[4:5], 0, s[12:13]
	s_add_i32 m0, s31, 0x1a000
	s_add_i32 s50, s31, 0x8000
	s_add_i32 s51, s31, 0xa000
	global_load_lds_dwordx4 v[4:5], off
	v_lshl_add_u64 v[2:3], v[2:3], 0, s[12:13]
	s_mov_b32 m0, s50
	s_add_u32 s14, s36, 0x80080
	global_load_lds_dwordx4 v[2:3], off
	v_lshl_add_u64 v[0:1], v[0:1], 0, s[12:13]
	s_mov_b32 m0, s51
	s_addc_u32 s15, s37, 0
	global_load_lds_dwordx4 v[0:1], off
	s_add_i32 m0, s31, 0x1c000
	v_lshl_add_u64 v[0:1], s[14:15], 0, v[130:131]
	global_load_lds_dwordx4 v[0:1], off
	v_lshl_add_u64 v[0:1], s[14:15], 0, v[134:135]
	s_add_i32 m0, s31, 0x1e000
	s_sext_i32_i8 s1, s4
	global_load_lds_dwordx4 v[0:1], off
	v_and_b32_e32 v0, 15, v161
	v_lshlrev_b32_e32 v1, 1, v11
	v_lshlrev_b32_e32 v2, 2, v161
	v_lshlrev_b32_e32 v3, 6, v161
	s_movk_i32 s4, 0x3c0
	v_lshl_or_b32 v168, s5, 6, v0
	v_lshl_or_b32 v0, v0, 6, v1
	v_and_b32_e32 v2, 32, v2
	v_and_or_b32 v1, v3, s4, v1
	v_bitop3_b32 v169, s17, v1, v2 bitop3:0xf6
	v_lshlrev_b32_e32 v1, 9, v161
	v_bitop3_b32 v0, v0, s16, v2 bitop3:0xde
	v_and_b32_e32 v1, 0x70000, v1
	v_lshlrev_b32_e32 v2, 12, v10
	s_cmpk_lt_u32 s3, 0x100
	v_or3_b32 v1, v8, v1, v2
	s_cselect_b64 s[14:15], -1, 0
	s_waitcnt lgkmcnt(0)
	s_ashr_i32 s52, s47, 31
	v_add_u32_e32 v136, v1, v9
	v_lshlrev_b32_e32 v1, 5, v12
	s_waitcnt vmcnt(6)
	s_add_u32 s18, s86, 0x4000
	v_and_b32_e32 v1, 0xf0000, v1
	s_addc_u32 s19, s87, 0
	v_or3_b32 v1, v8, v1, v2
	s_add_i32 s53, 0, 0x10000
	s_add_i32 s54, 0, 0x14000
	s_mov_b64 s[16:17], 0x4000
	v_lshl_add_u32 v170, s20, 1, v11
	v_mov_b32_e32 v137, v131
	v_add_u32_e32 v138, v1, v9
	v_mov_b32_e32 v139, v131
	v_mov_b64_e32 v[140:141], 0x400
	v_mov_b64_e32 v[142:143], 0x3ff
	v_add_u32_e32 v161, s53, v169
	v_add_u32_e32 v171, 0x11000, v169
	v_add_u32_e32 v172, 0, v0
	s_mov_b32 s20, 0x3f9837f0
	s_barrier
	s_branch .LBB0_936

; #define PG8_STAGE(bufoff, gbase, voff) do { _Pragma("unroll") for (int _i = 0; _i < 2; ++_i) \
;         __builtin_amdgcn_global_load_lds((const unsigned*)((const char*)(gbase) + (voff)[_i]), (PG8_LAS unsigned*)(lds + (bufoff) + ldsw + _i * 8192), 16, 0, 0); } while (0)
; #define PG8_LDA(dst, b, h) do { _Pragma("unroll") for (int m = 0; m < 4; ++m) _Pragma("unroll") for (int k = 0; k < 2; ++k) dst[m][k] = *(const PG8_LAS bf16x8*)(lds + PG8_SA(b, h) + aoff + m * 2048 + k * 1024); } while (0)
; #define PG8_LDB(dst, b, h) do { _Pragma("unroll") for (int n = 0; n < 2; ++n) _Pragma("unroll") for (int k = 0; k < 2; ++k) dst[n][k] = *(const PG8_LAS bf16x8*)(lds + PG8_SB(b, h) + boff + n * 2048 + k * 1024); } while (0)
; #define PG8_MMA(ai, bj, At, Bt) do { __builtin_amdgcn_s_setprio(1); _Pragma("unroll") for (int m = 0; m < 4; ++m) _Pragma("unroll") for (int n = 0; n < 2; ++n) _Pragma("unroll") for (int k = 0; k < 2; ++k) \
;         acc[ai][bj][m][n] = __builtin_amdgcn_mfma_f32_16x16x32_bf16(Bt[n][k], At[m][k], acc[ai][bj][m][n], 0, 0, 0); __builtin_amdgcn_s_setprio(0); } while (0)
; #define PG8_WAIT_V(n) asm volatile("s_waitcnt vmcnt(" #n ")" ::: "memory")
; #define PG8_BAR __builtin_amdgcn_s_barrier()
; template <class Epi, class Sched, bool ALIGN_EPI = false, bool SP2 = false>
; __device__ __forceinline__ void gemm_phase(PG8_LAS unsigned char* lds, const Gemm g, const Sched& S, const Epi& E) {
;     ...
;         for (int t = 0; t < nt; t += 2) {
;             const bool last = (t == nt - 2);
;             const char* a1 = cA + (size_t)(t + 1) * kstep;
;             const char* a2 = last ? nA : cA + (size_t)(t + 2) * kstep; const char* b2 = last ? nB : cB + (size_t)(t + 2) * kstep;
;             const char* a3 = a2 + kstep; const char* b3 = b2 + kstep;
;             if (last && has_next) S.a_ready(nxt);
;             if constexpr (SP2) {
;             PG8_LDB(B0, 0, 0); PG8_LDB(B1, 0, 1); PG8_SCHED; PG8_LDA(At, 0, 0); PG8_STAGE(PG8_SA(1, 1), a1 + hstep, voffA);
;             PG8_WAIT_V(8); PG8_WAIT_L(0); PG8_BAR; PG8_MMA(0, 0, At, B0); PG8_MMA(0, 1, At, B1); PG8_BAR; PG8_SCHED;
;             PG8_LDA(At, 0, 1); PG8_STAGE(PG8_SB(0, 0), b2, voffB); PG8_STAGE(PG8_SB(0, 1), b2 + hstep, voffB); PG8_STAGE(PG8_SA(0, 0), a2, voffA);
;             PG8_WAIT_V(8); PG8_WAIT_L(0); PG8_BAR; PG8_MMA(1, 0, At, B0); PG8_MMA(1, 1, At, B1); PG8_BAR; PG8_SCHED;
.LBB0_943:
	ds_read_b128 v[144:147], v161
	ds_read_b128 v[148:151], v161 offset:1024
	ds_read_b128 v[152:155], v161 offset:2048
	ds_read_b128 v[156:159], v161 offset:3072
	ds_read_b128 v[162:165], v171
	ds_read_b128 v[174:177], v171 offset:1024
	ds_read_b128 v[178:181], v171 offset:2048
	ds_read_b128 v[182:185], v171 offset:3072
	s_add_u32 s36, s34, 0xfff80080
	s_addc_u32 s37, s35, -1
	s_cmp_eq_u32 s58, 28
	s_cselect_b32 s39, s3, s37
	s_cselect_b32 s38, s25, s36
	s_cselect_b32 s37, s23, s57
	s_cselect_b32 s36, s55, s56
	v_lshl_add_u64 v[166:167], s[34:35], 0, v[136:137]
	s_add_i32 m0, s31, 0xc000
	ds_read_b128 v[186:189], v172
	ds_read_b128 v[190:193], v172 offset:1024
	ds_read_b128 v[194:197], v172 offset:2048
	ds_read_b128 v[198:201], v172 offset:3072
	ds_read_b128 v[202:205], v172 offset:4096
	ds_read_b128 v[206:209], v172 offset:5120
	ds_read_b128 v[210:213], v172 offset:6144
	ds_read_b128 v[214:217], v172 offset:7168
	global_load_lds_dwordx4 v[166:167], off
	v_lshl_add_u64 v[166:167], s[34:35], 0, v[138:139]
	s_add_i32 m0, s31, 0xe000
	s_nop 0
	global_load_lds_dwordx4 v[166:167], off
	s_waitcnt vmcnt(8)
	s_waitcnt lgkmcnt(0)
	s_barrier
	s_setprio 1
	s_waitcnt lgkmcnt(0)
	v_mfma_f32_16x16x32_bf16 v[120:123], v[144:147], v[186:189], v[120:123]
	v_mfma_f32_16x16x32_bf16 v[124:127], v[152:155], v[186:189], v[124:127]
	v_mfma_f32_16x16x32_bf16 v[112:115], v[144:147], v[194:197], v[112:115]
	v_mfma_f32_16x16x32_bf16 v[116:119], v[152:155], v[194:197], v[116:119]
	v_mfma_f32_16x16x32_bf16 v[92:95], v[144:147], v[202:205], v[92:95]
	v_mfma_f32_16x16x32_bf16 v[88:91], v[152:155], v[202:205], v[88:91]
	v_mfma_f32_16x16x32_bf16 v[84:87], v[144:147], v[210:213], v[84:87]
	v_mfma_f32_16x16x32_bf16 v[80:83], v[152:155], v[210:213], v[80:83]
	v_mfma_f32_16x16x32_bf16 v[120:123], v[148:151], v[190:193], v[120:123]
	v_mfma_f32_16x16x32_bf16 v[124:127], v[156:159], v[190:193], v[124:127]
	v_mfma_f32_16x16x32_bf16 v[112:115], v[148:151], v[198:201], v[112:115]
	v_mfma_f32_16x16x32_bf16 v[116:119], v[156:159], v[198:201], v[116:119]
	v_mfma_f32_16x16x32_bf16 v[92:95], v[148:151], v[206:209], v[92:95]
	v_mfma_f32_16x16x32_bf16 v[88:91], v[156:159], v[206:209], v[88:91]
	v_mfma_f32_16x16x32_bf16 v[84:87], v[148:151], v[214:217], v[84:87]
	v_mfma_f32_16x16x32_bf16 v[80:83], v[156:159], v[214:217], v[80:83]
	s_setprio 0
	s_setprio 1
	v_mfma_f32_16x16x32_bf16 v[108:111], v[162:165], v[186:189], v[108:111]
	v_mfma_f32_16x16x32_bf16 v[104:107], v[178:181], v[186:189], v[104:107]
	v_mfma_f32_16x16x32_bf16 v[100:103], v[162:165], v[194:197], v[100:103]
	v_mfma_f32_16x16x32_bf16 v[96:99], v[178:181], v[194:197], v[96:99]
	v_mfma_f32_16x16x32_bf16 v[76:79], v[162:165], v[202:205], v[76:79]
	v_mfma_f32_16x16x32_bf16 v[72:75], v[178:181], v[202:205], v[72:75]
	v_mfma_f32_16x16x32_bf16 v[68:71], v[162:165], v[210:213], v[68:71]
	v_mfma_f32_16x16x32_bf16 v[64:67], v[178:181], v[210:213], v[64:67]
	v_mfma_f32_16x16x32_bf16 v[108:111], v[174:177], v[190:193], v[108:111]
	v_mfma_f32_16x16x32_bf16 v[104:107], v[182:185], v[190:193], v[104:107]
	v_mfma_f32_16x16x32_bf16 v[100:103], v[174:177], v[198:201], v[100:103]
	v_mfma_f32_16x16x32_bf16 v[96:99], v[182:185], v[198:201], v[96:99]
	v_mfma_f32_16x16x32_bf16 v[76:79], v[174:177], v[206:209], v[76:79]
	v_mfma_f32_16x16x32_bf16 v[72:75], v[182:185], v[206:209], v[72:75]
	v_mfma_f32_16x16x32_bf16 v[68:71], v[174:177], v[214:217], v[68:71]
	v_mfma_f32_16x16x32_bf16 v[64:67], v[182:185], v[214:217], v[64:67]
	s_setprio 0
	s_barrier
	s_add_i32 s59, s53, s43
	v_lshl_add_u64 v[166:167], s[36:37], 0, v[130:131]
	s_mov_b32 m0, s59
	ds_read_b128 v[186:189], v172 offset:16384
	ds_read_b128 v[190:193], v172 offset:17408
	ds_read_b128 v[194:197], v172 offset:18432
	ds_read_b128 v[198:201], v172 offset:19456
	ds_read_b128 v[202:205], v172 offset:20480
	ds_read_b128 v[206:209], v172 offset:21504
	ds_read_b128 v[210:213], v172 offset:22528
	ds_read_b128 v[214:217], v172 offset:23552
	global_load_lds_dwordx4 v[166:167], off
	s_add_i32 m0, s59, 0x2000
	s_add_u32 s60, s36, 0x80000
	v_lshl_add_u64 v[218:219], s[36:37], 0, v[134:135]
	s_addc_u32 s61, s37, 0
	s_add_i32 s59, s54, s43
	global_load_lds_dwordx4 v[218:219], off
	v_lshl_add_u64 v[220:221], s[60:61], 0, v[130:131]
	s_mov_b32 m0, s59
	v_lshl_add_u64 v[222:223], s[38:39], 0, v[132:133]
	global_load_lds_dwordx4 v[220:221], off
	v_lshl_add_u64 v[220:221], s[60:61], 0, v[134:135]
	s_add_i32 m0, s59, 0x2000
	s_nop 0
	global_load_lds_dwordx4 v[220:221], off
	v_lshl_add_u64 v[220:221], s[38:39], 0, v[128:129]
	s_mov_b32 m0, s31
	s_nop 0
	global_load_lds_dwordx4 v[220:221], off
	s_mov_b32 m0, s44
	s_nop 0
	global_load_lds_dwordx4 v[222:223], off
	s_waitcnt vmcnt(8)
	s_waitcnt lgkmcnt(0)
	s_barrier
; #define PG8_STAGE(bufoff, gbase, voff) do { _Pragma("unroll") for (int _i = 0; _i < 2; ++_i) \
;         __builtin_amdgcn_global_load_lds((const unsigned*)((const char*)(gbase) + (voff)[_i]), (PG8_LAS unsigned*)(lds + (bufoff) + ldsw + _i * 8192), 16, 0, 0); } while (0)
; #define PG8_LDA(dst, b, h) do { _Pragma("unroll") for (int m = 0; m < 4; ++m) _Pragma("unroll") for (int k = 0; k < 2; ++k) dst[m][k] = *(const PG8_LAS bf16x8*)(lds + PG8_SA(b, h) + aoff + m * 2048 + k * 1024); } while (0)
; #define PG8_LDB(dst, b, h) do { _Pragma("unroll") for (int n = 0; n < 2; ++n) _Pragma("unroll") for (int k = 0; k < 2; ++k) dst[n][k] = *(const PG8_LAS bf16x8*)(lds + PG8_SB(b, h) + boff + n * 2048 + k * 1024); } while (0)
; #define PG8_MMA(ai, bj, At, Bt) do { __builtin_amdgcn_s_setprio(1); _Pragma("unroll") for (int m = 0; m < 4; ++m) _Pragma("unroll") for (int n = 0; n < 2; ++n) _Pragma("unroll") for (int k = 0; k < 2; ++k) \
;         acc[ai][bj][m][n] = __builtin_amdgcn_mfma_f32_16x16x32_bf16(Bt[n][k], At[m][k], acc[ai][bj][m][n], 0, 0, 0); __builtin_amdgcn_s_setprio(0); } while (0)
; #define PG8_WAIT_V(n) asm volatile("s_waitcnt vmcnt(" #n ")" ::: "memory")
; #define PG8_WAIT_L(n) asm volatile("s_waitcnt lgkmcnt(" #n ")" ::: "memory")
; #define PG8_BAR __builtin_amdgcn_s_barrier()
; #define PG8_SCHED __builtin_amdgcn_sched_barrier(0)
; template <class Epi, class Sched, bool ALIGN_EPI = false, bool SP2 = false>
; __device__ __forceinline__ void gemm_phase(PG8_LAS unsigned char* lds, const Gemm g, const Sched& S, const Epi& E) {
;     ...
;             PG8_WAIT_V(8); PG8_WAIT_L(0); PG8_BAR; PG8_MMA(1, 0, At, B0); PG8_MMA(1, 1, At, B1); PG8_BAR; PG8_SCHED;
;             PG8_LDB(B0, 1, 0); PG8_LDB(B1, 1, 1); PG8_SCHED; PG8_LDA(At, 1, 0); PG8_STAGE(PG8_SA(0, 1), a2 + hstep, voffA);
;             PG8_WAIT_V(8); PG8_WAIT_L(0); PG8_BAR; PG8_MMA(0, 0, At, B0); PG8_MMA(0, 1, At, B1); PG8_BAR; PG8_SCHED;
;             PG8_LDA(At, 1, 1); PG8_STAGE(PG8_SB(1, 0), b3, voffB); PG8_STAGE(PG8_SB(1, 1), b3 + hstep, voffB); PG8_STAGE(PG8_SA(1, 0), a3, voffA);
;             PG8_WAIT_V(8); PG8_WAIT_L(0); PG8_BAR; PG8_MMA(1, 0, At, B0); PG8_MMA(1, 1, At, B1); PG8_BAR; PG8_SCHED;
	s_setprio 1
	s_waitcnt lgkmcnt(0)
	v_mfma_f32_16x16x32_bf16 v[60:63], v[144:147], v[186:189], v[60:63]
	v_mfma_f32_16x16x32_bf16 v[56:59], v[152:155], v[186:189], v[56:59]
	v_mfma_f32_16x16x32_bf16 v[52:55], v[144:147], v[194:197], v[52:55]
	v_mfma_f32_16x16x32_bf16 v[48:51], v[152:155], v[194:197], v[48:51]
	v_mfma_f32_16x16x32_bf16 v[28:31], v[144:147], v[202:205], v[28:31]
	v_mfma_f32_16x16x32_bf16 v[24:27], v[152:155], v[202:205], v[24:27]
	v_mfma_f32_16x16x32_bf16 v[20:23], v[144:147], v[210:213], v[20:23]
	v_mfma_f32_16x16x32_bf16 v[16:19], v[152:155], v[210:213], v[16:19]
	v_mfma_f32_16x16x32_bf16 v[60:63], v[148:151], v[190:193], v[60:63]
	v_mfma_f32_16x16x32_bf16 v[56:59], v[156:159], v[190:193], v[56:59]
	v_mfma_f32_16x16x32_bf16 v[52:55], v[148:151], v[198:201], v[52:55]
	v_mfma_f32_16x16x32_bf16 v[48:51], v[156:159], v[198:201], v[48:51]
	v_mfma_f32_16x16x32_bf16 v[28:31], v[148:151], v[206:209], v[28:31]
	v_mfma_f32_16x16x32_bf16 v[24:27], v[156:159], v[206:209], v[24:27]
	v_mfma_f32_16x16x32_bf16 v[20:23], v[148:151], v[214:217], v[20:23]
	v_mfma_f32_16x16x32_bf16 v[16:19], v[156:159], v[214:217], v[16:19]
	s_setprio 0
	s_setprio 1
	v_mfma_f32_16x16x32_bf16 v[44:47], v[162:165], v[186:189], v[44:47]
	v_mfma_f32_16x16x32_bf16 v[40:43], v[178:181], v[186:189], v[40:43]
	v_mfma_f32_16x16x32_bf16 v[36:39], v[162:165], v[194:197], v[36:39]
	v_mfma_f32_16x16x32_bf16 v[32:35], v[178:181], v[194:197], v[32:35]
	v_mfma_f32_16x16x32_bf16 v[12:15], v[162:165], v[202:205], v[12:15]
	v_mfma_f32_16x16x32_bf16 v[8:11], v[178:181], v[202:205], v[8:11]
	v_mfma_f32_16x16x32_bf16 v[4:7], v[162:165], v[210:213], v[4:7]
	v_mfma_f32_16x16x32_bf16 v[0:3], v[178:181], v[210:213], v[0:3]
	v_mfma_f32_16x16x32_bf16 v[44:47], v[174:177], v[190:193], v[44:47]
	v_mfma_f32_16x16x32_bf16 v[40:43], v[182:185], v[190:193], v[40:43]
	v_mfma_f32_16x16x32_bf16 v[36:39], v[174:177], v[198:201], v[36:39]
	v_mfma_f32_16x16x32_bf16 v[32:35], v[182:185], v[198:201], v[32:35]
	v_mfma_f32_16x16x32_bf16 v[12:15], v[174:177], v[206:209], v[12:15]
	v_mfma_f32_16x16x32_bf16 v[8:11], v[182:185], v[206:209], v[8:11]
	v_mfma_f32_16x16x32_bf16 v[4:7], v[174:177], v[214:217], v[4:7]
	v_mfma_f32_16x16x32_bf16 v[0:3], v[182:185], v[214:217], v[0:3]
	s_setprio 0
	s_barrier
	s_add_i32 s59, 0, 0x18000
	s_add_i32 s60, 0, 0x1c000
	v_add_u32_e32 v156, s59, v169
	v_add_u32_e32 v173, 0x19000, v169
	ds_read_b128 v[144:147], v156
	ds_read_b128 v[148:151], v156 offset:1024
	ds_read_b128 v[152:155], v156 offset:2048
	ds_read_b128 v[156:159], v156 offset:3072
	ds_read_b128 v[162:165], v173
	ds_read_b128 v[174:177], v173 offset:1024
	ds_read_b128 v[178:181], v173 offset:2048
	ds_read_b128 v[182:185], v173 offset:3072
	s_add_u32 s38, s38, 0x80000
	s_addc_u32 s39, s39, 0
	s_mov_b32 m0, s45
	v_lshl_add_u64 v[224:225], s[38:39], 0, v[128:129]
	ds_read_b128 v[186:189], v172 offset:32768
	ds_read_b128 v[190:193], v172 offset:33792
	ds_read_b128 v[194:197], v172 offset:34816
	ds_read_b128 v[198:201], v172 offset:35840
	ds_read_b128 v[202:205], v172 offset:36864
	ds_read_b128 v[206:209], v172 offset:37888
	ds_read_b128 v[210:213], v172 offset:38912
	ds_read_b128 v[214:217], v172 offset:39936
	global_load_lds_dwordx4 v[224:225], off
	v_lshl_add_u64 v[224:225], s[38:39], 0, v[132:133]
	s_mov_b32 m0, s46
	s_nop 0
	global_load_lds_dwordx4 v[224:225], off
	s_waitcnt vmcnt(8)
	s_waitcnt lgkmcnt(0)
	s_barrier
	s_setprio 1
	s_waitcnt lgkmcnt(0)
	v_mfma_f32_16x16x32_bf16 v[120:123], v[144:147], v[186:189], v[120:123]
	v_mfma_f32_16x16x32_bf16 v[124:127], v[152:155], v[186:189], v[124:127]
	v_mfma_f32_16x16x32_bf16 v[112:115], v[144:147], v[194:197], v[112:115]
	v_mfma_f32_16x16x32_bf16 v[116:119], v[152:155], v[194:197], v[116:119]
	v_mfma_f32_16x16x32_bf16 v[92:95], v[144:147], v[202:205], v[92:95]
	v_mfma_f32_16x16x32_bf16 v[88:91], v[152:155], v[202:205], v[88:91]
	v_mfma_f32_16x16x32_bf16 v[84:87], v[144:147], v[210:213], v[84:87]
	v_mfma_f32_16x16x32_bf16 v[80:83], v[152:155], v[210:213], v[80:83]
	v_mfma_f32_16x16x32_bf16 v[120:123], v[148:151], v[190:193], v[120:123]
	v_mfma_f32_16x16x32_bf16 v[124:127], v[156:159], v[190:193], v[124:127]
	v_mfma_f32_16x16x32_bf16 v[112:115], v[148:151], v[198:201], v[112:115]
	v_mfma_f32_16x16x32_bf16 v[116:119], v[156:159], v[198:201], v[116:119]
	v_mfma_f32_16x16x32_bf16 v[92:95], v[148:151], v[206:209], v[92:95]
	v_mfma_f32_16x16x32_bf16 v[88:91], v[156:159], v[206:209], v[88:91]
	v_mfma_f32_16x16x32_bf16 v[84:87], v[148:151], v[214:217], v[84:87]
	v_mfma_f32_16x16x32_bf16 v[80:83], v[156:159], v[214:217], v[80:83]
	s_setprio 0
	s_setprio 1
	v_mfma_f32_16x16x32_bf16 v[108:111], v[162:165], v[186:189], v[108:111]
	v_mfma_f32_16x16x32_bf16 v[104:107], v[178:181], v[186:189], v[104:107]
	v_mfma_f32_16x16x32_bf16 v[100:103], v[162:165], v[194:197], v[100:103]
	v_mfma_f32_16x16x32_bf16 v[96:99], v[178:181], v[194:197], v[96:99]
	v_mfma_f32_16x16x32_bf16 v[76:79], v[162:165], v[202:205], v[76:79]
	v_mfma_f32_16x16x32_bf16 v[72:75], v[178:181], v[202:205], v[72:75]
	v_mfma_f32_16x16x32_bf16 v[68:71], v[162:165], v[210:213], v[68:71]
	v_mfma_f32_16x16x32_bf16 v[64:67], v[178:181], v[210:213], v[64:67]
	v_mfma_f32_16x16x32_bf16 v[108:111], v[174:177], v[190:193], v[108:111]
	v_mfma_f32_16x16x32_bf16 v[104:107], v[182:185], v[190:193], v[104:107]
	v_mfma_f32_16x16x32_bf16 v[100:103], v[174:177], v[198:201], v[100:103]
	v_mfma_f32_16x16x32_bf16 v[96:99], v[182:185], v[198:201], v[96:99]
	v_mfma_f32_16x16x32_bf16 v[76:79], v[174:177], v[206:209], v[76:79]
	v_mfma_f32_16x16x32_bf16 v[72:75], v[182:185], v[206:209], v[72:75]
	v_mfma_f32_16x16x32_bf16 v[68:71], v[174:177], v[214:217], v[68:71]
	v_mfma_f32_16x16x32_bf16 v[64:67], v[182:185], v[214:217], v[64:67]
	s_setprio 0
	s_barrier
; #define PG8_STAGE(bufoff, gbase, voff) do { _Pragma("unroll") for (int _i = 0; _i < 2; ++_i) \
;         __builtin_amdgcn_global_load_lds((const unsigned*)((const char*)(gbase) + (voff)[_i]), (PG8_LAS unsigned*)(lds + (bufoff) + ldsw + _i * 8192), 16, 0, 0); } while (0)
; #define PG8_LDA(dst, b, h) do { _Pragma("unroll") for (int m = 0; m < 4; ++m) _Pragma("unroll") for (int k = 0; k < 2; ++k) dst[m][k] = *(const PG8_LAS bf16x8*)(lds + PG8_SA(b, h) + aoff + m * 2048 + k * 1024); } while (0)
; #define PG8_MMA(ai, bj, At, Bt) do { __builtin_amdgcn_s_setprio(1); _Pragma("unroll") for (int m = 0; m < 4; ++m) _Pragma("unroll") for (int n = 0; n < 2; ++n) _Pragma("unroll") for (int k = 0; k < 2; ++k) \
;         acc[ai][bj][m][n] = __builtin_amdgcn_mfma_f32_16x16x32_bf16(Bt[n][k], At[m][k], acc[ai][bj][m][n], 0, 0, 0); __builtin_amdgcn_s_setprio(0); } while (0)
; template <class Epi, class Sched, bool ALIGN_EPI = false, bool SP2 = false>
; __device__ __forceinline__ void gemm_phase(PG8_LAS unsigned char* lds, const Gemm g, const Sched& S, const Epi& E) {
;     ...
;             PG8_WAIT_V(8); PG8_WAIT_L(0); PG8_BAR; PG8_MMA(0, 0, At, B0); PG8_MMA(0, 1, At, B1); PG8_BAR; PG8_SCHED;
;             PG8_LDA(At, 1, 1); PG8_STAGE(PG8_SB(1, 0), b3, voffB); PG8_STAGE(PG8_SB(1, 1), b3 + hstep, voffB); PG8_STAGE(PG8_SA(1, 0), a3, voffA);
;             PG8_WAIT_V(8); PG8_WAIT_L(0); PG8_BAR; PG8_MMA(1, 0, At, B0); PG8_MMA(1, 1, At, B1); PG8_BAR; PG8_SCHED;
;     __device__ __forceinline__ void operator()(const f32x4 (&acc)[2][2][4][2], const pg8::Unit& u, int wr, int wc, int fr, int fq) const {
;     ...
;         const int b = (u.pm * 256) >> 14;
;         f32x4 gt[2][2];
; #pragma unroll
;         for (int bj = 0; bj < 2; ++bj)
; #pragma unroll
;             for (int n = 0; n < 2; ++n) gt[bj][n] = *(const f32x4*)(MOD + b * 6144 + 4096 + col0 + bj * 128 + 4 * n) + *(const f32x4*)(b_mod + 4096 + col0 + bj * 128 + 4 * n);
; #pragma unroll
;         for (int ai = 0; ai < 2; ++ai)
; #pragma unroll
;           for (int mp = 0; mp < 2; ++mp) {
;             f32x4 xb[2][2][2];
; #pragma unroll
;             for (int mm = 0; mm < 2; ++mm)
; #pragma unroll
;                 for (int bj = 0; bj < 2; ++bj)
; #pragma unroll
;                     for (int n = 0; n < 2; ++n) xb[mm][bj][n] = *(const f32x4*)(x + (size_t)(row0 + ai * 128 + (mp * 2 + mm) * 16) * 2048 + col0 + bj * 128 + 4 * n);
	s_add_i32 s38, s59, s43
	v_lshl_add_u64 v[166:167], v[166:167], 0, s[12:13]
	s_mov_b32 m0, s38
	ds_read_b128 v[186:189], v172 offset:49152
	ds_read_b128 v[190:193], v172 offset:50176
	ds_read_b128 v[194:197], v172 offset:51200
	ds_read_b128 v[198:201], v172 offset:52224
	ds_read_b128 v[202:205], v172 offset:53248
	ds_read_b128 v[206:209], v172 offset:54272
	ds_read_b128 v[210:213], v172 offset:55296
	ds_read_b128 v[214:217], v172 offset:56320
	global_load_lds_dwordx4 v[166:167], off
	s_add_i32 m0, s38, 0x2000
	s_add_u32 s36, s36, 0x80080
	v_lshl_add_u64 v[166:167], v[218:219], 0, s[12:13]
	s_addc_u32 s37, s37, 0
	s_add_i32 s38, s60, s43
	global_load_lds_dwordx4 v[166:167], off
	v_lshl_add_u64 v[166:167], s[36:37], 0, v[130:131]
	s_mov_b32 m0, s38
	s_nop 0
	global_load_lds_dwordx4 v[166:167], off
	v_lshl_add_u64 v[166:167], s[36:37], 0, v[134:135]
	s_add_i32 m0, s38, 0x2000
	s_nop 0
	global_load_lds_dwordx4 v[166:167], off
	v_lshl_add_u64 v[166:167], v[220:221], 0, s[12:13]
	s_mov_b32 m0, s50
	s_nop 0
	global_load_lds_dwordx4 v[166:167], off
	v_lshl_add_u64 v[166:167], v[222:223], 0, s[12:13]
	s_mov_b32 m0, s51
	s_nop 0
	global_load_lds_dwordx4 v[166:167], off
	s_waitcnt vmcnt(8)
	s_waitcnt lgkmcnt(0)
	s_barrier
	s_setprio 1
	s_waitcnt lgkmcnt(0)
	v_mfma_f32_16x16x32_bf16 v[60:63], v[144:147], v[186:189], v[60:63]
	v_mfma_f32_16x16x32_bf16 v[56:59], v[152:155], v[186:189], v[56:59]
	v_mfma_f32_16x16x32_bf16 v[52:55], v[144:147], v[194:197], v[52:55]
	v_mfma_f32_16x16x32_bf16 v[48:51], v[152:155], v[194:197], v[48:51]
	v_mfma_f32_16x16x32_bf16 v[28:31], v[144:147], v[202:205], v[28:31]
	v_mfma_f32_16x16x32_bf16 v[24:27], v[152:155], v[202:205], v[24:27]
	v_mfma_f32_16x16x32_bf16 v[20:23], v[144:147], v[210:213], v[20:23]
	v_mfma_f32_16x16x32_bf16 v[16:19], v[152:155], v[210:213], v[16:19]
	v_mfma_f32_16x16x32_bf16 v[60:63], v[148:151], v[190:193], v[60:63]
	v_mfma_f32_16x16x32_bf16 v[56:59], v[156:159], v[190:193], v[56:59]
	v_mfma_f32_16x16x32_bf16 v[52:55], v[148:151], v[198:201], v[52:55]
	v_mfma_f32_16x16x32_bf16 v[48:51], v[156:159], v[198:201], v[48:51]
	v_mfma_f32_16x16x32_bf16 v[28:31], v[148:151], v[206:209], v[28:31]
	v_mfma_f32_16x16x32_bf16 v[24:27], v[156:159], v[206:209], v[24:27]
	v_mfma_f32_16x16x32_bf16 v[20:23], v[148:151], v[214:217], v[20:23]
	v_mfma_f32_16x16x32_bf16 v[16:19], v[156:159], v[214:217], v[16:19]
	s_setprio 0
	s_setprio 1
	v_mfma_f32_16x16x32_bf16 v[44:47], v[162:165], v[186:189], v[44:47]
	v_mfma_f32_16x16x32_bf16 v[40:43], v[178:181], v[186:189], v[40:43]
	v_mfma_f32_16x16x32_bf16 v[36:39], v[162:165], v[194:197], v[36:39]
	v_mfma_f32_16x16x32_bf16 v[32:35], v[178:181], v[194:197], v[32:35]
	v_mfma_f32_16x16x32_bf16 v[12:15], v[162:165], v[202:205], v[12:15]
	v_mfma_f32_16x16x32_bf16 v[8:11], v[178:181], v[202:205], v[8:11]
	v_mfma_f32_16x16x32_bf16 v[4:7], v[162:165], v[210:213], v[4:7]
	v_mfma_f32_16x16x32_bf16 v[0:3], v[178:181], v[210:213], v[0:3]
	v_mfma_f32_16x16x32_bf16 v[44:47], v[174:177], v[190:193], v[44:47]
	v_mfma_f32_16x16x32_bf16 v[40:43], v[182:185], v[190:193], v[40:43]
	v_mfma_f32_16x16x32_bf16 v[36:39], v[174:177], v[198:201], v[36:39]
	v_mfma_f32_16x16x32_bf16 v[32:35], v[182:185], v[198:201], v[32:35]
	v_mfma_f32_16x16x32_bf16 v[12:15], v[174:177], v[206:209], v[12:15]
	v_mfma_f32_16x16x32_bf16 v[8:11], v[182:185], v[206:209], v[8:11]
	v_mfma_f32_16x16x32_bf16 v[4:7], v[174:177], v[214:217], v[4:7]
	v_mfma_f32_16x16x32_bf16 v[0:3], v[182:185], v[214:217], v[0:3]
	s_setprio 0
	s_barrier
	s_add_i32 s58, s58, 2
	s_add_u32 s34, s34, 0x100
	s_addc_u32 s35, s35, 0
	s_add_u32 s56, s56, 0x100
	s_addc_u32 s57, s57, 0
	s_cmp_gt_u32 s58, 29
	s_cbranch_scc0 .LBB0_943
	s_and_b64 vcc, exec, s[14:15]
	s_cbranch_vccz .LBB0_946
	s_barrier
.LBB0_946:
	v_lshl_or_b32 v144, s1, 8, v170
	s_lshr_b32 s1, s30, 6
	s_mul_i32 s34, s1, 0x1800
	s_ashr_i32 s35, s34, 31
	s_lshl_b64 s[34:35], s[34:35], 2
	s_add_u32 s34, s94, s34
	v_ashrrev_i32_e32 v145, 31, v144
	v_lshl_add_u32 v166, s30, 8, v168
	s_addc_u32 s35, s95, s35
	v_lshlrev_b64 v[146:147], 2, v[144:145]
	v_ashrrev_i32_e32 v167, 31, v166
	v_lshl_add_u64 v[162:163], s[34:35], 0, v[146:147]
	v_lshl_add_u64 v[210:211], s[18:19], 0, v[146:147]
	v_lshl_add_u64 v[164:165], s[76:77], 0, v[146:147]
	v_lshlrev_b64 v[146:147], 13, v[166:167]
	v_lshl_add_u64 v[146:147], v[164:165], 0, v[146:147]
	global_load_dwordx4 v[148:151], v[210:211], off offset:16 nt
	global_load_dwordx4 v[152:155], v[146:147], off offset:16 nt
	global_load_dwordx4 v[156:159], v[146:147], off nt
	global_load_dwordx4 v[174:177], v[146:147], off offset:144 nt
	global_load_dwordx4 v[178:181], v[146:147], off offset:128 nt
	v_or_b32_e32 v146, 16, v166
	v_ashrrev_i32_e32 v147, 31, v146
	v_lshlrev_b64 v[182:183], 13, v[146:147]
	v_lshl_add_u64 v[222:223], v[164:165], 0, v[182:183]
	v_lshl_add_u64 v[206:207], v[162:163], 0, s[16:17]
	global_load_dwordx4 v[182:185], v[222:223], off offset:16 nt
	global_load_dwordx4 v[186:189], v[222:223], off nt
	global_load_dwordx4 v[190:193], v[206:207], off offset:16 nt
	global_load_dwordx4 v[194:197], v[206:207], off offset:128 nt
	global_load_dwordx4 v[198:201], v[210:211], off offset:144 nt
	global_load_dwordx4 v[202:205], v[210:211], off offset:128 nt
	v_add_co_u32_e32 v162, vcc, s49, v162
	v_lshlrev_b64 v[144:145], 1, v[144:145]
	s_nop 0
	v_addc_co_u32_e32 v163, vcc, 0, v163, vcc
	global_load_dwordx4 v[206:209], v[206:207], off offset:144 nt
	s_nop 0
	global_load_dwordx4 v[210:213], v[210:211], off nt
	s_nop 0
	global_load_dwordx4 v[214:217], v[162:163], off nt
	global_load_dwordx4 v[218:221], v[222:223], off offset:128 nt
	s_nop 0
	global_load_dwordx4 v[222:225], v[222:223], off offset:144 nt
	v_lshlrev_b64 v[162:163], 12, v[166:167]
	v_lshl_add_u64 v[162:163], s[10:11], 0, v[162:163]
	v_lshlrev_b64 v[226:227], 12, v[146:147]
	v_lshl_add_u64 v[228:229], v[162:163], 0, v[144:145]
	s_andn2_b64 vcc, exec, s[4:5]
	s_mov_b64 s[4:5], -1
	s_waitcnt vmcnt(0)
; __device__ __forceinline__ unsigned pkh2(float lo, float hi) { const f32x2 v = {lo, hi}; const f16x2_t h = __builtin_convertvector(v, f16x2_t); return __builtin_bit_cast(unsigned, h); }
;     __device__ __forceinline__ void operator()(const f32x4 (&acc)[2][2][4][2], const pg8::Unit& u, int wr, int wc, int fr, int fq) const {
;     ...
;         for (int ai = 0; ai < 2; ++ai)
; #pragma unroll
;           for (int mp = 0; mp < 2; ++mp) {
;             f32x4 xb[2][2][2];
; #pragma unroll
;             for (int mm = 0; mm < 2; ++mm)
; #pragma unroll
;                 for (int bj = 0; bj < 2; ++bj)
; #pragma unroll
;                     for (int n = 0; n < 2; ++n) xb[mm][bj][n] = *(const f32x4*)(x + (size_t)(row0 + ai * 128 + (mp * 2 + mm) * 16) * 2048 + col0 + bj * 128 + 4 * n);
;             asm volatile("" ::: "memory");
; #pragma unroll
;             for (int mm = 0; mm < 2; ++mm) { const int m = mp * 2 + mm; const size_t ro = (size_t)(row0 + ai * 128 + m * 16) * 2048 + col0;
; #pragma unroll
;                 for (int bj = 0; bj < 2; ++bj) {
;                     const f32x4 v0 = xb[mm][bj][0] * 1.189207115002721f + gt[bj][0] * acc[ai][bj][m][0], v1 = xb[mm][bj][1] * 1.189207115002721f + gt[bj][1] * acc[ai][bj][m][1];
;                     u32x4 w; w.x = pkh2(v0[0], v0[1]); w.y = pkh2(v0[2], v0[3]); w.z = pkh2(v1[0], v1[1]); w.w = pkh2(v1[2], v1[3]);
;                     *(u32x4*)(out + ro + bj * 128) = w; } }
	v_pk_mul_f32 v[234:235], v[154:155], s[20:21] op_sel_hi:[1,0]
	v_pk_mul_f32 v[230:231], v[158:159], s[20:21] op_sel_hi:[1,0]
	v_pk_mul_f32 v[232:233], v[156:157], s[20:21] op_sel_hi:[1,0]
	v_pk_mul_f32 v[236:237], v[152:153], s[20:21] op_sel_hi:[1,0]
	v_pk_mul_f32 v[180:181], v[180:181], s[20:21] op_sel_hi:[1,0]
	v_pk_mul_f32 v[178:179], v[178:179], s[20:21] op_sel_hi:[1,0]
	v_pk_mul_f32 v[176:177], v[176:177], s[20:21] op_sel_hi:[1,0]
	v_pk_mul_f32 v[174:175], v[174:175], s[20:21] op_sel_hi:[1,0]
	v_pk_add_f32 v[146:147], v[192:193], v[150:151]
	v_pk_add_f32 v[148:149], v[190:191], v[148:149]
	v_pk_add_f32 v[150:151], v[196:197], v[204:205]
	v_pk_add_f32 v[152:153], v[194:195], v[202:203]
	v_pk_add_f32 v[154:155], v[208:209], v[200:201]
	v_pk_add_f32 v[156:157], v[206:207], v[198:199]
	v_pk_add_f32 v[158:159], v[216:217], v[212:213]
	v_pk_add_f32 v[162:163], v[214:215], v[210:211]
	v_pk_fma_f32 v[126:127], v[126:127], v[146:147], v[234:235]
	v_pk_fma_f32 v[124:125], v[124:125], v[148:149], v[236:237]
	v_pk_fma_f32 v[110:111], v[110:111], v[150:151], v[180:181]
	v_pk_fma_f32 v[108:109], v[108:109], v[152:153], v[178:179]
	v_pk_fma_f32 v[176:177], v[106:107], v[154:155], v[176:177]
	v_pk_fma_f32 v[104:105], v[104:105], v[156:157], v[174:175]
	v_pk_fma_f32 v[122:123], v[122:123], v[158:159], v[230:231]
	v_pk_fma_f32 v[120:121], v[120:121], v[162:163], v[232:233]
	v_cvt_pk_f16_f32 v106, v124, v125
	v_cvt_pk_f16_f32 v107, v126, v127
	v_cvt_pk_f16_f32 v108, v108, v109
	v_cvt_pk_f16_f32 v109, v110, v111
	v_cvt_pk_f16_f32 v110, v104, v105
	v_cvt_pk_f16_f32 v111, v176, v177
	v_cvt_pk_f16_f32 v104, v120, v121
	v_cvt_pk_f16_f32 v105, v122, v123
	global_store_dwordx4 v[228:229], v[108:111], off offset:64
	global_store_dwordx4 v[228:229], v[104:107], off
	v_pk_mul_f32 v[188:189], v[188:189], s[20:21] op_sel_hi:[1,0]
	v_pk_mul_f32 v[108:109], v[218:219], s[20:21] op_sel_hi:[1,0]
	v_pk_mul_f32 v[106:107], v[220:221], s[20:21] op_sel_hi:[1,0]
	v_pk_fma_f32 v[100:101], v[100:101], v[152:153], v[108:109]
	v_pk_fma_f32 v[102:103], v[102:103], v[150:151], v[106:107]
	v_pk_mul_f32 v[106:107], v[224:225], s[20:21] op_sel_hi:[1,0]
	v_pk_mul_f32 v[108:109], v[222:223], s[20:21] op_sel_hi:[1,0]
	v_pk_mul_f32 v[186:187], v[186:187], s[20:21] op_sel_hi:[1,0]
	v_pk_mul_f32 v[184:185], v[184:185], s[20:21] op_sel_hi:[1,0]
	v_pk_mul_f32 v[182:183], v[182:183], s[20:21] op_sel_hi:[1,0]
	v_lshl_add_u64 v[104:105], s[10:11], 0, v[226:227]
	v_pk_fma_f32 v[106:107], v[98:99], v[154:155], v[106:107]
	v_pk_fma_f32 v[98:99], v[96:97], v[156:157], v[108:109]
	v_or_b32_e32 v174, 32, v166
	v_pk_fma_f32 v[118:119], v[118:119], v[146:147], v[184:185]
	v_pk_fma_f32 v[116:117], v[116:117], v[148:149], v[182:183]
	v_pk_fma_f32 v[114:115], v[114:115], v[158:159], v[188:189]
	v_pk_fma_f32 v[124:125], v[112:113], v[162:163], v[186:187]
	v_lshl_add_u64 v[104:105], v[104:105], 0, v[144:145]
	v_cvt_pk_f16_f32 v96, v100, v101
	v_cvt_pk_f16_f32 v97, v102, v103
	v_cvt_pk_f16_f32 v98, v98, v99
	v_cvt_pk_f16_f32 v99, v106, v107
	v_ashrrev_i32_e32 v175, 31, v174
	v_or_b32_e32 v176, 48, v166
	v_cvt_pk_f16_f32 v112, v116, v117
	v_cvt_pk_f16_f32 v110, v124, v125
	v_cvt_pk_f16_f32 v111, v114, v115
	v_cvt_pk_f16_f32 v113, v118, v119
	global_store_dwordx4 v[104:105], v[96:99], off offset:64
	v_ashrrev_i32_e32 v177, 31, v176
	global_store_dwordx4 v[104:105], v[110:113], off
	v_lshlrev_b64 v[96:97], 13, v[174:175]
	v_lshl_add_u64 v[108:109], v[164:165], 0, v[96:97]
	v_lshlrev_b64 v[112:113], 13, v[176:177]
	global_load_dwordx4 v[96:99], v[108:109], off nt
	global_load_dwordx4 v[100:103], v[108:109], off offset:16 nt
	global_load_dwordx4 v[104:107], v[108:109], off offset:144 nt
	s_nop 0
	global_load_dwordx4 v[108:111], v[108:109], off offset:128 nt
	v_lshl_add_u64 v[124:125], v[164:165], 0, v[112:113]
	global_load_dwordx4 v[112:115], v[124:125], off nt
	global_load_dwordx4 v[116:119], v[124:125], off offset:16 nt
	global_load_dwordx4 v[120:123], v[124:125], off offset:128 nt
	s_nop 0
	global_load_dwordx4 v[124:127], v[124:125], off offset:144 nt
	v_lshlrev_b64 v[174:175], 12, v[174:175]
	v_lshlrev_b64 v[176:177], 12, v[176:177]
	v_lshl_add_u64 v[174:175], s[10:11], 0, v[174:175]
	v_lshl_add_u64 v[176:177], s[10:11], 0, v[176:177]
	v_lshl_add_u64 v[174:175], v[174:175], 0, v[144:145]
	v_lshl_add_u64 v[176:177], v[176:177], 0, v[144:145]
	s_waitcnt vmcnt(7)
	v_pk_mul_f32 v[98:99], v[98:99], s[20:21] op_sel_hi:[1,0]
	v_pk_mul_f32 v[96:97], v[96:97], s[20:21] op_sel_hi:[1,0]
	s_waitcnt vmcnt(6)
	v_pk_mul_f32 v[102:103], v[102:103], s[20:21] op_sel_hi:[1,0]
	v_pk_mul_f32 v[100:101], v[100:101], s[20:21] op_sel_hi:[1,0]
	s_waitcnt vmcnt(4)
	v_pk_mul_f32 v[110:111], v[110:111], s[20:21] op_sel_hi:[1,0]
	v_pk_mul_f32 v[108:109], v[108:109], s[20:21] op_sel_hi:[1,0]
	v_pk_mul_f32 v[106:107], v[106:107], s[20:21] op_sel_hi:[1,0]
	v_pk_mul_f32 v[104:105], v[104:105], s[20:21] op_sel_hi:[1,0]
	s_waitcnt vmcnt(3)
	v_pk_mul_f32 v[114:115], v[114:115], s[20:21] op_sel_hi:[1,0]
	v_pk_mul_f32 v[112:113], v[112:113], s[20:21] op_sel_hi:[1,0]
	s_waitcnt vmcnt(2)
	v_pk_mul_f32 v[118:119], v[118:119], s[20:21] op_sel_hi:[1,0]
	v_pk_mul_f32 v[116:117], v[116:117], s[20:21] op_sel_hi:[1,0]
	s_waitcnt vmcnt(1)
; __device__ __forceinline__ unsigned pkh2(float lo, float hi) { const f32x2 v = {lo, hi}; const f16x2_t h = __builtin_convertvector(v, f16x2_t); return __builtin_bit_cast(unsigned, h); }
;     __device__ __forceinline__ void operator()(const f32x4 (&acc)[2][2][4][2], const pg8::Unit& u, int wr, int wc, int fr, int fq) const {
;     ...
;                     for (int n = 0; n < 2; ++n) xb[mm][bj][n] = *(const f32x4*)(x + (size_t)(row0 + ai * 128 + (mp * 2 + mm) * 16) * 2048 + col0 + bj * 128 + 4 * n);
;             asm volatile("" ::: "memory");
; #pragma unroll
;             for (int mm = 0; mm < 2; ++mm) { const int m = mp * 2 + mm; const size_t ro = (size_t)(row0 + ai * 128 + m * 16) * 2048 + col0;
; #pragma unroll
;                 for (int bj = 0; bj < 2; ++bj) {
;                     const f32x4 v0 = xb[mm][bj][0] * 1.189207115002721f + gt[bj][0] * acc[ai][bj][m][0], v1 = xb[mm][bj][1] * 1.189207115002721f + gt[bj][1] * acc[ai][bj][m][1];
;                     u32x4 w; w.x = pkh2(v0[0], v0[1]); w.y = pkh2(v0[2], v0[3]); w.z = pkh2(v1[0], v1[1]); w.w = pkh2(v1[2], v1[3]);
;                     *(u32x4*)(out + ro + bj * 128) = w; } }
	v_pk_mul_f32 v[122:123], v[122:123], s[20:21] op_sel_hi:[1,0]
	v_pk_mul_f32 v[120:121], v[120:121], s[20:21] op_sel_hi:[1,0]
	v_pk_fma_f32 v[94:95], v[94:95], v[158:159], v[98:99]
	v_pk_fma_f32 v[92:93], v[92:93], v[162:163], v[96:97]
	v_pk_fma_f32 v[90:91], v[90:91], v[146:147], v[102:103]
	v_pk_fma_f32 v[88:89], v[88:89], v[148:149], v[100:101]
	v_pk_fma_f32 v[78:79], v[78:79], v[150:151], v[110:111]
	v_pk_fma_f32 v[76:77], v[76:77], v[152:153], v[108:109]
	v_pk_fma_f32 v[96:97], v[74:75], v[154:155], v[106:107]
	v_pk_fma_f32 v[74:75], v[72:73], v[156:157], v[104:105]
	v_pk_fma_f32 v[86:87], v[86:87], v[158:159], v[114:115]
	v_pk_fma_f32 v[84:85], v[84:85], v[162:163], v[112:113]
	v_pk_fma_f32 v[82:83], v[82:83], v[146:147], v[118:119]
	v_pk_fma_f32 v[80:81], v[80:81], v[148:149], v[116:117]
	v_pk_fma_f32 v[98:99], v[70:71], v[150:151], v[122:123]
	v_pk_fma_f32 v[100:101], v[68:69], v[152:153], v[120:121]
	v_cvt_pk_f16_f32 v68, v92, v93
	v_cvt_pk_f16_f32 v69, v94, v95
	v_cvt_pk_f16_f32 v70, v88, v89
	v_cvt_pk_f16_f32 v71, v90, v91
	s_waitcnt vmcnt(0)
	v_pk_mul_f32 v[126:127], v[126:127], s[20:21] op_sel_hi:[1,0]
	v_cvt_pk_f16_f32 v72, v76, v77
	v_cvt_pk_f16_f32 v73, v78, v79
	v_cvt_pk_f16_f32 v74, v74, v75
	v_cvt_pk_f16_f32 v75, v96, v97
	v_cvt_pk_f16_f32 v76, v84, v85
	v_cvt_pk_f16_f32 v77, v86, v87
	v_cvt_pk_f16_f32 v78, v80, v81
	v_cvt_pk_f16_f32 v79, v82, v83
	global_store_dwordx4 v[174:175], v[68:71], off
	global_store_dwordx4 v[174:175], v[72:75], off offset:64
	global_store_dwordx4 v[176:177], v[76:79], off
	v_pk_mul_f32 v[68:69], v[124:125], s[20:21] op_sel_hi:[1,0]
	v_pk_fma_f32 v[70:71], v[66:67], v[154:155], v[126:127]
	v_pk_fma_f32 v[66:67], v[64:65], v[156:157], v[68:69]
	v_add_u32_e32 v96, 0x80, v166
	v_cvt_pk_f16_f32 v64, v100, v101
	v_cvt_pk_f16_f32 v65, v98, v99
	v_cvt_pk_f16_f32 v66, v66, v67
	v_cvt_pk_f16_f32 v67, v70, v71
	v_ashrrev_i32_e32 v97, 31, v96
	v_add_u32_e32 v98, 0x90, v166
	global_store_dwordx4 v[176:177], v[64:67], off offset:64
	v_ashrrev_i32_e32 v99, 31, v98
	v_lshlrev_b64 v[80:81], 13, v[98:99]
	v_lshlrev_b64 v[64:65], 13, v[96:97]
	v_lshl_add_u64 v[76:77], v[164:165], 0, v[64:65]
	global_load_dwordx4 v[64:67], v[76:77], off nt
	global_load_dwordx4 v[68:71], v[76:77], off offset:16 nt
	global_load_dwordx4 v[72:75], v[76:77], off offset:144 nt
	s_nop 0
	global_load_dwordx4 v[76:79], v[76:77], off offset:128 nt
	v_lshl_add_u64 v[92:93], v[164:165], 0, v[80:81]
	global_load_dwordx4 v[80:83], v[92:93], off nt
	global_load_dwordx4 v[84:87], v[92:93], off offset:16 nt
	global_load_dwordx4 v[88:91], v[92:93], off offset:128 nt
	s_nop 0
	global_load_dwordx4 v[92:95], v[92:93], off offset:144 nt
	v_lshlrev_b64 v[96:97], 12, v[96:97]
	v_add_u32_e32 v100, 0xa0, v166
	v_lshlrev_b64 v[98:99], 12, v[98:99]
	v_lshl_add_u64 v[96:97], s[10:11], 0, v[96:97]
	v_lshl_add_u64 v[98:99], s[10:11], 0, v[98:99]
	v_lshl_add_u64 v[96:97], v[96:97], 0, v[144:145]
	v_ashrrev_i32_e32 v101, 31, v100
	v_lshl_add_u64 v[98:99], v[98:99], 0, v[144:145]
	s_waitcnt vmcnt(7)
	v_pk_mul_f32 v[64:65], v[64:65], s[20:21] op_sel_hi:[1,0]
	v_pk_mul_f32 v[66:67], v[66:67], s[20:21] op_sel_hi:[1,0]
	s_waitcnt vmcnt(6)
	v_pk_mul_f32 v[70:71], v[70:71], s[20:21] op_sel_hi:[1,0]
	s_waitcnt vmcnt(4)
	v_pk_mul_f32 v[76:77], v[76:77], s[20:21] op_sel_hi:[1,0]
	s_waitcnt vmcnt(1)
	v_pk_mul_f32 v[90:91], v[90:91], s[20:21] op_sel_hi:[1,0]
	v_pk_mul_f32 v[68:69], v[68:69], s[20:21] op_sel_hi:[1,0]
	v_pk_mul_f32 v[88:89], v[88:89], s[20:21] op_sel_hi:[1,0]
	v_pk_fma_f32 v[60:61], v[60:61], v[162:163], v[64:65]
	v_pk_fma_f32 v[44:45], v[44:45], v[152:153], v[76:77]
	v_pk_fma_f32 v[64:65], v[38:39], v[150:151], v[90:91]
	v_pk_mul_f32 v[78:79], v[78:79], s[20:21] op_sel_hi:[1,0]
	v_pk_mul_f32 v[74:75], v[74:75], s[20:21] op_sel_hi:[1,0]
	v_pk_mul_f32 v[72:73], v[72:73], s[20:21] op_sel_hi:[1,0]
	v_pk_mul_f32 v[82:83], v[82:83], s[20:21] op_sel_hi:[1,0]
	v_pk_mul_f32 v[80:81], v[80:81], s[20:21] op_sel_hi:[1,0]
	v_pk_mul_f32 v[86:87], v[86:87], s[20:21] op_sel_hi:[1,0]
	v_pk_mul_f32 v[84:85], v[84:85], s[20:21] op_sel_hi:[1,0]
	s_waitcnt vmcnt(0)
; #define PG8_BAR __builtin_amdgcn_s_barrier()
; __device__ __forceinline__ unsigned pkh2(float lo, float hi) { const f32x2 v = {lo, hi}; const f16x2_t h = __builtin_convertvector(v, f16x2_t); return __builtin_bit_cast(unsigned, h); }
; template <class Epi, class Sched, bool ALIGN_EPI = false, bool SP2 = false>
; __device__ __forceinline__ void gemm_phase(PG8_LAS unsigned char* lds, const Gemm g, const Sched& S, const Epi& E) {
;     ...
;         if constexpr (ALIGN_EPI) { if (wr == 1) PG8_BAR; }
;     __device__ __forceinline__ void operator()(const f32x4 (&acc)[2][2][4][2], const pg8::Unit& u, int wr, int wc, int fr, int fq) const {
;     ...
;                     for (int n = 0; n < 2; ++n) xb[mm][bj][n] = *(const f32x4*)(x + (size_t)(row0 + ai * 128 + (mp * 2 + mm) * 16) * 2048 + col0 + bj * 128 + 4 * n);
;             asm volatile("" ::: "memory");
; #pragma unroll
;             for (int mm = 0; mm < 2; ++mm) { const int m = mp * 2 + mm; const size_t ro = (size_t)(row0 + ai * 128 + m * 16) * 2048 + col0;
; #pragma unroll
;                 for (int bj = 0; bj < 2; ++bj) {
;                     const f32x4 v0 = xb[mm][bj][0] * 1.189207115002721f + gt[bj][0] * acc[ai][bj][m][0], v1 = xb[mm][bj][1] * 1.189207115002721f + gt[bj][1] * acc[ai][bj][m][1];
;                     u32x4 w; w.x = pkh2(v0[0], v0[1]); w.y = pkh2(v0[2], v0[3]); w.z = pkh2(v1[0], v1[1]); w.w = pkh2(v1[2], v1[3]);
;                     *(u32x4*)(out + ro + bj * 128) = w; } }
	v_pk_mul_f32 v[94:95], v[94:95], s[20:21] op_sel_hi:[1,0]
	v_pk_mul_f32 v[92:93], v[92:93], s[20:21] op_sel_hi:[1,0]
	v_pk_fma_f32 v[62:63], v[62:63], v[158:159], v[66:67]
	v_pk_fma_f32 v[58:59], v[58:59], v[146:147], v[70:71]
	v_pk_fma_f32 v[56:57], v[56:57], v[148:149], v[68:69]
	v_pk_fma_f32 v[66:67], v[36:37], v[152:153], v[88:89]
	v_cvt_pk_f16_f32 v36, v44, v45
	v_cvt_pk_f16_f32 v45, v64, v65
	v_add_u32_e32 v64, 0xb0, v166
	v_pk_fma_f32 v[46:47], v[46:47], v[150:151], v[78:79]
	v_pk_fma_f32 v[42:43], v[42:43], v[154:155], v[74:75]
	v_pk_fma_f32 v[40:41], v[40:41], v[156:157], v[72:73]
	v_pk_fma_f32 v[54:55], v[54:55], v[158:159], v[82:83]
	v_pk_fma_f32 v[52:53], v[52:53], v[162:163], v[80:81]
	v_pk_fma_f32 v[50:51], v[50:51], v[146:147], v[86:87]
	v_pk_fma_f32 v[48:49], v[48:49], v[148:149], v[84:85]
	v_pk_fma_f32 v[68:69], v[34:35], v[154:155], v[94:95]
	v_pk_fma_f32 v[70:71], v[32:33], v[156:157], v[92:93]
	v_cvt_pk_f16_f32 v32, v60, v61
	v_cvt_pk_f16_f32 v33, v62, v63
	v_cvt_pk_f16_f32 v34, v56, v57
	v_cvt_pk_f16_f32 v35, v58, v59
	v_ashrrev_i32_e32 v65, 31, v64
	v_cvt_pk_f16_f32 v37, v46, v47
	v_cvt_pk_f16_f32 v38, v40, v41
	v_cvt_pk_f16_f32 v39, v42, v43
	v_cvt_pk_f16_f32 v40, v52, v53
	v_cvt_pk_f16_f32 v41, v54, v55
	v_cvt_pk_f16_f32 v42, v48, v49
	v_cvt_pk_f16_f32 v43, v50, v51
	v_cvt_pk_f16_f32 v44, v66, v67
	v_cvt_pk_f16_f32 v46, v70, v71
	v_cvt_pk_f16_f32 v47, v68, v69
	global_store_dwordx4 v[96:97], v[32:35], off
	global_store_dwordx4 v[96:97], v[36:39], off offset:64
	global_store_dwordx4 v[98:99], v[40:43], off
	global_store_dwordx4 v[98:99], v[44:47], off offset:64
	v_lshlrev_b64 v[32:33], 13, v[100:101]
	v_lshlrev_b64 v[48:49], 13, v[64:65]
	v_lshl_add_u64 v[44:45], v[164:165], 0, v[32:33]
	v_lshl_add_u64 v[60:61], v[164:165], 0, v[48:49]
	global_load_dwordx4 v[32:35], v[44:45], off nt
	global_load_dwordx4 v[36:39], v[44:45], off offset:16 nt
	global_load_dwordx4 v[40:43], v[44:45], off offset:144 nt
	s_nop 0
	global_load_dwordx4 v[44:47], v[44:45], off offset:128 nt
	s_nop 0
	global_load_dwordx4 v[48:51], v[60:61], off nt
	global_load_dwordx4 v[52:55], v[60:61], off offset:16 nt
	global_load_dwordx4 v[56:59], v[60:61], off offset:128 nt
	s_nop 0
	global_load_dwordx4 v[60:63], v[60:61], off offset:144 nt
	v_lshlrev_b64 v[66:67], 12, v[100:101]
	v_lshlrev_b64 v[64:65], 12, v[64:65]
	v_lshl_add_u64 v[66:67], s[10:11], 0, v[66:67]
	v_lshl_add_u64 v[64:65], s[10:11], 0, v[64:65]
	v_lshl_add_u64 v[66:67], v[66:67], 0, v[144:145]
	v_lshl_add_u64 v[64:65], v[64:65], 0, v[144:145]
	s_waitcnt vmcnt(7)
	v_pk_mul_f32 v[34:35], v[34:35], s[20:21] op_sel_hi:[1,0]
	v_pk_mul_f32 v[32:33], v[32:33], s[20:21] op_sel_hi:[1,0]
	s_waitcnt vmcnt(6)
	v_pk_mul_f32 v[38:39], v[38:39], s[20:21] op_sel_hi:[1,0]
	v_pk_mul_f32 v[36:37], v[36:37], s[20:21] op_sel_hi:[1,0]
	s_waitcnt vmcnt(4)
	v_pk_mul_f32 v[46:47], v[46:47], s[20:21] op_sel_hi:[1,0]
	v_pk_mul_f32 v[44:45], v[44:45], s[20:21] op_sel_hi:[1,0]
	v_pk_mul_f32 v[42:43], v[42:43], s[20:21] op_sel_hi:[1,0]
	v_pk_mul_f32 v[40:41], v[40:41], s[20:21] op_sel_hi:[1,0]
	s_waitcnt vmcnt(3)
	v_pk_mul_f32 v[50:51], v[50:51], s[20:21] op_sel_hi:[1,0]
	v_pk_mul_f32 v[48:49], v[48:49], s[20:21] op_sel_hi:[1,0]
	s_waitcnt vmcnt(2)
	v_pk_mul_f32 v[54:55], v[54:55], s[20:21] op_sel_hi:[1,0]
	v_pk_mul_f32 v[52:53], v[52:53], s[20:21] op_sel_hi:[1,0]
	s_waitcnt vmcnt(1)
	v_pk_mul_f32 v[58:59], v[58:59], s[20:21] op_sel_hi:[1,0]
	v_pk_mul_f32 v[56:57], v[56:57], s[20:21] op_sel_hi:[1,0]
	s_waitcnt vmcnt(0)
	v_pk_mul_f32 v[62:63], v[62:63], s[20:21] op_sel_hi:[1,0]
	v_pk_mul_f32 v[60:61], v[60:61], s[20:21] op_sel_hi:[1,0]
	v_pk_fma_f32 v[30:31], v[30:31], v[158:159], v[34:35]
	v_pk_fma_f32 v[28:29], v[28:29], v[162:163], v[32:33]
	v_pk_fma_f32 v[26:27], v[26:27], v[146:147], v[38:39]
	v_pk_fma_f32 v[24:25], v[24:25], v[148:149], v[36:37]
	v_pk_fma_f32 v[14:15], v[14:15], v[150:151], v[46:47]
	v_pk_fma_f32 v[12:13], v[12:13], v[152:153], v[44:45]
	v_pk_fma_f32 v[10:11], v[10:11], v[154:155], v[42:43]
	v_pk_fma_f32 v[8:9], v[8:9], v[156:157], v[40:41]
	v_pk_fma_f32 v[22:23], v[22:23], v[158:159], v[50:51]
	v_pk_fma_f32 v[20:21], v[20:21], v[162:163], v[48:49]
	v_pk_fma_f32 v[18:19], v[18:19], v[146:147], v[54:55]
	v_pk_fma_f32 v[16:17], v[16:17], v[148:149], v[52:53]
	v_pk_fma_f32 v[32:33], v[6:7], v[150:151], v[58:59]
	v_pk_fma_f32 v[34:35], v[4:5], v[152:153], v[56:57]
	v_pk_fma_f32 v[36:37], v[2:3], v[154:155], v[62:63]
	v_pk_fma_f32 v[38:39], v[0:1], v[156:157], v[60:61]
	v_cvt_pk_f16_f32 v0, v28, v29
	v_cvt_pk_f16_f32 v1, v30, v31
	v_cvt_pk_f16_f32 v2, v24, v25
	v_cvt_pk_f16_f32 v3, v26, v27
	v_cvt_pk_f16_f32 v4, v12, v13
	v_cvt_pk_f16_f32 v5, v14, v15
	v_cvt_pk_f16_f32 v6, v8, v9
	v_cvt_pk_f16_f32 v7, v10, v11
	v_cvt_pk_f16_f32 v8, v20, v21
	v_cvt_pk_f16_f32 v9, v22, v23
	v_cvt_pk_f16_f32 v10, v16, v17
	v_cvt_pk_f16_f32 v11, v18, v19
	v_cvt_pk_f16_f32 v12, v34, v35
	v_cvt_pk_f16_f32 v13, v32, v33
	v_cvt_pk_f16_f32 v14, v38, v39
	v_cvt_pk_f16_f32 v15, v36, v37
	global_store_dwordx4 v[66:67], v[0:3], off
	global_store_dwordx4 v[66:67], v[4:7], off offset:64
	global_store_dwordx4 v[64:65], v[8:11], off
	global_store_dwordx4 v[64:65], v[12:15], off offset:64
	s_cbranch_vccnz .LBB0_935
	s_andn2_b64 vcc, exec, s[8:9]
	s_cbranch_vccnz .LBB0_934
	s_barrier
	s_branch .LBB0_934
